# GEMM K-loops without the per-segment s_setprio flips (16 fewer scalar instructions per K iteration); P4 static raise for waves 0-3 kept
# baseline (speedup 1.0000x reference)
; #define PG8_STAGE(bufoff, gbase, voff) do { _Pragma("unroll") for (int _i = 0; _i < 2; ++_i) \
;         __builtin_amdgcn_global_load_lds((const unsigned*)((const char*)(gbase) + (voff)[_i]), (LAS unsigned*)(lds + (bufoff) + ldsw + _i * 8192), 16, 0, 0); } while (0)
; #define PG8_LDA(dst, b, h) do { _Pragma("unroll") for (int m = 0; m < 4; ++m) _Pragma("unroll") for (int k = 0; k < 2; ++k) dst[m][k] = *(const LAS bf16x8*)(lds + PG8_SA(b, h) + aoff + m * 2048 + k * 1024); } while (0)
; #define PG8_LDB(dst, b, h) do { _Pragma("unroll") for (int n = 0; n < 2; ++n) _Pragma("unroll") for (int k = 0; k < 2; ++k) dst[n][k] = *(const LAS bf16x8*)(lds + PG8_SB(b, h) + boff + n * 2048 + k * 1024); } while (0)
; #define PG8_MMA(ai, bj, At, Bt) do { __builtin_amdgcn_s_setprio(1); _Pragma("unroll") for (int m = 0; m < 4; ++m) _Pragma("unroll") for (int n = 0; n < 2; ++n) _Pragma("unroll") for (int k = 0; k < 2; ++k) \
;         acc[ai][bj][m][n] = __builtin_amdgcn_mfma_f32_16x16x32_bf16(Bt[n][k], At[m][k], acc[ai][bj][m][n], 0, 0, 0); __builtin_amdgcn_s_setprio(0); } while (0)
; #define PG8_WAIT_V(n) asm volatile("s_waitcnt vmcnt(" #n ")" ::: "memory")
; #define PG8_WAIT_L(n) asm volatile("s_waitcnt lgkmcnt(" #n ")" ::: "memory")
; #define PG8_BAR __builtin_amdgcn_s_barrier()
; #define PG8_SCHED __builtin_amdgcn_sched_barrier(0)
; template <class Epi, class Sched>
; __device__ __forceinline__ void gemm_phase(LAS unsigned char* lds, const Gemm g, const Sched& S, const Epi& E) {
;     ...
;         for (int t = 0; t < nt; t += 2) {
;             const bool last = (t == nt - 2);
;             const char* a1 = cA + (size_t)(t + 1) * kstep;
;             const char* a2 = last ? nA : cA + (size_t)(t + 2) * kstep; const char* b2 = last ? nB : cB + (size_t)(t + 2) * kstep;
;             const char* a3 = a2 + kstep; const char* b3 = b2 + kstep;
;             PG8_LDB(B0, 0, 0); PG8_LDB(B1, 0, 1); PG8_SCHED; PG8_LDA(At, 0, 0); PG8_STAGE(PG8_SA(1, 1), a1 + hstep, voffA);
;             PG8_WAIT_V(8); PG8_WAIT_L(0); PG8_BAR; PG8_MMA(0, 0, At, B0); PG8_MMA(0, 1, At, B1); PG8_BAR; PG8_SCHED;
;             PG8_LDA(At, 0, 1); PG8_STAGE(PG8_SB(0, 0), b2, voffB); PG8_STAGE(PG8_SB(0, 1), b2 + hstep, voffB); PG8_STAGE(PG8_SA(0, 0), a2, voffA);
.LBB0_178:
	ds_read_b128 v[130:133], v235
	ds_read_b128 v[134:137], v235 offset:1024
	ds_read_b128 v[138:141], v235 offset:2048
	ds_read_b128 v[142:145], v235 offset:3072
	ds_read_b128 v[146:149], v238
	ds_read_b128 v[150:153], v238 offset:1024
	ds_read_b128 v[166:169], v238 offset:2048
	ds_read_b128 v[170:173], v238 offset:3072
	ds_read_b128 v[174:177], v187
	ds_read_b128 v[178:181], v187 offset:1024
	ds_read_b128 v[188:191], v187 offset:2048
	ds_read_b128 v[206:209], v187 offset:3072
	ds_read_b128 v[210:213], v187 offset:4096
	ds_read_b128 v[214:217], v187 offset:5120
	ds_read_b128 v[218:221], v187 offset:6144
	ds_read_b128 v[222:225], v187 offset:7168
	s_add_i32 s40, s28, 2
	s_add_u32 s26, s0, 0x80
	s_addc_u32 s29, s1, 0
	s_add_i32 s41, 0, 0x10000
	s_cmp_eq_u32 s80, s28
	s_cselect_b32 s29, s61, s29
	s_cselect_b32 s28, s60, s26
	s_cselect_b32 s65, s63, s16
	s_cselect_b32 s64, s62, s15
	s_add_i32 s26, 0, 0x14000
	s_add_i32 m0, s13, 0xc000
	v_lshl_add_u64 v[182:183], s[0:1], 0, v[164:165]
	global_load_lds_dwordx4 v[182:183], off
	s_add_i32 m0, s13, 0xe000
	v_lshl_add_u64 v[182:183], s[0:1], 0, v[162:163]
	global_load_lds_dwordx4 v[182:183], off
	s_waitcnt vmcnt(8)
	s_waitcnt lgkmcnt(0)
	s_barrier
	s_waitcnt lgkmcnt(0)
	v_mfma_f32_16x16x32_bf16 v[122:125], v[130:133], v[174:177], v[122:125]
	v_mfma_f32_16x16x32_bf16 v[114:117], v[138:141], v[174:177], v[114:117]
	v_mfma_f32_16x16x32_bf16 v[106:109], v[130:133], v[188:191], v[106:109]
	v_mfma_f32_16x16x32_bf16 v[98:101], v[138:141], v[188:191], v[98:101]
	v_mfma_f32_16x16x32_bf16 v[90:93], v[130:133], v[210:213], v[90:93]
	v_mfma_f32_16x16x32_bf16 v[82:85], v[138:141], v[210:213], v[82:85]
	v_mfma_f32_16x16x32_bf16 v[74:77], v[130:133], v[218:221], v[74:77]
	v_mfma_f32_16x16x32_bf16 v[66:69], v[138:141], v[218:221], v[66:69]
	v_mfma_f32_16x16x32_bf16 v[122:125], v[134:137], v[178:181], v[122:125]
	v_mfma_f32_16x16x32_bf16 v[114:117], v[142:145], v[178:181], v[114:117]
	v_mfma_f32_16x16x32_bf16 v[106:109], v[134:137], v[206:209], v[106:109]
	v_mfma_f32_16x16x32_bf16 v[98:101], v[142:145], v[206:209], v[98:101]
	v_mfma_f32_16x16x32_bf16 v[90:93], v[134:137], v[214:217], v[90:93]
	v_mfma_f32_16x16x32_bf16 v[82:85], v[142:145], v[214:217], v[82:85]
	v_mfma_f32_16x16x32_bf16 v[74:77], v[134:137], v[222:225], v[74:77]
	v_mfma_f32_16x16x32_bf16 v[66:69], v[142:145], v[222:225], v[66:69]
	v_mfma_f32_16x16x32_bf16 v[126:129], v[146:149], v[174:177], v[126:129]
	v_mfma_f32_16x16x32_bf16 v[118:121], v[166:169], v[174:177], v[118:121]
	v_mfma_f32_16x16x32_bf16 v[110:113], v[146:149], v[188:191], v[110:113]
	v_mfma_f32_16x16x32_bf16 v[102:105], v[166:169], v[188:191], v[102:105]
	v_mfma_f32_16x16x32_bf16 v[94:97], v[146:149], v[210:213], v[94:97]
	v_mfma_f32_16x16x32_bf16 v[86:89], v[166:169], v[210:213], v[86:89]
	v_mfma_f32_16x16x32_bf16 v[78:81], v[146:149], v[218:221], v[78:81]
	v_mfma_f32_16x16x32_bf16 v[70:73], v[166:169], v[218:221], v[70:73]
	v_mfma_f32_16x16x32_bf16 v[126:129], v[150:153], v[178:181], v[126:129]
	v_mfma_f32_16x16x32_bf16 v[118:121], v[170:173], v[178:181], v[118:121]
	v_mfma_f32_16x16x32_bf16 v[110:113], v[150:153], v[206:209], v[110:113]
	v_mfma_f32_16x16x32_bf16 v[102:105], v[170:173], v[206:209], v[102:105]
	v_mfma_f32_16x16x32_bf16 v[94:97], v[150:153], v[214:217], v[94:97]
	v_mfma_f32_16x16x32_bf16 v[86:89], v[170:173], v[214:217], v[86:89]
	v_mfma_f32_16x16x32_bf16 v[78:81], v[150:153], v[222:225], v[78:81]
	v_mfma_f32_16x16x32_bf16 v[70:73], v[170:173], v[222:225], v[70:73]
	s_barrier
	s_add_i32 s41, s41, s12
	v_lshl_add_u64 v[182:183], s[64:65], 0, v[0:1]
	s_mov_b32 m0, s41
	ds_read_b128 v[174:177], v187 offset:16384
	ds_read_b128 v[178:181], v187 offset:17408
	ds_read_b128 v[188:191], v187 offset:18432
	ds_read_b128 v[206:209], v187 offset:19456
	ds_read_b128 v[210:213], v187 offset:20480
	ds_read_b128 v[214:217], v187 offset:21504
	ds_read_b128 v[218:221], v187 offset:22528
	ds_read_b128 v[222:225], v187 offset:23552
	global_load_lds_dwordx4 v[182:183], off
	s_add_i32 m0, s41, 0x2000
	v_lshl_add_u64 v[192:193], s[64:65], 0, v[154:155]
	s_add_u32 s64, s64, s46
	s_addc_u32 s65, s65, s47
	s_add_i32 s26, s26, s12
	global_load_lds_dwordx4 v[192:193], off
	v_lshl_add_u64 v[226:227], s[64:65], 0, v[0:1]
	s_mov_b32 m0, s26
	v_lshl_add_u64 v[228:229], s[64:65], 0, v[154:155]
	global_load_lds_dwordx4 v[226:227], off
	s_add_i32 m0, s26, 0x2000
	v_lshl_add_u64 v[230:231], s[28:29], 0, v[158:159]
	global_load_lds_dwordx4 v[228:229], off
	s_mov_b32 m0, s13
	v_lshl_add_u64 v[232:233], s[28:29], 0, v[156:157]
	global_load_lds_dwordx4 v[230:231], off
	s_mov_b32 m0, s27
	s_nop 0
	global_load_lds_dwordx4 v[232:233], off
	s_waitcnt vmcnt(8)
	s_waitcnt lgkmcnt(0)
	s_barrier
; #define PG8_STAGE(bufoff, gbase, voff) do { _Pragma("unroll") for (int _i = 0; _i < 2; ++_i) \
;         __builtin_amdgcn_global_load_lds((const unsigned*)((const char*)(gbase) + (voff)[_i]), (LAS unsigned*)(lds + (bufoff) + ldsw + _i * 8192), 16, 0, 0); } while (0)
; #define PG8_LDA(dst, b, h) do { _Pragma("unroll") for (int m = 0; m < 4; ++m) _Pragma("unroll") for (int k = 0; k < 2; ++k) dst[m][k] = *(const LAS bf16x8*)(lds + PG8_SA(b, h) + aoff + m * 2048 + k * 1024); } while (0)
; #define PG8_LDB(dst, b, h) do { _Pragma("unroll") for (int n = 0; n < 2; ++n) _Pragma("unroll") for (int k = 0; k < 2; ++k) dst[n][k] = *(const LAS bf16x8*)(lds + PG8_SB(b, h) + boff + n * 2048 + k * 1024); } while (0)
; #define PG8_MMA(ai, bj, At, Bt) do { __builtin_amdgcn_s_setprio(1); _Pragma("unroll") for (int m = 0; m < 4; ++m) _Pragma("unroll") for (int n = 0; n < 2; ++n) _Pragma("unroll") for (int k = 0; k < 2; ++k) \
;         acc[ai][bj][m][n] = __builtin_amdgcn_mfma_f32_16x16x32_bf16(Bt[n][k], At[m][k], acc[ai][bj][m][n], 0, 0, 0); __builtin_amdgcn_s_setprio(0); } while (0)
; #define PG8_WAIT_V(n) asm volatile("s_waitcnt vmcnt(" #n ")" ::: "memory")
; #define PG8_WAIT_L(n) asm volatile("s_waitcnt lgkmcnt(" #n ")" ::: "memory")
; #define PG8_BAR __builtin_amdgcn_s_barrier()
; #define PG8_SCHED __builtin_amdgcn_sched_barrier(0)
; template <class Epi, class Sched>
; __device__ __forceinline__ void gemm_phase(LAS unsigned char* lds, const Gemm g, const Sched& S, const Epi& E) {
;     ...
;             PG8_WAIT_V(8); PG8_WAIT_L(0); PG8_BAR; PG8_MMA(1, 0, At, B0); PG8_MMA(1, 1, At, B1); PG8_BAR; PG8_SCHED;
;             PG8_LDB(B0, 1, 0); PG8_LDB(B1, 1, 1); PG8_SCHED; PG8_LDA(At, 1, 0); PG8_STAGE(PG8_SA(0, 1), a2 + hstep, voffA);
;             PG8_WAIT_V(8); PG8_WAIT_L(0); PG8_BAR; PG8_MMA(0, 0, At, B0); PG8_MMA(0, 1, At, B1); PG8_BAR; PG8_SCHED;
	s_waitcnt lgkmcnt(0)
	v_mfma_f32_16x16x32_bf16 v[58:61], v[130:133], v[174:177], v[58:61]
	v_mfma_f32_16x16x32_bf16 v[50:53], v[138:141], v[174:177], v[50:53]
	v_mfma_f32_16x16x32_bf16 v[42:45], v[130:133], v[188:191], v[42:45]
	v_mfma_f32_16x16x32_bf16 v[34:37], v[138:141], v[188:191], v[34:37]
	v_mfma_f32_16x16x32_bf16 v[26:29], v[130:133], v[210:213], v[26:29]
	v_mfma_f32_16x16x32_bf16 v[18:21], v[138:141], v[210:213], v[18:21]
	v_mfma_f32_16x16x32_bf16 v[10:13], v[130:133], v[218:221], v[10:13]
	v_mfma_f32_16x16x32_bf16 v[2:5], v[138:141], v[218:221], v[2:5]
	v_mfma_f32_16x16x32_bf16 v[58:61], v[134:137], v[178:181], v[58:61]
	v_mfma_f32_16x16x32_bf16 v[50:53], v[142:145], v[178:181], v[50:53]
	v_mfma_f32_16x16x32_bf16 v[42:45], v[134:137], v[206:209], v[42:45]
	v_mfma_f32_16x16x32_bf16 v[34:37], v[142:145], v[206:209], v[34:37]
	v_mfma_f32_16x16x32_bf16 v[26:29], v[134:137], v[214:217], v[26:29]
	v_mfma_f32_16x16x32_bf16 v[18:21], v[142:145], v[214:217], v[18:21]
	v_mfma_f32_16x16x32_bf16 v[10:13], v[134:137], v[222:225], v[10:13]
	v_mfma_f32_16x16x32_bf16 v[2:5], v[142:145], v[222:225], v[2:5]
	v_mfma_f32_16x16x32_bf16 v[62:65], v[146:149], v[174:177], v[62:65]
	v_mfma_f32_16x16x32_bf16 v[54:57], v[166:169], v[174:177], v[54:57]
	v_mfma_f32_16x16x32_bf16 v[46:49], v[146:149], v[188:191], v[46:49]
	v_mfma_f32_16x16x32_bf16 v[38:41], v[166:169], v[188:191], v[38:41]
	v_mfma_f32_16x16x32_bf16 v[30:33], v[146:149], v[210:213], v[30:33]
	v_mfma_f32_16x16x32_bf16 v[22:25], v[166:169], v[210:213], v[22:25]
	v_mfma_f32_16x16x32_bf16 v[14:17], v[146:149], v[218:221], v[14:17]
	v_mfma_f32_16x16x32_bf16 v[6:9], v[166:169], v[218:221], v[6:9]
	v_mfma_f32_16x16x32_bf16 v[62:65], v[150:153], v[178:181], v[62:65]
	v_mfma_f32_16x16x32_bf16 v[54:57], v[170:173], v[178:181], v[54:57]
	v_mfma_f32_16x16x32_bf16 v[46:49], v[150:153], v[206:209], v[46:49]
	v_mfma_f32_16x16x32_bf16 v[38:41], v[170:173], v[206:209], v[38:41]
	v_mfma_f32_16x16x32_bf16 v[30:33], v[150:153], v[214:217], v[30:33]
	v_mfma_f32_16x16x32_bf16 v[22:25], v[170:173], v[214:217], v[22:25]
	v_mfma_f32_16x16x32_bf16 v[14:17], v[150:153], v[222:225], v[14:17]
	v_mfma_f32_16x16x32_bf16 v[6:9], v[170:173], v[222:225], v[6:9]
	s_barrier
	ds_read_b128 v[130:133], v239
	ds_read_b128 v[134:137], v239 offset:1024
	ds_read_b128 v[138:141], v239 offset:2048
	ds_read_b128 v[142:145], v239 offset:3072
	ds_read_b128 v[146:149], v250
	ds_read_b128 v[150:153], v250 offset:1024
	ds_read_b128 v[166:169], v250 offset:2048
	ds_read_b128 v[170:173], v250 offset:3072
	s_add_i32 s26, 0, 0x18000
	s_add_i32 s41, 0, 0x1c000
	s_add_u32 s28, s28, s46
	s_addc_u32 s29, s29, s47
	s_mov_b32 m0, s30
	v_lshl_add_u64 v[244:245], s[28:29], 0, v[158:159]
	ds_read_b128 v[174:177], v187 offset:32768
	ds_read_b128 v[178:181], v187 offset:33792
	ds_read_b128 v[188:191], v187 offset:34816
	ds_read_b128 v[206:209], v187 offset:35840
	ds_read_b128 v[210:213], v187 offset:36864
	ds_read_b128 v[214:217], v187 offset:37888
	ds_read_b128 v[218:221], v187 offset:38912
	ds_read_b128 v[222:225], v187 offset:39936
	global_load_lds_dwordx4 v[244:245], off
	s_mov_b32 m0, s31
	v_lshl_add_u64 v[244:245], s[28:29], 0, v[156:157]
	global_load_lds_dwordx4 v[244:245], off
	s_waitcnt vmcnt(8)
	s_waitcnt lgkmcnt(0)
	s_barrier
	s_waitcnt lgkmcnt(0)
	v_mfma_f32_16x16x32_bf16 v[122:125], v[130:133], v[174:177], v[122:125]
	v_mfma_f32_16x16x32_bf16 v[114:117], v[138:141], v[174:177], v[114:117]
	v_mfma_f32_16x16x32_bf16 v[106:109], v[130:133], v[188:191], v[106:109]
	v_mfma_f32_16x16x32_bf16 v[98:101], v[138:141], v[188:191], v[98:101]
	v_mfma_f32_16x16x32_bf16 v[90:93], v[130:133], v[210:213], v[90:93]
	v_mfma_f32_16x16x32_bf16 v[82:85], v[138:141], v[210:213], v[82:85]
	v_mfma_f32_16x16x32_bf16 v[74:77], v[130:133], v[218:221], v[74:77]
	v_mfma_f32_16x16x32_bf16 v[66:69], v[138:141], v[218:221], v[66:69]
	v_mfma_f32_16x16x32_bf16 v[122:125], v[134:137], v[178:181], v[122:125]
	v_mfma_f32_16x16x32_bf16 v[114:117], v[142:145], v[178:181], v[114:117]
	v_mfma_f32_16x16x32_bf16 v[106:109], v[134:137], v[206:209], v[106:109]
	v_mfma_f32_16x16x32_bf16 v[98:101], v[142:145], v[206:209], v[98:101]
	v_mfma_f32_16x16x32_bf16 v[90:93], v[134:137], v[214:217], v[90:93]
	v_mfma_f32_16x16x32_bf16 v[82:85], v[142:145], v[214:217], v[82:85]
	v_mfma_f32_16x16x32_bf16 v[74:77], v[134:137], v[222:225], v[74:77]
	v_mfma_f32_16x16x32_bf16 v[66:69], v[142:145], v[222:225], v[66:69]
	v_mfma_f32_16x16x32_bf16 v[126:129], v[146:149], v[174:177], v[126:129]
	v_mfma_f32_16x16x32_bf16 v[118:121], v[166:169], v[174:177], v[118:121]
	v_mfma_f32_16x16x32_bf16 v[110:113], v[146:149], v[188:191], v[110:113]
	v_mfma_f32_16x16x32_bf16 v[102:105], v[166:169], v[188:191], v[102:105]
	v_mfma_f32_16x16x32_bf16 v[94:97], v[146:149], v[210:213], v[94:97]
	v_mfma_f32_16x16x32_bf16 v[86:89], v[166:169], v[210:213], v[86:89]
	v_mfma_f32_16x16x32_bf16 v[78:81], v[146:149], v[218:221], v[78:81]
	v_mfma_f32_16x16x32_bf16 v[70:73], v[166:169], v[218:221], v[70:73]
	v_mfma_f32_16x16x32_bf16 v[126:129], v[150:153], v[178:181], v[126:129]
	v_mfma_f32_16x16x32_bf16 v[118:121], v[170:173], v[178:181], v[118:121]
	v_mfma_f32_16x16x32_bf16 v[110:113], v[150:153], v[206:209], v[110:113]
	v_mfma_f32_16x16x32_bf16 v[102:105], v[170:173], v[206:209], v[102:105]
	v_mfma_f32_16x16x32_bf16 v[94:97], v[150:153], v[214:217], v[94:97]
	v_mfma_f32_16x16x32_bf16 v[86:89], v[170:173], v[214:217], v[86:89]
	v_mfma_f32_16x16x32_bf16 v[78:81], v[150:153], v[222:225], v[78:81]
	v_mfma_f32_16x16x32_bf16 v[70:73], v[170:173], v[222:225], v[70:73]
	s_barrier
; #define PG8_STAGE(bufoff, gbase, voff) do { _Pragma("unroll") for (int _i = 0; _i < 2; ++_i) \
;         __builtin_amdgcn_global_load_lds((const unsigned*)((const char*)(gbase) + (voff)[_i]), (LAS unsigned*)(lds + (bufoff) + ldsw + _i * 8192), 16, 0, 0); } while (0)
; #define PG8_LDA(dst, b, h) do { _Pragma("unroll") for (int m = 0; m < 4; ++m) _Pragma("unroll") for (int k = 0; k < 2; ++k) dst[m][k] = *(const LAS bf16x8*)(lds + PG8_SA(b, h) + aoff + m * 2048 + k * 1024); } while (0)
; #define PG8_MMA(ai, bj, At, Bt) do { __builtin_amdgcn_s_setprio(1); _Pragma("unroll") for (int m = 0; m < 4; ++m) _Pragma("unroll") for (int n = 0; n < 2; ++n) _Pragma("unroll") for (int k = 0; k < 2; ++k) \
;         acc[ai][bj][m][n] = __builtin_amdgcn_mfma_f32_16x16x32_bf16(Bt[n][k], At[m][k], acc[ai][bj][m][n], 0, 0, 0); __builtin_amdgcn_s_setprio(0); } while (0)
; #define PG8_WAIT_V(n) asm volatile("s_waitcnt vmcnt(" #n ")" ::: "memory")
; #define PG8_WAIT_L(n) asm volatile("s_waitcnt lgkmcnt(" #n ")" ::: "memory")
; #define PG8_BAR __builtin_amdgcn_s_barrier()
; #define PG8_SCHED __builtin_amdgcn_sched_barrier(0)
; template <class Epi, class Sched>
; __device__ __forceinline__ void gemm_phase(LAS unsigned char* lds, const Gemm g, const Sched& S, const Epi& E) {
;     ...
;             PG8_LDA(At, 1, 1); PG8_STAGE(PG8_SB(1, 0), b3, voffB); PG8_STAGE(PG8_SB(1, 1), b3 + hstep, voffB); PG8_STAGE(PG8_SA(1, 0), a3, voffA);
;             PG8_WAIT_V(8); PG8_WAIT_L(0); PG8_BAR; PG8_MMA(1, 0, At, B0); PG8_MMA(1, 1, At, B1); PG8_BAR; PG8_SCHED;
;         }
	s_add_i32 s26, s26, s12
	v_lshl_add_u64 v[182:183], v[182:183], 0, s[18:19]
	s_mov_b32 m0, s26
	ds_read_b128 v[174:177], v187 offset:49152
	ds_read_b128 v[178:181], v187 offset:50176
	ds_read_b128 v[188:191], v187 offset:51200
	ds_read_b128 v[206:209], v187 offset:52224
	ds_read_b128 v[210:213], v187 offset:53248
	ds_read_b128 v[214:217], v187 offset:54272
	ds_read_b128 v[218:221], v187 offset:55296
	ds_read_b128 v[222:225], v187 offset:56320
	global_load_lds_dwordx4 v[182:183], off
	v_lshl_add_u64 v[182:183], v[192:193], 0, s[18:19]
	s_add_i32 m0, s26, 0x2000
	s_add_i32 s26, s41, s12
	global_load_lds_dwordx4 v[182:183], off
	s_mov_b32 m0, s26
	v_lshl_add_u64 v[182:183], v[226:227], 0, s[18:19]
	global_load_lds_dwordx4 v[182:183], off
	s_add_i32 m0, s26, 0x2000
	v_lshl_add_u64 v[182:183], v[228:229], 0, s[18:19]
	global_load_lds_dwordx4 v[182:183], off
	s_mov_b32 m0, s34
	v_lshl_add_u64 v[182:183], v[230:231], 0, s[18:19]
	global_load_lds_dwordx4 v[182:183], off
	s_mov_b32 m0, s35
	v_lshl_add_u64 v[182:183], v[232:233], 0, s[18:19]
	global_load_lds_dwordx4 v[182:183], off
	s_waitcnt vmcnt(8)
	s_waitcnt lgkmcnt(0)
	s_barrier
	s_waitcnt lgkmcnt(0)
	v_mfma_f32_16x16x32_bf16 v[58:61], v[130:133], v[174:177], v[58:61]
	v_mfma_f32_16x16x32_bf16 v[50:53], v[138:141], v[174:177], v[50:53]
	v_mfma_f32_16x16x32_bf16 v[42:45], v[130:133], v[188:191], v[42:45]
	v_mfma_f32_16x16x32_bf16 v[34:37], v[138:141], v[188:191], v[34:37]
	v_mfma_f32_16x16x32_bf16 v[26:29], v[130:133], v[210:213], v[26:29]
	v_mfma_f32_16x16x32_bf16 v[18:21], v[138:141], v[210:213], v[18:21]
	v_mfma_f32_16x16x32_bf16 v[10:13], v[130:133], v[218:221], v[10:13]
	v_mfma_f32_16x16x32_bf16 v[2:5], v[138:141], v[218:221], v[2:5]
	v_mfma_f32_16x16x32_bf16 v[58:61], v[134:137], v[178:181], v[58:61]
	v_mfma_f32_16x16x32_bf16 v[50:53], v[142:145], v[178:181], v[50:53]
	v_mfma_f32_16x16x32_bf16 v[42:45], v[134:137], v[206:209], v[42:45]
	v_mfma_f32_16x16x32_bf16 v[34:37], v[142:145], v[206:209], v[34:37]
	v_mfma_f32_16x16x32_bf16 v[26:29], v[134:137], v[214:217], v[26:29]
	v_mfma_f32_16x16x32_bf16 v[18:21], v[142:145], v[214:217], v[18:21]
	v_mfma_f32_16x16x32_bf16 v[10:13], v[134:137], v[222:225], v[10:13]
	v_mfma_f32_16x16x32_bf16 v[2:5], v[142:145], v[222:225], v[2:5]
	v_mfma_f32_16x16x32_bf16 v[62:65], v[146:149], v[174:177], v[62:65]
	v_mfma_f32_16x16x32_bf16 v[54:57], v[166:169], v[174:177], v[54:57]
	v_mfma_f32_16x16x32_bf16 v[46:49], v[146:149], v[188:191], v[46:49]
	v_mfma_f32_16x16x32_bf16 v[38:41], v[166:169], v[188:191], v[38:41]
	v_mfma_f32_16x16x32_bf16 v[30:33], v[146:149], v[210:213], v[30:33]
	v_mfma_f32_16x16x32_bf16 v[22:25], v[166:169], v[210:213], v[22:25]
	v_mfma_f32_16x16x32_bf16 v[14:17], v[146:149], v[218:221], v[14:17]
	v_mfma_f32_16x16x32_bf16 v[6:9], v[166:169], v[218:221], v[6:9]
	v_mfma_f32_16x16x32_bf16 v[62:65], v[150:153], v[178:181], v[62:65]
	v_mfma_f32_16x16x32_bf16 v[54:57], v[170:173], v[178:181], v[54:57]
	v_mfma_f32_16x16x32_bf16 v[46:49], v[150:153], v[206:209], v[46:49]
	v_mfma_f32_16x16x32_bf16 v[38:41], v[170:173], v[206:209], v[38:41]
	v_mfma_f32_16x16x32_bf16 v[30:33], v[150:153], v[214:217], v[30:33]
	v_mfma_f32_16x16x32_bf16 v[22:25], v[170:173], v[214:217], v[22:25]
	v_mfma_f32_16x16x32_bf16 v[14:17], v[150:153], v[222:225], v[14:17]
	v_mfma_f32_16x16x32_bf16 v[6:9], v[170:173], v[222:225], v[6:9]
	s_barrier
	s_add_u32 s15, s15, 0x100
	s_addc_u32 s16, s16, 0
	s_add_u32 s0, s0, 0x100
	s_addc_u32 s1, s1, 0
	s_cmp_ge_i32 s40, s67
	s_mov_b32 s28, s40
	s_cbranch_scc0 .LBB0_178

; #define PG8_STAGE(bufoff, gbase, voff) do { _Pragma("unroll") for (int _i = 0; _i < 2; ++_i) \
;         __builtin_amdgcn_global_load_lds((const unsigned*)((const char*)(gbase) + (voff)[_i]), (LAS unsigned*)(lds + (bufoff) + ldsw + _i * 8192), 16, 0, 0); } while (0)
; #define PG8_LDA(dst, b, h) do { _Pragma("unroll") for (int m = 0; m < 4; ++m) _Pragma("unroll") for (int k = 0; k < 2; ++k) dst[m][k] = *(const LAS bf16x8*)(lds + PG8_SA(b, h) + aoff + m * 2048 + k * 1024); } while (0)
; #define PG8_LDB(dst, b, h) do { _Pragma("unroll") for (int n = 0; n < 2; ++n) _Pragma("unroll") for (int k = 0; k < 2; ++k) dst[n][k] = *(const LAS bf16x8*)(lds + PG8_SB(b, h) + boff + n * 2048 + k * 1024); } while (0)
; #define PG8_MMA(ai, bj, At, Bt) do { __builtin_amdgcn_s_setprio(1); _Pragma("unroll") for (int m = 0; m < 4; ++m) _Pragma("unroll") for (int n = 0; n < 2; ++n) _Pragma("unroll") for (int k = 0; k < 2; ++k) \
;         acc[ai][bj][m][n] = __builtin_amdgcn_mfma_f32_16x16x32_bf16(Bt[n][k], At[m][k], acc[ai][bj][m][n], 0, 0, 0); __builtin_amdgcn_s_setprio(0); } while (0)
; #define PG8_WAIT_V(n) asm volatile("s_waitcnt vmcnt(" #n ")" ::: "memory")
; #define PG8_WAIT_L(n) asm volatile("s_waitcnt lgkmcnt(" #n ")" ::: "memory")
; #define PG8_BAR __builtin_amdgcn_s_barrier()
; #define PG8_SCHED __builtin_amdgcn_sched_barrier(0)
; template <class Epi, class Sched>
; __device__ __forceinline__ void gemm_phase(LAS unsigned char* lds, const Gemm g, const Sched& S, const Epi& E) {
;     ...
;         for (int t = 0; t < nt; t += 2) {
;             const bool last = (t == nt - 2);
;             const char* a1 = cA + (size_t)(t + 1) * kstep;
;             const char* a2 = last ? nA : cA + (size_t)(t + 2) * kstep; const char* b2 = last ? nB : cB + (size_t)(t + 2) * kstep;
;             const char* a3 = a2 + kstep; const char* b3 = b2 + kstep;
;             PG8_LDB(B0, 0, 0); PG8_LDB(B1, 0, 1); PG8_SCHED; PG8_LDA(At, 0, 0); PG8_STAGE(PG8_SA(1, 1), a1 + hstep, voffA);
;             PG8_WAIT_V(8); PG8_WAIT_L(0); PG8_BAR; PG8_MMA(0, 0, At, B0); PG8_MMA(0, 1, At, B1); PG8_BAR; PG8_SCHED;
;             PG8_LDA(At, 0, 1); PG8_STAGE(PG8_SB(0, 0), b2, voffB); PG8_STAGE(PG8_SB(0, 1), b2 + hstep, voffB); PG8_STAGE(PG8_SA(0, 0), a2, voffA);
.LBB0_296:
	ds_read_b128 v[140:143], v235
	ds_read_b128 v[144:147], v235 offset:1024
	ds_read_b128 v[148:151], v235 offset:2048
	ds_read_b128 v[152:155], v235 offset:3072
	ds_read_b128 v[156:159], v238
	ds_read_b128 v[160:163], v238 offset:1024
	ds_read_b128 v[164:167], v238 offset:2048
	ds_read_b128 v[168:171], v238 offset:3072
	ds_read_b128 v[172:175], v219
	ds_read_b128 v[176:179], v219 offset:1024
	ds_read_b128 v[180:183], v219 offset:2048
	ds_read_b128 v[184:187], v219 offset:3072
	ds_read_b128 v[188:191], v219 offset:4096
	ds_read_b128 v[206:209], v219 offset:5120
	ds_read_b128 v[210:213], v219 offset:6144
	ds_read_b128 v[220:223], v219 offset:7168
	s_add_i32 s38, s28, 2
	s_add_u32 s26, s0, 0x80
	s_addc_u32 s29, s1, 0
	s_add_i32 s39, 0, 0x10000
	s_cmp_eq_u32 s88, s28
	s_cselect_b32 s29, s47, s29
	s_cselect_b32 s28, s46, s26
	s_cselect_b32 s93, s67, s16
	s_cselect_b32 s92, s66, s15
	s_add_i32 s26, 0, 0x14000
	s_add_i32 m0, s13, 0xc000
	v_lshl_add_u64 v[192:193], s[0:1], 0, v[138:139]
	global_load_lds_dwordx4 v[192:193], off
	s_add_i32 m0, s13, 0xe000
	v_lshl_add_u64 v[192:193], s[0:1], 0, v[136:137]
	global_load_lds_dwordx4 v[192:193], off
	s_waitcnt vmcnt(8)
	s_waitcnt lgkmcnt(0)
	s_barrier
	s_waitcnt lgkmcnt(0)
	v_mfma_f32_16x16x32_bf16 v[126:129], v[140:143], v[172:175], v[126:129]
	v_mfma_f32_16x16x32_bf16 v[122:125], v[148:151], v[172:175], v[122:125]
	v_mfma_f32_16x16x32_bf16 v[118:121], v[140:143], v[180:183], v[118:121]
	v_mfma_f32_16x16x32_bf16 v[114:117], v[148:151], v[180:183], v[114:117]
	v_mfma_f32_16x16x32_bf16 v[106:109], v[140:143], v[188:191], v[106:109]
	v_mfma_f32_16x16x32_bf16 v[98:101], v[148:151], v[188:191], v[98:101]
	v_mfma_f32_16x16x32_bf16 v[90:93], v[140:143], v[210:213], v[90:93]
	v_mfma_f32_16x16x32_bf16 v[82:85], v[148:151], v[210:213], v[82:85]
	v_mfma_f32_16x16x32_bf16 v[126:129], v[144:147], v[176:179], v[126:129]
	v_mfma_f32_16x16x32_bf16 v[122:125], v[152:155], v[176:179], v[122:125]
	v_mfma_f32_16x16x32_bf16 v[118:121], v[144:147], v[184:187], v[118:121]
	v_mfma_f32_16x16x32_bf16 v[114:117], v[152:155], v[184:187], v[114:117]
	v_mfma_f32_16x16x32_bf16 v[106:109], v[144:147], v[206:209], v[106:109]
	v_mfma_f32_16x16x32_bf16 v[98:101], v[152:155], v[206:209], v[98:101]
	v_mfma_f32_16x16x32_bf16 v[90:93], v[144:147], v[220:223], v[90:93]
	v_mfma_f32_16x16x32_bf16 v[82:85], v[152:155], v[220:223], v[82:85]
	v_mfma_f32_16x16x32_bf16 v[110:113], v[156:159], v[172:175], v[110:113]
	v_mfma_f32_16x16x32_bf16 v[102:105], v[164:167], v[172:175], v[102:105]
	v_mfma_f32_16x16x32_bf16 v[94:97], v[156:159], v[180:183], v[94:97]
	v_mfma_f32_16x16x32_bf16 v[86:89], v[164:167], v[180:183], v[86:89]
	v_mfma_f32_16x16x32_bf16 v[78:81], v[156:159], v[188:191], v[78:81]
	v_mfma_f32_16x16x32_bf16 v[74:77], v[164:167], v[188:191], v[74:77]
	v_mfma_f32_16x16x32_bf16 v[70:73], v[156:159], v[210:213], v[70:73]
	v_mfma_f32_16x16x32_bf16 v[66:69], v[164:167], v[210:213], v[66:69]
	v_mfma_f32_16x16x32_bf16 v[110:113], v[160:163], v[176:179], v[110:113]
	v_mfma_f32_16x16x32_bf16 v[102:105], v[168:171], v[176:179], v[102:105]
	v_mfma_f32_16x16x32_bf16 v[94:97], v[160:163], v[184:187], v[94:97]
	v_mfma_f32_16x16x32_bf16 v[86:89], v[168:171], v[184:187], v[86:89]
	v_mfma_f32_16x16x32_bf16 v[78:81], v[160:163], v[206:209], v[78:81]
	v_mfma_f32_16x16x32_bf16 v[74:77], v[168:171], v[206:209], v[74:77]
	v_mfma_f32_16x16x32_bf16 v[70:73], v[160:163], v[220:223], v[70:73]
	v_mfma_f32_16x16x32_bf16 v[66:69], v[168:171], v[220:223], v[66:69]
	s_barrier
	s_add_i32 s39, s39, s12
	v_lshl_add_u64 v[192:193], s[92:93], 0, v[0:1]
	s_mov_b32 m0, s39
	ds_read_b128 v[172:175], v219 offset:16384
	ds_read_b128 v[176:179], v219 offset:17408
	ds_read_b128 v[180:183], v219 offset:18432
	ds_read_b128 v[184:187], v219 offset:19456
	ds_read_b128 v[188:191], v219 offset:20480
	ds_read_b128 v[206:209], v219 offset:21504
	ds_read_b128 v[210:213], v219 offset:22528
	ds_read_b128 v[220:223], v219 offset:23552
	global_load_lds_dwordx4 v[192:193], off
	s_add_i32 m0, s39, 0x2000
	v_lshl_add_u64 v[214:215], s[92:93], 0, v[130:131]
	s_add_u32 s92, s92, s56
	s_addc_u32 s93, s93, s57
	s_add_i32 s26, s26, s12
	global_load_lds_dwordx4 v[214:215], off
	v_lshl_add_u64 v[224:225], s[92:93], 0, v[0:1]
	s_mov_b32 m0, s26
	v_lshl_add_u64 v[226:227], s[92:93], 0, v[130:131]
	global_load_lds_dwordx4 v[224:225], off
	s_add_i32 m0, s26, 0x2000
	v_lshl_add_u64 v[228:229], s[28:29], 0, v[134:135]
	global_load_lds_dwordx4 v[226:227], off
	s_mov_b32 m0, s13
	v_lshl_add_u64 v[230:231], s[28:29], 0, v[132:133]
	global_load_lds_dwordx4 v[228:229], off
	s_mov_b32 m0, s27
	s_nop 0
	global_load_lds_dwordx4 v[230:231], off
	s_waitcnt vmcnt(8)
	s_waitcnt lgkmcnt(0)
	s_barrier
; #define PG8_STAGE(bufoff, gbase, voff) do { _Pragma("unroll") for (int _i = 0; _i < 2; ++_i) \
;         __builtin_amdgcn_global_load_lds((const unsigned*)((const char*)(gbase) + (voff)[_i]), (LAS unsigned*)(lds + (bufoff) + ldsw + _i * 8192), 16, 0, 0); } while (0)
; #define PG8_LDA(dst, b, h) do { _Pragma("unroll") for (int m = 0; m < 4; ++m) _Pragma("unroll") for (int k = 0; k < 2; ++k) dst[m][k] = *(const LAS bf16x8*)(lds + PG8_SA(b, h) + aoff + m * 2048 + k * 1024); } while (0)
; #define PG8_LDB(dst, b, h) do { _Pragma("unroll") for (int n = 0; n < 2; ++n) _Pragma("unroll") for (int k = 0; k < 2; ++k) dst[n][k] = *(const LAS bf16x8*)(lds + PG8_SB(b, h) + boff + n * 2048 + k * 1024); } while (0)
; #define PG8_MMA(ai, bj, At, Bt) do { __builtin_amdgcn_s_setprio(1); _Pragma("unroll") for (int m = 0; m < 4; ++m) _Pragma("unroll") for (int n = 0; n < 2; ++n) _Pragma("unroll") for (int k = 0; k < 2; ++k) \
;         acc[ai][bj][m][n] = __builtin_amdgcn_mfma_f32_16x16x32_bf16(Bt[n][k], At[m][k], acc[ai][bj][m][n], 0, 0, 0); __builtin_amdgcn_s_setprio(0); } while (0)
; #define PG8_WAIT_V(n) asm volatile("s_waitcnt vmcnt(" #n ")" ::: "memory")
; #define PG8_WAIT_L(n) asm volatile("s_waitcnt lgkmcnt(" #n ")" ::: "memory")
; #define PG8_BAR __builtin_amdgcn_s_barrier()
; #define PG8_SCHED __builtin_amdgcn_sched_barrier(0)
; template <class Epi, class Sched>
; __device__ __forceinline__ void gemm_phase(LAS unsigned char* lds, const Gemm g, const Sched& S, const Epi& E) {
;     ...
;             PG8_WAIT_V(8); PG8_WAIT_L(0); PG8_BAR; PG8_MMA(1, 0, At, B0); PG8_MMA(1, 1, At, B1); PG8_BAR; PG8_SCHED;
;             PG8_LDB(B0, 1, 0); PG8_LDB(B1, 1, 1); PG8_SCHED; PG8_LDA(At, 1, 0); PG8_STAGE(PG8_SA(0, 1), a2 + hstep, voffA);
;             PG8_WAIT_V(8); PG8_WAIT_L(0); PG8_BAR; PG8_MMA(0, 0, At, B0); PG8_MMA(0, 1, At, B1); PG8_BAR; PG8_SCHED;
	s_waitcnt lgkmcnt(0)
	v_mfma_f32_16x16x32_bf16 v[62:65], v[140:143], v[172:175], v[62:65]
	v_mfma_f32_16x16x32_bf16 v[58:61], v[148:151], v[172:175], v[58:61]
	v_mfma_f32_16x16x32_bf16 v[54:57], v[140:143], v[180:183], v[54:57]
	v_mfma_f32_16x16x32_bf16 v[50:53], v[148:151], v[180:183], v[50:53]
	v_mfma_f32_16x16x32_bf16 v[42:45], v[140:143], v[188:191], v[42:45]
	v_mfma_f32_16x16x32_bf16 v[34:37], v[148:151], v[188:191], v[34:37]
	v_mfma_f32_16x16x32_bf16 v[26:29], v[140:143], v[210:213], v[26:29]
	v_mfma_f32_16x16x32_bf16 v[18:21], v[148:151], v[210:213], v[18:21]
	v_mfma_f32_16x16x32_bf16 v[62:65], v[144:147], v[176:179], v[62:65]
	v_mfma_f32_16x16x32_bf16 v[58:61], v[152:155], v[176:179], v[58:61]
	v_mfma_f32_16x16x32_bf16 v[54:57], v[144:147], v[184:187], v[54:57]
	v_mfma_f32_16x16x32_bf16 v[50:53], v[152:155], v[184:187], v[50:53]
	v_mfma_f32_16x16x32_bf16 v[42:45], v[144:147], v[206:209], v[42:45]
	v_mfma_f32_16x16x32_bf16 v[34:37], v[152:155], v[206:209], v[34:37]
	v_mfma_f32_16x16x32_bf16 v[26:29], v[144:147], v[220:223], v[26:29]
	v_mfma_f32_16x16x32_bf16 v[18:21], v[152:155], v[220:223], v[18:21]
	v_mfma_f32_16x16x32_bf16 v[46:49], v[156:159], v[172:175], v[46:49]
	v_mfma_f32_16x16x32_bf16 v[38:41], v[164:167], v[172:175], v[38:41]
	v_mfma_f32_16x16x32_bf16 v[30:33], v[156:159], v[180:183], v[30:33]
	v_mfma_f32_16x16x32_bf16 v[22:25], v[164:167], v[180:183], v[22:25]
	v_mfma_f32_16x16x32_bf16 v[14:17], v[156:159], v[188:191], v[14:17]
	v_mfma_f32_16x16x32_bf16 v[10:13], v[164:167], v[188:191], v[10:13]
	v_mfma_f32_16x16x32_bf16 v[6:9], v[156:159], v[210:213], v[6:9]
	v_mfma_f32_16x16x32_bf16 v[2:5], v[164:167], v[210:213], v[2:5]
	v_mfma_f32_16x16x32_bf16 v[46:49], v[160:163], v[176:179], v[46:49]
	v_mfma_f32_16x16x32_bf16 v[38:41], v[168:171], v[176:179], v[38:41]
	v_mfma_f32_16x16x32_bf16 v[30:33], v[160:163], v[184:187], v[30:33]
	v_mfma_f32_16x16x32_bf16 v[22:25], v[168:171], v[184:187], v[22:25]
	v_mfma_f32_16x16x32_bf16 v[14:17], v[160:163], v[206:209], v[14:17]
	v_mfma_f32_16x16x32_bf16 v[10:13], v[168:171], v[206:209], v[10:13]
	v_mfma_f32_16x16x32_bf16 v[6:9], v[160:163], v[220:223], v[6:9]
	v_mfma_f32_16x16x32_bf16 v[2:5], v[168:171], v[220:223], v[2:5]
	s_barrier
	ds_read_b128 v[140:143], v239
	ds_read_b128 v[144:147], v239 offset:1024
	ds_read_b128 v[148:151], v239 offset:2048
	ds_read_b128 v[152:155], v239 offset:3072
	ds_read_b128 v[156:159], v250
	ds_read_b128 v[160:163], v250 offset:1024
	ds_read_b128 v[164:167], v250 offset:2048
	ds_read_b128 v[168:171], v250 offset:3072
	s_add_i32 s26, 0, 0x18000
	s_add_i32 s39, 0, 0x1c000
	s_add_u32 s28, s28, s56
	s_addc_u32 s29, s29, s57
	s_mov_b32 m0, s34
	v_lshl_add_u64 v[232:233], s[28:29], 0, v[134:135]
	ds_read_b128 v[172:175], v219 offset:32768
	ds_read_b128 v[176:179], v219 offset:33792
	ds_read_b128 v[180:183], v219 offset:34816
	ds_read_b128 v[184:187], v219 offset:35840
	ds_read_b128 v[188:191], v219 offset:36864
	ds_read_b128 v[206:209], v219 offset:37888
	ds_read_b128 v[210:213], v219 offset:38912
	ds_read_b128 v[220:223], v219 offset:39936
	global_load_lds_dwordx4 v[232:233], off
	s_mov_b32 m0, s35
	v_lshl_add_u64 v[232:233], s[28:29], 0, v[132:133]
	global_load_lds_dwordx4 v[232:233], off
	s_waitcnt vmcnt(8)
	s_waitcnt lgkmcnt(0)
	s_barrier
	s_waitcnt lgkmcnt(0)
	v_mfma_f32_16x16x32_bf16 v[126:129], v[140:143], v[172:175], v[126:129]
	v_mfma_f32_16x16x32_bf16 v[122:125], v[148:151], v[172:175], v[122:125]
	v_mfma_f32_16x16x32_bf16 v[118:121], v[140:143], v[180:183], v[118:121]
	v_mfma_f32_16x16x32_bf16 v[114:117], v[148:151], v[180:183], v[114:117]
	v_mfma_f32_16x16x32_bf16 v[106:109], v[140:143], v[188:191], v[106:109]
	v_mfma_f32_16x16x32_bf16 v[98:101], v[148:151], v[188:191], v[98:101]
	v_mfma_f32_16x16x32_bf16 v[90:93], v[140:143], v[210:213], v[90:93]
	v_mfma_f32_16x16x32_bf16 v[82:85], v[148:151], v[210:213], v[82:85]
	v_mfma_f32_16x16x32_bf16 v[126:129], v[144:147], v[176:179], v[126:129]
	v_mfma_f32_16x16x32_bf16 v[122:125], v[152:155], v[176:179], v[122:125]
	v_mfma_f32_16x16x32_bf16 v[118:121], v[144:147], v[184:187], v[118:121]
	v_mfma_f32_16x16x32_bf16 v[114:117], v[152:155], v[184:187], v[114:117]
	v_mfma_f32_16x16x32_bf16 v[106:109], v[144:147], v[206:209], v[106:109]
	v_mfma_f32_16x16x32_bf16 v[98:101], v[152:155], v[206:209], v[98:101]
	v_mfma_f32_16x16x32_bf16 v[90:93], v[144:147], v[220:223], v[90:93]
	v_mfma_f32_16x16x32_bf16 v[82:85], v[152:155], v[220:223], v[82:85]
	v_mfma_f32_16x16x32_bf16 v[110:113], v[156:159], v[172:175], v[110:113]
	v_mfma_f32_16x16x32_bf16 v[102:105], v[164:167], v[172:175], v[102:105]
	v_mfma_f32_16x16x32_bf16 v[94:97], v[156:159], v[180:183], v[94:97]
	v_mfma_f32_16x16x32_bf16 v[86:89], v[164:167], v[180:183], v[86:89]
	v_mfma_f32_16x16x32_bf16 v[78:81], v[156:159], v[188:191], v[78:81]
	v_mfma_f32_16x16x32_bf16 v[74:77], v[164:167], v[188:191], v[74:77]
	v_mfma_f32_16x16x32_bf16 v[70:73], v[156:159], v[210:213], v[70:73]
	v_mfma_f32_16x16x32_bf16 v[66:69], v[164:167], v[210:213], v[66:69]
	v_mfma_f32_16x16x32_bf16 v[110:113], v[160:163], v[176:179], v[110:113]
	v_mfma_f32_16x16x32_bf16 v[102:105], v[168:171], v[176:179], v[102:105]
	v_mfma_f32_16x16x32_bf16 v[94:97], v[160:163], v[184:187], v[94:97]
	v_mfma_f32_16x16x32_bf16 v[86:89], v[168:171], v[184:187], v[86:89]
	v_mfma_f32_16x16x32_bf16 v[78:81], v[160:163], v[206:209], v[78:81]
	v_mfma_f32_16x16x32_bf16 v[74:77], v[168:171], v[206:209], v[74:77]
	v_mfma_f32_16x16x32_bf16 v[70:73], v[160:163], v[220:223], v[70:73]
	v_mfma_f32_16x16x32_bf16 v[66:69], v[168:171], v[220:223], v[66:69]
	s_barrier
; #define PG8_STAGE(bufoff, gbase, voff) do { _Pragma("unroll") for (int _i = 0; _i < 2; ++_i) \
;         __builtin_amdgcn_global_load_lds((const unsigned*)((const char*)(gbase) + (voff)[_i]), (LAS unsigned*)(lds + (bufoff) + ldsw + _i * 8192), 16, 0, 0); } while (0)
; #define PG8_LDA(dst, b, h) do { _Pragma("unroll") for (int m = 0; m < 4; ++m) _Pragma("unroll") for (int k = 0; k < 2; ++k) dst[m][k] = *(const LAS bf16x8*)(lds + PG8_SA(b, h) + aoff + m * 2048 + k * 1024); } while (0)
; #define PG8_MMA(ai, bj, At, Bt) do { __builtin_amdgcn_s_setprio(1); _Pragma("unroll") for (int m = 0; m < 4; ++m) _Pragma("unroll") for (int n = 0; n < 2; ++n) _Pragma("unroll") for (int k = 0; k < 2; ++k) \
;         acc[ai][bj][m][n] = __builtin_amdgcn_mfma_f32_16x16x32_bf16(Bt[n][k], At[m][k], acc[ai][bj][m][n], 0, 0, 0); __builtin_amdgcn_s_setprio(0); } while (0)
; #define PG8_WAIT_V(n) asm volatile("s_waitcnt vmcnt(" #n ")" ::: "memory")
; #define PG8_WAIT_L(n) asm volatile("s_waitcnt lgkmcnt(" #n ")" ::: "memory")
; #define PG8_BAR __builtin_amdgcn_s_barrier()
; #define PG8_SCHED __builtin_amdgcn_sched_barrier(0)
; template <class Epi, class Sched>
; __device__ __forceinline__ void gemm_phase(LAS unsigned char* lds, const Gemm g, const Sched& S, const Epi& E) {
;     ...
;             PG8_LDA(At, 1, 1); PG8_STAGE(PG8_SB(1, 0), b3, voffB); PG8_STAGE(PG8_SB(1, 1), b3 + hstep, voffB); PG8_STAGE(PG8_SA(1, 0), a3, voffA);
;             PG8_WAIT_V(8); PG8_WAIT_L(0); PG8_BAR; PG8_MMA(1, 0, At, B0); PG8_MMA(1, 1, At, B1); PG8_BAR; PG8_SCHED;
;         }
	s_add_i32 s26, s26, s12
	v_lshl_add_u64 v[192:193], v[192:193], 0, s[18:19]
	s_mov_b32 m0, s26
	ds_read_b128 v[172:175], v219 offset:49152
	ds_read_b128 v[176:179], v219 offset:50176
	ds_read_b128 v[180:183], v219 offset:51200
	ds_read_b128 v[184:187], v219 offset:52224
	ds_read_b128 v[188:191], v219 offset:53248
	ds_read_b128 v[206:209], v219 offset:54272
	ds_read_b128 v[210:213], v219 offset:55296
	ds_read_b128 v[220:223], v219 offset:56320
	global_load_lds_dwordx4 v[192:193], off
	v_lshl_add_u64 v[192:193], v[214:215], 0, s[18:19]
	s_add_i32 m0, s26, 0x2000
	s_add_i32 s26, s39, s12
	global_load_lds_dwordx4 v[192:193], off
	s_mov_b32 m0, s26
	v_lshl_add_u64 v[192:193], v[224:225], 0, s[18:19]
	global_load_lds_dwordx4 v[192:193], off
	s_add_i32 m0, s26, 0x2000
	v_lshl_add_u64 v[192:193], v[226:227], 0, s[18:19]
	global_load_lds_dwordx4 v[192:193], off
	s_mov_b32 m0, s84
	v_lshl_add_u64 v[192:193], v[228:229], 0, s[18:19]
	global_load_lds_dwordx4 v[192:193], off
	s_mov_b32 m0, s85
	v_lshl_add_u64 v[192:193], v[230:231], 0, s[18:19]
	global_load_lds_dwordx4 v[192:193], off
	s_waitcnt vmcnt(8)
	s_waitcnt lgkmcnt(0)
	s_barrier
	s_waitcnt lgkmcnt(0)
	v_mfma_f32_16x16x32_bf16 v[62:65], v[140:143], v[172:175], v[62:65]
	v_mfma_f32_16x16x32_bf16 v[58:61], v[148:151], v[172:175], v[58:61]
	v_mfma_f32_16x16x32_bf16 v[54:57], v[140:143], v[180:183], v[54:57]
	v_mfma_f32_16x16x32_bf16 v[50:53], v[148:151], v[180:183], v[50:53]
	v_mfma_f32_16x16x32_bf16 v[42:45], v[140:143], v[188:191], v[42:45]
	v_mfma_f32_16x16x32_bf16 v[34:37], v[148:151], v[188:191], v[34:37]
	v_mfma_f32_16x16x32_bf16 v[26:29], v[140:143], v[210:213], v[26:29]
	v_mfma_f32_16x16x32_bf16 v[18:21], v[148:151], v[210:213], v[18:21]
	v_mfma_f32_16x16x32_bf16 v[62:65], v[144:147], v[176:179], v[62:65]
	v_mfma_f32_16x16x32_bf16 v[58:61], v[152:155], v[176:179], v[58:61]
	v_mfma_f32_16x16x32_bf16 v[54:57], v[144:147], v[184:187], v[54:57]
	v_mfma_f32_16x16x32_bf16 v[50:53], v[152:155], v[184:187], v[50:53]
	v_mfma_f32_16x16x32_bf16 v[42:45], v[144:147], v[206:209], v[42:45]
	v_mfma_f32_16x16x32_bf16 v[34:37], v[152:155], v[206:209], v[34:37]
	v_mfma_f32_16x16x32_bf16 v[26:29], v[144:147], v[220:223], v[26:29]
	v_mfma_f32_16x16x32_bf16 v[18:21], v[152:155], v[220:223], v[18:21]
	v_mfma_f32_16x16x32_bf16 v[46:49], v[156:159], v[172:175], v[46:49]
	v_mfma_f32_16x16x32_bf16 v[38:41], v[164:167], v[172:175], v[38:41]
	v_mfma_f32_16x16x32_bf16 v[30:33], v[156:159], v[180:183], v[30:33]
	v_mfma_f32_16x16x32_bf16 v[22:25], v[164:167], v[180:183], v[22:25]
	v_mfma_f32_16x16x32_bf16 v[14:17], v[156:159], v[188:191], v[14:17]
	v_mfma_f32_16x16x32_bf16 v[10:13], v[164:167], v[188:191], v[10:13]
	v_mfma_f32_16x16x32_bf16 v[6:9], v[156:159], v[210:213], v[6:9]
	v_mfma_f32_16x16x32_bf16 v[2:5], v[164:167], v[210:213], v[2:5]
	v_mfma_f32_16x16x32_bf16 v[46:49], v[160:163], v[176:179], v[46:49]
	v_mfma_f32_16x16x32_bf16 v[38:41], v[168:171], v[176:179], v[38:41]
	v_mfma_f32_16x16x32_bf16 v[30:33], v[160:163], v[184:187], v[30:33]
	v_mfma_f32_16x16x32_bf16 v[22:25], v[168:171], v[184:187], v[22:25]
	v_mfma_f32_16x16x32_bf16 v[14:17], v[160:163], v[206:209], v[14:17]
	v_mfma_f32_16x16x32_bf16 v[10:13], v[168:171], v[206:209], v[10:13]
	v_mfma_f32_16x16x32_bf16 v[6:9], v[160:163], v[220:223], v[6:9]
	v_mfma_f32_16x16x32_bf16 v[2:5], v[168:171], v[220:223], v[2:5]
	s_barrier
	s_add_u32 s15, s15, 0x100
	s_addc_u32 s16, s16, 0
	s_add_u32 s0, s0, 0x100
	s_addc_u32 s1, s1, 0
	s_cmp_ge_i32 s38, s31
	s_mov_b32 s28, s38
	s_cbranch_scc0 .LBB0_296
; __device__ __forceinline__ unsigned cvtpk(float lo, float hi) { f32x2_t v = {lo, hi}; bf16x2_t b = __builtin_convertvector(v, bf16x2_t); return __builtin_bit_cast(unsigned, b); }
; __device__ __forceinline__ float bflo(unsigned u) { return __uint_as_float(u << 16); }
; __device__ __forceinline__ float bfhi(unsigned u) { return __uint_as_float(u & 0xffff0000u); }
;     __device__ __forceinline__ void operator()(const AccT& acc, const Unit& u, int wr, int wc, int fr, int fq) const {
;     ...
;                 for (int bj = 0; bj < 2; ++bj) { const u32x4 h4 = hv[ai][m][bj];
;                     f32x4 v0 = {bflo(h4.x), bfhi(h4.x), bflo(h4.y), bfhi(h4.y)}, v1 = {bflo(h4.z), bfhi(h4.z), bflo(h4.w), bfhi(h4.w)};
;                     v0 = v0 + acc[ai][bj][m][0] * c; v1 = v1 + acc[ai][bj][m][1] * c;
;                     q += ((v0[0] * v0[0] + v0[1] * v0[1]) + (v0[2] * v0[2] + v0[3] * v0[3])) + ((v1[0] * v1[0] + v1[1] * v1[1]) + (v1[2] * v1[2] + v1[3] * v1[3]));
;                     u32x4 w; w.x = cvtpk(v0[0], v0[1]); w.y = cvtpk(v0[2], v0[3]); w.z = cvtpk(v1[0], v1[1]); w.w = cvtpk(v1[2], v1[3]); *(u32x4*)(bp + bj * 128) = w; }
	v_readlane_b32 s92, v255, 40
	v_pk_mul_f32 v[208:209], v[128:129], 0.5 op_sel_hi:[1,0]
	v_pk_mul_f32 v[210:211], v[126:127], 0.5 op_sel_hi:[1,0]
	v_pk_mul_f32 v[212:213], v[124:125], 0.5 op_sel_hi:[1,0]
	v_pk_mul_f32 v[214:215], v[122:123], 0.5 op_sel_hi:[1,0]
	v_pk_mul_f32 v[192:193], v[112:113], 0.5 op_sel_hi:[1,0]
	v_pk_mul_f32 v[190:191], v[110:111], 0.5 op_sel_hi:[1,0]
	v_pk_mul_f32 v[188:189], v[104:105], 0.5 op_sel_hi:[1,0]
	v_pk_mul_f32 v[186:187], v[102:103], 0.5 op_sel_hi:[1,0]
	v_pk_mul_f32 v[184:185], v[120:121], 0.5 op_sel_hi:[1,0]
	v_pk_mul_f32 v[182:183], v[118:119], 0.5 op_sel_hi:[1,0]
	v_pk_mul_f32 v[180:181], v[116:117], 0.5 op_sel_hi:[1,0]
	v_pk_mul_f32 v[178:179], v[114:115], 0.5 op_sel_hi:[1,0]
	v_pk_mul_f32 v[176:177], v[96:97], 0.5 op_sel_hi:[1,0]
	v_pk_mul_f32 v[174:175], v[94:95], 0.5 op_sel_hi:[1,0]
	v_pk_mul_f32 v[172:173], v[88:89], 0.5 op_sel_hi:[1,0]
	v_pk_mul_f32 v[170:171], v[86:87], 0.5 op_sel_hi:[1,0]
	v_pk_mul_f32 v[168:169], v[108:109], 0.5 op_sel_hi:[1,0]
	v_pk_mul_f32 v[166:167], v[106:107], 0.5 op_sel_hi:[1,0]
	v_pk_mul_f32 v[164:165], v[100:101], 0.5 op_sel_hi:[1,0]
	v_pk_mul_f32 v[162:163], v[98:99], 0.5 op_sel_hi:[1,0]
	v_pk_mul_f32 v[160:161], v[80:81], 0.5 op_sel_hi:[1,0]
	v_pk_mul_f32 v[158:159], v[78:79], 0.5 op_sel_hi:[1,0]
	v_pk_mul_f32 v[156:157], v[76:77], 0.5 op_sel_hi:[1,0]
	v_pk_mul_f32 v[154:155], v[74:75], 0.5 op_sel_hi:[1,0]
	v_pk_mul_f32 v[150:151], v[92:93], 0.5 op_sel_hi:[1,0]
	v_pk_mul_f32 v[148:149], v[90:91], 0.5 op_sel_hi:[1,0]
	v_pk_mul_f32 v[146:147], v[84:85], 0.5 op_sel_hi:[1,0]
	v_pk_mul_f32 v[144:145], v[82:83], 0.5 op_sel_hi:[1,0]
	v_pk_mul_f32 v[142:143], v[72:73], 0.5 op_sel_hi:[1,0]
	v_pk_mul_f32 v[140:141], v[70:71], 0.5 op_sel_hi:[1,0]
	v_pk_mul_f32 v[128:129], v[68:69], 0.5 op_sel_hi:[1,0]
	v_pk_mul_f32 v[126:127], v[66:67], 0.5 op_sel_hi:[1,0]
	v_pk_mul_f32 v[124:125], v[64:65], 0.5 op_sel_hi:[1,0]
	v_pk_mul_f32 v[122:123], v[62:63], 0.5 op_sel_hi:[1,0]
	v_pk_mul_f32 v[120:121], v[60:61], 0.5 op_sel_hi:[1,0]
	v_pk_mul_f32 v[118:119], v[58:59], 0.5 op_sel_hi:[1,0]
	v_pk_mul_f32 v[116:117], v[48:49], 0.5 op_sel_hi:[1,0]
	v_pk_mul_f32 v[114:115], v[46:47], 0.5 op_sel_hi:[1,0]
	v_pk_mul_f32 v[112:113], v[40:41], 0.5 op_sel_hi:[1,0]
	v_pk_mul_f32 v[110:111], v[38:39], 0.5 op_sel_hi:[1,0]
	v_pk_mul_f32 v[108:109], v[56:57], 0.5 op_sel_hi:[1,0]
	v_pk_mul_f32 v[106:107], v[54:55], 0.5 op_sel_hi:[1,0]
	v_pk_mul_f32 v[104:105], v[52:53], 0.5 op_sel_hi:[1,0]
	v_pk_mul_f32 v[102:103], v[50:51], 0.5 op_sel_hi:[1,0]
	v_pk_mul_f32 v[100:101], v[32:33], 0.5 op_sel_hi:[1,0]
	v_pk_mul_f32 v[98:99], v[30:31], 0.5 op_sel_hi:[1,0]
	v_pk_mul_f32 v[96:97], v[24:25], 0.5 op_sel_hi:[1,0]
	v_pk_mul_f32 v[94:95], v[22:23], 0.5 op_sel_hi:[1,0]
	v_pk_mul_f32 v[92:93], v[44:45], 0.5 op_sel_hi:[1,0]
	v_pk_mul_f32 v[90:91], v[42:43], 0.5 op_sel_hi:[1,0]
	v_pk_mul_f32 v[88:89], v[36:37], 0.5 op_sel_hi:[1,0]
	v_pk_mul_f32 v[86:87], v[34:35], 0.5 op_sel_hi:[1,0]
	v_pk_mul_f32 v[84:85], v[16:17], 0.5 op_sel_hi:[1,0]
	v_pk_mul_f32 v[82:83], v[14:15], 0.5 op_sel_hi:[1,0]
	v_pk_mul_f32 v[80:81], v[12:13], 0.5 op_sel_hi:[1,0]
	v_pk_mul_f32 v[78:79], v[10:11], 0.5 op_sel_hi:[1,0]
	v_pk_mul_f32 v[76:77], v[28:29], 0.5 op_sel_hi:[1,0]
	v_pk_mul_f32 v[74:75], v[26:27], 0.5 op_sel_hi:[1,0]
	v_pk_mul_f32 v[72:73], v[20:21], 0.5 op_sel_hi:[1,0]
	v_pk_mul_f32 v[70:71], v[18:19], 0.5 op_sel_hi:[1,0]
	v_pk_mul_f32 v[68:69], v[8:9], 0.5 op_sel_hi:[1,0]
	v_pk_mul_f32 v[66:67], v[6:7], 0.5 op_sel_hi:[1,0]
	v_pk_mul_f32 v[64:65], v[4:5], 0.5 op_sel_hi:[1,0]
	v_pk_mul_f32 v[62:63], v[2:3], 0.5 op_sel_hi:[1,0]
	v_readlane_b32 s93, v255, 41

; #define PG8_STAGE(bufoff, gbase, voff) do { _Pragma("unroll") for (int _i = 0; _i < 2; ++_i) \
;         __builtin_amdgcn_global_load_lds((const unsigned*)((const char*)(gbase) + (voff)[_i]), (LAS unsigned*)(lds + (bufoff) + ldsw + _i * 8192), 16, 0, 0); } while (0)
; #define PG8_LDA(dst, b, h) do { _Pragma("unroll") for (int m = 0; m < 4; ++m) _Pragma("unroll") for (int k = 0; k < 2; ++k) dst[m][k] = *(const LAS bf16x8*)(lds + PG8_SA(b, h) + aoff + m * 2048 + k * 1024); } while (0)
; #define PG8_LDB(dst, b, h) do { _Pragma("unroll") for (int n = 0; n < 2; ++n) _Pragma("unroll") for (int k = 0; k < 2; ++k) dst[n][k] = *(const LAS bf16x8*)(lds + PG8_SB(b, h) + boff + n * 2048 + k * 1024); } while (0)
; #define PG8_MMA(ai, bj, At, Bt) do { __builtin_amdgcn_s_setprio(1); _Pragma("unroll") for (int m = 0; m < 4; ++m) _Pragma("unroll") for (int n = 0; n < 2; ++n) _Pragma("unroll") for (int k = 0; k < 2; ++k) \
;         acc[ai][bj][m][n] = __builtin_amdgcn_mfma_f32_16x16x32_bf16(Bt[n][k], At[m][k], acc[ai][bj][m][n], 0, 0, 0); __builtin_amdgcn_s_setprio(0); } while (0)
; #define PG8_WAIT_V(n) asm volatile("s_waitcnt vmcnt(" #n ")" ::: "memory")
; #define PG8_WAIT_L(n) asm volatile("s_waitcnt lgkmcnt(" #n ")" ::: "memory")
; #define PG8_BAR __builtin_amdgcn_s_barrier()
; #define PG8_SCHED __builtin_amdgcn_sched_barrier(0)
; template <class Epi, class Sched>
; __device__ __forceinline__ void gemm_phase(LAS unsigned char* lds, const Gemm g, const Sched& S, const Epi& E) {
;     ...
;         for (int t = 0; t < nt; t += 2) {
;             const bool last = (t == nt - 2);
;             const char* a1 = cA + (size_t)(t + 1) * kstep;
;             const char* a2 = last ? nA : cA + (size_t)(t + 2) * kstep; const char* b2 = last ? nB : cB + (size_t)(t + 2) * kstep;
;             const char* a3 = a2 + kstep; const char* b3 = b2 + kstep;
;             PG8_LDB(B0, 0, 0); PG8_LDB(B1, 0, 1); PG8_SCHED; PG8_LDA(At, 0, 0); PG8_STAGE(PG8_SA(1, 1), a1 + hstep, voffA);
;             PG8_WAIT_V(8); PG8_WAIT_L(0); PG8_BAR; PG8_MMA(0, 0, At, B0); PG8_MMA(0, 1, At, B1); PG8_BAR; PG8_SCHED;
;             PG8_LDA(At, 0, 1); PG8_STAGE(PG8_SB(0, 0), b2, voffB); PG8_STAGE(PG8_SB(0, 1), b2 + hstep, voffB); PG8_STAGE(PG8_SA(0, 0), a2, voffA);
.LBB0_428:
	ds_read_b128 v[130:133], v235
	ds_read_b128 v[134:137], v235 offset:1024
	ds_read_b128 v[138:141], v235 offset:2048
	ds_read_b128 v[142:145], v235 offset:3072
	ds_read_b128 v[146:149], v238
	ds_read_b128 v[150:153], v238 offset:1024
	ds_read_b128 v[166:169], v238 offset:2048
	ds_read_b128 v[170:173], v238 offset:3072
	ds_read_b128 v[174:177], v189
	ds_read_b128 v[178:181], v189 offset:1024
	ds_read_b128 v[190:193], v189 offset:2048
	ds_read_b128 v[206:209], v189 offset:3072
	ds_read_b128 v[210:213], v189 offset:4096
	ds_read_b128 v[214:217], v189 offset:5120
	ds_read_b128 v[218:221], v189 offset:6144
	ds_read_b128 v[222:225], v189 offset:7168
	s_add_i32 s38, s28, 2
	s_add_u32 s26, s0, 0x80
	s_addc_u32 s29, s1, 0
	s_add_i32 s39, 0, 0x10000
	s_cmp_eq_u32 s84, s28
	s_cselect_b32 s29, s65, s29
	s_cselect_b32 s28, s64, s26
	s_cselect_b32 s47, s67, s16
	s_cselect_b32 s46, s66, s15
	s_add_i32 s26, 0, 0x14000
	s_add_i32 m0, s13, 0xc000
	v_lshl_add_u64 v[186:187], s[0:1], 0, v[164:165]
	global_load_lds_dwordx4 v[186:187], off
	s_add_i32 m0, s13, 0xe000
	v_lshl_add_u64 v[186:187], s[0:1], 0, v[162:163]
	global_load_lds_dwordx4 v[186:187], off
	s_waitcnt vmcnt(8)
	s_waitcnt lgkmcnt(0)
	s_barrier
	s_waitcnt lgkmcnt(0)
	v_mfma_f32_16x16x32_bf16 v[126:129], v[130:133], v[174:177], v[126:129]
	v_mfma_f32_16x16x32_bf16 v[122:125], v[138:141], v[174:177], v[122:125]
	v_mfma_f32_16x16x32_bf16 v[110:113], v[130:133], v[190:193], v[110:113]
	v_mfma_f32_16x16x32_bf16 v[106:109], v[138:141], v[190:193], v[106:109]
	v_mfma_f32_16x16x32_bf16 v[94:97], v[130:133], v[210:213], v[94:97]
	v_mfma_f32_16x16x32_bf16 v[90:93], v[138:141], v[210:213], v[90:93]
	v_mfma_f32_16x16x32_bf16 v[78:81], v[130:133], v[218:221], v[78:81]
	v_mfma_f32_16x16x32_bf16 v[74:77], v[138:141], v[218:221], v[74:77]
	v_mfma_f32_16x16x32_bf16 v[126:129], v[134:137], v[178:181], v[126:129]
	v_mfma_f32_16x16x32_bf16 v[122:125], v[142:145], v[178:181], v[122:125]
	v_mfma_f32_16x16x32_bf16 v[110:113], v[134:137], v[206:209], v[110:113]
	v_mfma_f32_16x16x32_bf16 v[106:109], v[142:145], v[206:209], v[106:109]
	v_mfma_f32_16x16x32_bf16 v[94:97], v[134:137], v[214:217], v[94:97]
	v_mfma_f32_16x16x32_bf16 v[90:93], v[142:145], v[214:217], v[90:93]
	v_mfma_f32_16x16x32_bf16 v[78:81], v[134:137], v[222:225], v[78:81]
	v_mfma_f32_16x16x32_bf16 v[74:77], v[142:145], v[222:225], v[74:77]
	v_mfma_f32_16x16x32_bf16 v[118:121], v[146:149], v[174:177], v[118:121]
	v_mfma_f32_16x16x32_bf16 v[114:117], v[166:169], v[174:177], v[114:117]
	v_mfma_f32_16x16x32_bf16 v[102:105], v[146:149], v[190:193], v[102:105]
	v_mfma_f32_16x16x32_bf16 v[98:101], v[166:169], v[190:193], v[98:101]
	v_mfma_f32_16x16x32_bf16 v[86:89], v[146:149], v[210:213], v[86:89]
	v_mfma_f32_16x16x32_bf16 v[82:85], v[166:169], v[210:213], v[82:85]
	v_mfma_f32_16x16x32_bf16 v[70:73], v[146:149], v[218:221], v[70:73]
	v_mfma_f32_16x16x32_bf16 v[66:69], v[166:169], v[218:221], v[66:69]
	v_mfma_f32_16x16x32_bf16 v[118:121], v[150:153], v[178:181], v[118:121]
	v_mfma_f32_16x16x32_bf16 v[114:117], v[170:173], v[178:181], v[114:117]
	v_mfma_f32_16x16x32_bf16 v[102:105], v[150:153], v[206:209], v[102:105]
	v_mfma_f32_16x16x32_bf16 v[98:101], v[170:173], v[206:209], v[98:101]
	v_mfma_f32_16x16x32_bf16 v[86:89], v[150:153], v[214:217], v[86:89]
	v_mfma_f32_16x16x32_bf16 v[82:85], v[170:173], v[214:217], v[82:85]
	v_mfma_f32_16x16x32_bf16 v[70:73], v[150:153], v[222:225], v[70:73]
	v_mfma_f32_16x16x32_bf16 v[66:69], v[170:173], v[222:225], v[66:69]
	s_barrier
	s_add_i32 s39, s39, s12
	v_lshl_add_u64 v[186:187], s[46:47], 0, v[0:1]
	s_mov_b32 m0, s39
	ds_read_b128 v[174:177], v189 offset:16384
	ds_read_b128 v[178:181], v189 offset:17408
	ds_read_b128 v[190:193], v189 offset:18432
	ds_read_b128 v[206:209], v189 offset:19456
	ds_read_b128 v[210:213], v189 offset:20480
	ds_read_b128 v[214:217], v189 offset:21504
	ds_read_b128 v[218:221], v189 offset:22528
	ds_read_b128 v[222:225], v189 offset:23552
	global_load_lds_dwordx4 v[186:187], off
	s_add_i32 m0, s39, 0x2000
	v_lshl_add_u64 v[226:227], s[46:47], 0, v[154:155]
	s_add_u32 s46, s46, s48
	s_addc_u32 s47, s47, s49
	s_add_i32 s26, s26, s12
	global_load_lds_dwordx4 v[226:227], off
	v_lshl_add_u64 v[228:229], s[46:47], 0, v[0:1]
	s_mov_b32 m0, s26
	v_lshl_add_u64 v[230:231], s[46:47], 0, v[154:155]
	global_load_lds_dwordx4 v[228:229], off
	s_add_i32 m0, s26, 0x2000
	v_lshl_add_u64 v[232:233], s[28:29], 0, v[158:159]
	global_load_lds_dwordx4 v[230:231], off
	s_mov_b32 m0, s13
	v_lshl_add_u64 v[244:245], s[28:29], 0, v[156:157]
	global_load_lds_dwordx4 v[232:233], off
	s_mov_b32 m0, s27
	s_nop 0
	global_load_lds_dwordx4 v[244:245], off
	s_waitcnt vmcnt(8)
	s_waitcnt lgkmcnt(0)
	s_barrier
; #define PG8_STAGE(bufoff, gbase, voff) do { _Pragma("unroll") for (int _i = 0; _i < 2; ++_i) \
;         __builtin_amdgcn_global_load_lds((const unsigned*)((const char*)(gbase) + (voff)[_i]), (LAS unsigned*)(lds + (bufoff) + ldsw + _i * 8192), 16, 0, 0); } while (0)
; #define PG8_LDA(dst, b, h) do { _Pragma("unroll") for (int m = 0; m < 4; ++m) _Pragma("unroll") for (int k = 0; k < 2; ++k) dst[m][k] = *(const LAS bf16x8*)(lds + PG8_SA(b, h) + aoff + m * 2048 + k * 1024); } while (0)
; #define PG8_LDB(dst, b, h) do { _Pragma("unroll") for (int n = 0; n < 2; ++n) _Pragma("unroll") for (int k = 0; k < 2; ++k) dst[n][k] = *(const LAS bf16x8*)(lds + PG8_SB(b, h) + boff + n * 2048 + k * 1024); } while (0)
; #define PG8_MMA(ai, bj, At, Bt) do { __builtin_amdgcn_s_setprio(1); _Pragma("unroll") for (int m = 0; m < 4; ++m) _Pragma("unroll") for (int n = 0; n < 2; ++n) _Pragma("unroll") for (int k = 0; k < 2; ++k) \
;         acc[ai][bj][m][n] = __builtin_amdgcn_mfma_f32_16x16x32_bf16(Bt[n][k], At[m][k], acc[ai][bj][m][n], 0, 0, 0); __builtin_amdgcn_s_setprio(0); } while (0)
; #define PG8_WAIT_V(n) asm volatile("s_waitcnt vmcnt(" #n ")" ::: "memory")
; #define PG8_WAIT_L(n) asm volatile("s_waitcnt lgkmcnt(" #n ")" ::: "memory")
; #define PG8_BAR __builtin_amdgcn_s_barrier()
; #define PG8_SCHED __builtin_amdgcn_sched_barrier(0)
; template <class Epi, class Sched>
; __device__ __forceinline__ void gemm_phase(LAS unsigned char* lds, const Gemm g, const Sched& S, const Epi& E) {
;     ...
;             PG8_WAIT_V(8); PG8_WAIT_L(0); PG8_BAR; PG8_MMA(1, 0, At, B0); PG8_MMA(1, 1, At, B1); PG8_BAR; PG8_SCHED;
;             PG8_LDB(B0, 1, 0); PG8_LDB(B1, 1, 1); PG8_SCHED; PG8_LDA(At, 1, 0); PG8_STAGE(PG8_SA(0, 1), a2 + hstep, voffA);
;             PG8_WAIT_V(8); PG8_WAIT_L(0); PG8_BAR; PG8_MMA(0, 0, At, B0); PG8_MMA(0, 1, At, B1); PG8_BAR; PG8_SCHED;
	s_waitcnt lgkmcnt(0)
	v_mfma_f32_16x16x32_bf16 v[62:65], v[130:133], v[174:177], v[62:65]
	v_mfma_f32_16x16x32_bf16 v[58:61], v[138:141], v[174:177], v[58:61]
	v_mfma_f32_16x16x32_bf16 v[46:49], v[130:133], v[190:193], v[46:49]
	v_mfma_f32_16x16x32_bf16 v[42:45], v[138:141], v[190:193], v[42:45]
	v_mfma_f32_16x16x32_bf16 v[30:33], v[130:133], v[210:213], v[30:33]
	v_mfma_f32_16x16x32_bf16 v[26:29], v[138:141], v[210:213], v[26:29]
	v_mfma_f32_16x16x32_bf16 v[14:17], v[130:133], v[218:221], v[14:17]
	v_mfma_f32_16x16x32_bf16 v[10:13], v[138:141], v[218:221], v[10:13]
	v_mfma_f32_16x16x32_bf16 v[62:65], v[134:137], v[178:181], v[62:65]
	v_mfma_f32_16x16x32_bf16 v[58:61], v[142:145], v[178:181], v[58:61]
	v_mfma_f32_16x16x32_bf16 v[46:49], v[134:137], v[206:209], v[46:49]
	v_mfma_f32_16x16x32_bf16 v[42:45], v[142:145], v[206:209], v[42:45]
	v_mfma_f32_16x16x32_bf16 v[30:33], v[134:137], v[214:217], v[30:33]
	v_mfma_f32_16x16x32_bf16 v[26:29], v[142:145], v[214:217], v[26:29]
	v_mfma_f32_16x16x32_bf16 v[14:17], v[134:137], v[222:225], v[14:17]
	v_mfma_f32_16x16x32_bf16 v[10:13], v[142:145], v[222:225], v[10:13]
	v_mfma_f32_16x16x32_bf16 v[54:57], v[146:149], v[174:177], v[54:57]
	v_mfma_f32_16x16x32_bf16 v[50:53], v[166:169], v[174:177], v[50:53]
	v_mfma_f32_16x16x32_bf16 v[38:41], v[146:149], v[190:193], v[38:41]
	v_mfma_f32_16x16x32_bf16 v[34:37], v[166:169], v[190:193], v[34:37]
	v_mfma_f32_16x16x32_bf16 v[22:25], v[146:149], v[210:213], v[22:25]
	v_mfma_f32_16x16x32_bf16 v[18:21], v[166:169], v[210:213], v[18:21]
	v_mfma_f32_16x16x32_bf16 v[6:9], v[146:149], v[218:221], v[6:9]
	v_mfma_f32_16x16x32_bf16 v[2:5], v[166:169], v[218:221], v[2:5]
	v_mfma_f32_16x16x32_bf16 v[54:57], v[150:153], v[178:181], v[54:57]
	v_mfma_f32_16x16x32_bf16 v[50:53], v[170:173], v[178:181], v[50:53]
	v_mfma_f32_16x16x32_bf16 v[38:41], v[150:153], v[206:209], v[38:41]
	v_mfma_f32_16x16x32_bf16 v[34:37], v[170:173], v[206:209], v[34:37]
	v_mfma_f32_16x16x32_bf16 v[22:25], v[150:153], v[214:217], v[22:25]
	v_mfma_f32_16x16x32_bf16 v[18:21], v[170:173], v[214:217], v[18:21]
	v_mfma_f32_16x16x32_bf16 v[6:9], v[150:153], v[222:225], v[6:9]
	v_mfma_f32_16x16x32_bf16 v[2:5], v[170:173], v[222:225], v[2:5]
	s_barrier
	ds_read_b128 v[130:133], v239
	ds_read_b128 v[134:137], v239 offset:1024
	ds_read_b128 v[138:141], v239 offset:2048
	ds_read_b128 v[142:145], v239 offset:3072
	ds_read_b128 v[146:149], v250
	ds_read_b128 v[150:153], v250 offset:1024
	ds_read_b128 v[166:169], v250 offset:2048
	ds_read_b128 v[170:173], v250 offset:3072
	s_add_i32 s26, 0, 0x18000
	s_add_i32 s39, 0, 0x1c000
	s_add_u32 s28, s28, s48
	s_addc_u32 s29, s29, s49
	s_mov_b32 m0, s30
	v_lshl_add_u64 v[246:247], s[28:29], 0, v[158:159]
	ds_read_b128 v[174:177], v189 offset:32768
	ds_read_b128 v[178:181], v189 offset:33792
	ds_read_b128 v[190:193], v189 offset:34816
	ds_read_b128 v[206:209], v189 offset:35840
	ds_read_b128 v[210:213], v189 offset:36864
	ds_read_b128 v[214:217], v189 offset:37888
	ds_read_b128 v[218:221], v189 offset:38912
	ds_read_b128 v[222:225], v189 offset:39936
	global_load_lds_dwordx4 v[246:247], off
	s_mov_b32 m0, s31
	v_lshl_add_u64 v[246:247], s[28:29], 0, v[156:157]
	global_load_lds_dwordx4 v[246:247], off
	s_waitcnt vmcnt(8)
	s_waitcnt lgkmcnt(0)
	s_barrier
	s_waitcnt lgkmcnt(0)
	v_mfma_f32_16x16x32_bf16 v[126:129], v[130:133], v[174:177], v[126:129]
	v_mfma_f32_16x16x32_bf16 v[122:125], v[138:141], v[174:177], v[122:125]
	v_mfma_f32_16x16x32_bf16 v[110:113], v[130:133], v[190:193], v[110:113]
	v_mfma_f32_16x16x32_bf16 v[106:109], v[138:141], v[190:193], v[106:109]
	v_mfma_f32_16x16x32_bf16 v[94:97], v[130:133], v[210:213], v[94:97]
	v_mfma_f32_16x16x32_bf16 v[90:93], v[138:141], v[210:213], v[90:93]
	v_mfma_f32_16x16x32_bf16 v[78:81], v[130:133], v[218:221], v[78:81]
	v_mfma_f32_16x16x32_bf16 v[74:77], v[138:141], v[218:221], v[74:77]
	v_mfma_f32_16x16x32_bf16 v[126:129], v[134:137], v[178:181], v[126:129]
	v_mfma_f32_16x16x32_bf16 v[122:125], v[142:145], v[178:181], v[122:125]
	v_mfma_f32_16x16x32_bf16 v[110:113], v[134:137], v[206:209], v[110:113]
	v_mfma_f32_16x16x32_bf16 v[106:109], v[142:145], v[206:209], v[106:109]
	v_mfma_f32_16x16x32_bf16 v[94:97], v[134:137], v[214:217], v[94:97]
	v_mfma_f32_16x16x32_bf16 v[90:93], v[142:145], v[214:217], v[90:93]
	v_mfma_f32_16x16x32_bf16 v[78:81], v[134:137], v[222:225], v[78:81]
	v_mfma_f32_16x16x32_bf16 v[74:77], v[142:145], v[222:225], v[74:77]
	v_mfma_f32_16x16x32_bf16 v[118:121], v[146:149], v[174:177], v[118:121]
	v_mfma_f32_16x16x32_bf16 v[114:117], v[166:169], v[174:177], v[114:117]
	v_mfma_f32_16x16x32_bf16 v[102:105], v[146:149], v[190:193], v[102:105]
	v_mfma_f32_16x16x32_bf16 v[98:101], v[166:169], v[190:193], v[98:101]
	v_mfma_f32_16x16x32_bf16 v[86:89], v[146:149], v[210:213], v[86:89]
	v_mfma_f32_16x16x32_bf16 v[82:85], v[166:169], v[210:213], v[82:85]
	v_mfma_f32_16x16x32_bf16 v[70:73], v[146:149], v[218:221], v[70:73]
	v_mfma_f32_16x16x32_bf16 v[66:69], v[166:169], v[218:221], v[66:69]
	v_mfma_f32_16x16x32_bf16 v[118:121], v[150:153], v[178:181], v[118:121]
	v_mfma_f32_16x16x32_bf16 v[114:117], v[170:173], v[178:181], v[114:117]
	v_mfma_f32_16x16x32_bf16 v[102:105], v[150:153], v[206:209], v[102:105]
	v_mfma_f32_16x16x32_bf16 v[98:101], v[170:173], v[206:209], v[98:101]
	v_mfma_f32_16x16x32_bf16 v[86:89], v[150:153], v[214:217], v[86:89]
	v_mfma_f32_16x16x32_bf16 v[82:85], v[170:173], v[214:217], v[82:85]
	v_mfma_f32_16x16x32_bf16 v[70:73], v[150:153], v[222:225], v[70:73]
	v_mfma_f32_16x16x32_bf16 v[66:69], v[170:173], v[222:225], v[66:69]
	s_barrier
; #define PG8_STAGE(bufoff, gbase, voff) do { _Pragma("unroll") for (int _i = 0; _i < 2; ++_i) \
;         __builtin_amdgcn_global_load_lds((const unsigned*)((const char*)(gbase) + (voff)[_i]), (LAS unsigned*)(lds + (bufoff) + ldsw + _i * 8192), 16, 0, 0); } while (0)
; #define PG8_LDA(dst, b, h) do { _Pragma("unroll") for (int m = 0; m < 4; ++m) _Pragma("unroll") for (int k = 0; k < 2; ++k) dst[m][k] = *(const LAS bf16x8*)(lds + PG8_SA(b, h) + aoff + m * 2048 + k * 1024); } while (0)
; #define PG8_MMA(ai, bj, At, Bt) do { __builtin_amdgcn_s_setprio(1); _Pragma("unroll") for (int m = 0; m < 4; ++m) _Pragma("unroll") for (int n = 0; n < 2; ++n) _Pragma("unroll") for (int k = 0; k < 2; ++k) \
;         acc[ai][bj][m][n] = __builtin_amdgcn_mfma_f32_16x16x32_bf16(Bt[n][k], At[m][k], acc[ai][bj][m][n], 0, 0, 0); __builtin_amdgcn_s_setprio(0); } while (0)
; #define PG8_WAIT_V(n) asm volatile("s_waitcnt vmcnt(" #n ")" ::: "memory")
; #define PG8_WAIT_L(n) asm volatile("s_waitcnt lgkmcnt(" #n ")" ::: "memory")
; #define PG8_BAR __builtin_amdgcn_s_barrier()
; #define PG8_SCHED __builtin_amdgcn_sched_barrier(0)
; template <class Epi, class Sched>
; __device__ __forceinline__ void gemm_phase(LAS unsigned char* lds, const Gemm g, const Sched& S, const Epi& E) {
;     ...
;             PG8_LDA(At, 1, 1); PG8_STAGE(PG8_SB(1, 0), b3, voffB); PG8_STAGE(PG8_SB(1, 1), b3 + hstep, voffB); PG8_STAGE(PG8_SA(1, 0), a3, voffA);
;             PG8_WAIT_V(8); PG8_WAIT_L(0); PG8_BAR; PG8_MMA(1, 0, At, B0); PG8_MMA(1, 1, At, B1); PG8_BAR; PG8_SCHED;
;         }
	s_add_i32 s26, s26, s12
	v_lshl_add_u64 v[186:187], v[186:187], 0, s[18:19]
	s_mov_b32 m0, s26
	ds_read_b128 v[174:177], v189 offset:49152
	ds_read_b128 v[178:181], v189 offset:50176
	ds_read_b128 v[190:193], v189 offset:51200
	ds_read_b128 v[206:209], v189 offset:52224
	ds_read_b128 v[210:213], v189 offset:53248
	ds_read_b128 v[214:217], v189 offset:54272
	ds_read_b128 v[218:221], v189 offset:55296
	ds_read_b128 v[222:225], v189 offset:56320
	global_load_lds_dwordx4 v[186:187], off
	v_lshl_add_u64 v[186:187], v[226:227], 0, s[18:19]
	s_add_i32 m0, s26, 0x2000
	s_add_i32 s26, s39, s12
	global_load_lds_dwordx4 v[186:187], off
	s_mov_b32 m0, s26
	v_lshl_add_u64 v[186:187], v[228:229], 0, s[18:19]
	global_load_lds_dwordx4 v[186:187], off
	s_add_i32 m0, s26, 0x2000
	v_lshl_add_u64 v[186:187], v[230:231], 0, s[18:19]
	global_load_lds_dwordx4 v[186:187], off
	s_mov_b32 m0, s34
	v_lshl_add_u64 v[186:187], v[232:233], 0, s[18:19]
	global_load_lds_dwordx4 v[186:187], off
	s_mov_b32 m0, s35
	v_lshl_add_u64 v[186:187], v[244:245], 0, s[18:19]
	global_load_lds_dwordx4 v[186:187], off
	s_waitcnt vmcnt(8)
	s_waitcnt lgkmcnt(0)
	s_barrier
	s_waitcnt lgkmcnt(0)
	v_mfma_f32_16x16x32_bf16 v[62:65], v[130:133], v[174:177], v[62:65]
	v_mfma_f32_16x16x32_bf16 v[58:61], v[138:141], v[174:177], v[58:61]
	v_mfma_f32_16x16x32_bf16 v[46:49], v[130:133], v[190:193], v[46:49]
	v_mfma_f32_16x16x32_bf16 v[42:45], v[138:141], v[190:193], v[42:45]
	v_mfma_f32_16x16x32_bf16 v[30:33], v[130:133], v[210:213], v[30:33]
	v_mfma_f32_16x16x32_bf16 v[26:29], v[138:141], v[210:213], v[26:29]
	v_mfma_f32_16x16x32_bf16 v[14:17], v[130:133], v[218:221], v[14:17]
	v_mfma_f32_16x16x32_bf16 v[10:13], v[138:141], v[218:221], v[10:13]
	v_mfma_f32_16x16x32_bf16 v[62:65], v[134:137], v[178:181], v[62:65]
	v_mfma_f32_16x16x32_bf16 v[58:61], v[142:145], v[178:181], v[58:61]
	v_mfma_f32_16x16x32_bf16 v[46:49], v[134:137], v[206:209], v[46:49]
	v_mfma_f32_16x16x32_bf16 v[42:45], v[142:145], v[206:209], v[42:45]
	v_mfma_f32_16x16x32_bf16 v[30:33], v[134:137], v[214:217], v[30:33]
	v_mfma_f32_16x16x32_bf16 v[26:29], v[142:145], v[214:217], v[26:29]
	v_mfma_f32_16x16x32_bf16 v[14:17], v[134:137], v[222:225], v[14:17]
	v_mfma_f32_16x16x32_bf16 v[10:13], v[142:145], v[222:225], v[10:13]
	v_mfma_f32_16x16x32_bf16 v[54:57], v[146:149], v[174:177], v[54:57]
	v_mfma_f32_16x16x32_bf16 v[50:53], v[166:169], v[174:177], v[50:53]
	v_mfma_f32_16x16x32_bf16 v[38:41], v[146:149], v[190:193], v[38:41]
	v_mfma_f32_16x16x32_bf16 v[34:37], v[166:169], v[190:193], v[34:37]
	v_mfma_f32_16x16x32_bf16 v[22:25], v[146:149], v[210:213], v[22:25]
	v_mfma_f32_16x16x32_bf16 v[18:21], v[166:169], v[210:213], v[18:21]
	v_mfma_f32_16x16x32_bf16 v[6:9], v[146:149], v[218:221], v[6:9]
	v_mfma_f32_16x16x32_bf16 v[2:5], v[166:169], v[218:221], v[2:5]
	v_mfma_f32_16x16x32_bf16 v[54:57], v[150:153], v[178:181], v[54:57]
	v_mfma_f32_16x16x32_bf16 v[50:53], v[170:173], v[178:181], v[50:53]
	v_mfma_f32_16x16x32_bf16 v[38:41], v[150:153], v[206:209], v[38:41]
	v_mfma_f32_16x16x32_bf16 v[34:37], v[170:173], v[206:209], v[34:37]
	v_mfma_f32_16x16x32_bf16 v[22:25], v[150:153], v[214:217], v[22:25]
	v_mfma_f32_16x16x32_bf16 v[18:21], v[170:173], v[214:217], v[18:21]
	v_mfma_f32_16x16x32_bf16 v[6:9], v[150:153], v[222:225], v[6:9]
	v_mfma_f32_16x16x32_bf16 v[2:5], v[170:173], v[222:225], v[2:5]
	s_barrier
	s_add_u32 s15, s15, 0x100
	s_addc_u32 s16, s16, 0
	s_add_u32 s0, s0, 0x100
	s_addc_u32 s1, s1, 0
	s_cmp_ge_i32 s38, s80
	s_mov_b32 s28, s38
	s_cbranch_scc0 .LBB0_428

; #define PG8_STAGE(bufoff, gbase, voff) do { _Pragma("unroll") for (int _i = 0; _i < 2; ++_i) \
;         __builtin_amdgcn_global_load_lds((const unsigned*)((const char*)(gbase) + (voff)[_i]), (LAS unsigned*)(lds + (bufoff) + ldsw + _i * 8192), 16, 0, 0); } while (0)
; #define PG8_LDA(dst, b, h) do { _Pragma("unroll") for (int m = 0; m < 4; ++m) _Pragma("unroll") for (int k = 0; k < 2; ++k) dst[m][k] = *(const LAS bf16x8*)(lds + PG8_SA(b, h) + aoff + m * 2048 + k * 1024); } while (0)
; #define PG8_LDB(dst, b, h) do { _Pragma("unroll") for (int n = 0; n < 2; ++n) _Pragma("unroll") for (int k = 0; k < 2; ++k) dst[n][k] = *(const LAS bf16x8*)(lds + PG8_SB(b, h) + boff + n * 2048 + k * 1024); } while (0)
; #define PG8_MMA(ai, bj, At, Bt) do { __builtin_amdgcn_s_setprio(1); _Pragma("unroll") for (int m = 0; m < 4; ++m) _Pragma("unroll") for (int n = 0; n < 2; ++n) _Pragma("unroll") for (int k = 0; k < 2; ++k) \
;         acc[ai][bj][m][n] = __builtin_amdgcn_mfma_f32_16x16x32_bf16(Bt[n][k], At[m][k], acc[ai][bj][m][n], 0, 0, 0); __builtin_amdgcn_s_setprio(0); } while (0)
; #define PG8_WAIT_V(n) asm volatile("s_waitcnt vmcnt(" #n ")" ::: "memory")
; #define PG8_WAIT_L(n) asm volatile("s_waitcnt lgkmcnt(" #n ")" ::: "memory")
; #define PG8_BAR __builtin_amdgcn_s_barrier()
; #define PG8_SCHED __builtin_amdgcn_sched_barrier(0)
; template <class Epi, class Sched>
; __device__ __forceinline__ void gemm_phase(LAS unsigned char* lds, const Gemm g, const Sched& S, const Epi& E) {
;     ...
;         for (int t = 0; t < nt; t += 2) {
;             const bool last = (t == nt - 2);
;             const char* a1 = cA + (size_t)(t + 1) * kstep;
;             const char* a2 = last ? nA : cA + (size_t)(t + 2) * kstep; const char* b2 = last ? nB : cB + (size_t)(t + 2) * kstep;
;             const char* a3 = a2 + kstep; const char* b3 = b2 + kstep;
;             PG8_LDB(B0, 0, 0); PG8_LDB(B1, 0, 1); PG8_SCHED; PG8_LDA(At, 0, 0); PG8_STAGE(PG8_SA(1, 1), a1 + hstep, voffA);
;             PG8_WAIT_V(8); PG8_WAIT_L(0); PG8_BAR; PG8_MMA(0, 0, At, B0); PG8_MMA(0, 1, At, B1); PG8_BAR; PG8_SCHED;
;             PG8_LDA(At, 0, 1); PG8_STAGE(PG8_SB(0, 0), b2, voffB); PG8_STAGE(PG8_SB(0, 1), b2 + hstep, voffB); PG8_STAGE(PG8_SA(0, 0), a2, voffA);
.LBB0_1440:
	ds_read_b128 v[130:133], v235
	ds_read_b128 v[134:137], v235 offset:1024
	ds_read_b128 v[138:141], v235 offset:2048
	ds_read_b128 v[142:145], v235 offset:3072
	ds_read_b128 v[146:149], v238
	ds_read_b128 v[150:153], v238 offset:1024
	ds_read_b128 v[166:169], v238 offset:2048
	ds_read_b128 v[170:173], v238 offset:3072
	ds_read_b128 v[174:177], v187
	ds_read_b128 v[178:181], v187 offset:1024
	ds_read_b128 v[188:191], v187 offset:2048
	ds_read_b128 v[206:209], v187 offset:3072
	ds_read_b128 v[210:213], v187 offset:4096
	ds_read_b128 v[214:217], v187 offset:5120
	ds_read_b128 v[218:221], v187 offset:6144
	ds_read_b128 v[222:225], v187 offset:7168
	s_add_i32 s38, s28, 2
	s_add_u32 s26, s0, 0x80
	s_addc_u32 s29, s1, 0
	s_add_i32 s39, 0, 0x10000
	s_cmp_eq_u32 s84, s28
	s_cselect_b32 s29, s43, s29
	s_cselect_b32 s28, s42, s26
	s_cselect_b32 s47, s41, s16
	s_cselect_b32 s46, s40, s15
	s_add_i32 s26, 0, 0x14000
	s_add_i32 m0, s13, 0xc000
	v_lshl_add_u64 v[182:183], s[0:1], 0, v[164:165]
	global_load_lds_dwordx4 v[182:183], off
	s_add_i32 m0, s13, 0xe000
	v_lshl_add_u64 v[182:183], s[0:1], 0, v[162:163]
	global_load_lds_dwordx4 v[182:183], off
	s_waitcnt vmcnt(8)
	s_waitcnt lgkmcnt(0)
	s_barrier
	s_waitcnt lgkmcnt(0)
	v_mfma_f32_16x16x32_bf16 v[126:129], v[130:133], v[174:177], v[126:129]
	v_mfma_f32_16x16x32_bf16 v[122:125], v[138:141], v[174:177], v[122:125]
	v_mfma_f32_16x16x32_bf16 v[110:113], v[130:133], v[188:191], v[110:113]
	v_mfma_f32_16x16x32_bf16 v[106:109], v[138:141], v[188:191], v[106:109]
	v_mfma_f32_16x16x32_bf16 v[94:97], v[130:133], v[210:213], v[94:97]
	v_mfma_f32_16x16x32_bf16 v[90:93], v[138:141], v[210:213], v[90:93]
	v_mfma_f32_16x16x32_bf16 v[78:81], v[130:133], v[218:221], v[78:81]
	v_mfma_f32_16x16x32_bf16 v[74:77], v[138:141], v[218:221], v[74:77]
	v_mfma_f32_16x16x32_bf16 v[126:129], v[134:137], v[178:181], v[126:129]
	v_mfma_f32_16x16x32_bf16 v[122:125], v[142:145], v[178:181], v[122:125]
	v_mfma_f32_16x16x32_bf16 v[110:113], v[134:137], v[206:209], v[110:113]
	v_mfma_f32_16x16x32_bf16 v[106:109], v[142:145], v[206:209], v[106:109]
	v_mfma_f32_16x16x32_bf16 v[94:97], v[134:137], v[214:217], v[94:97]
	v_mfma_f32_16x16x32_bf16 v[90:93], v[142:145], v[214:217], v[90:93]
	v_mfma_f32_16x16x32_bf16 v[78:81], v[134:137], v[222:225], v[78:81]
	v_mfma_f32_16x16x32_bf16 v[74:77], v[142:145], v[222:225], v[74:77]
	v_mfma_f32_16x16x32_bf16 v[118:121], v[146:149], v[174:177], v[118:121]
	v_mfma_f32_16x16x32_bf16 v[114:117], v[166:169], v[174:177], v[114:117]
	v_mfma_f32_16x16x32_bf16 v[102:105], v[146:149], v[188:191], v[102:105]
	v_mfma_f32_16x16x32_bf16 v[98:101], v[166:169], v[188:191], v[98:101]
	v_mfma_f32_16x16x32_bf16 v[86:89], v[146:149], v[210:213], v[86:89]
	v_mfma_f32_16x16x32_bf16 v[82:85], v[166:169], v[210:213], v[82:85]
	v_mfma_f32_16x16x32_bf16 v[70:73], v[146:149], v[218:221], v[70:73]
	v_mfma_f32_16x16x32_bf16 v[66:69], v[166:169], v[218:221], v[66:69]
	v_mfma_f32_16x16x32_bf16 v[118:121], v[150:153], v[178:181], v[118:121]
	v_mfma_f32_16x16x32_bf16 v[114:117], v[170:173], v[178:181], v[114:117]
	v_mfma_f32_16x16x32_bf16 v[102:105], v[150:153], v[206:209], v[102:105]
	v_mfma_f32_16x16x32_bf16 v[98:101], v[170:173], v[206:209], v[98:101]
	v_mfma_f32_16x16x32_bf16 v[86:89], v[150:153], v[214:217], v[86:89]
	v_mfma_f32_16x16x32_bf16 v[82:85], v[170:173], v[214:217], v[82:85]
	v_mfma_f32_16x16x32_bf16 v[70:73], v[150:153], v[222:225], v[70:73]
	v_mfma_f32_16x16x32_bf16 v[66:69], v[170:173], v[222:225], v[66:69]
	s_barrier
	s_add_i32 s39, s39, s12
	v_lshl_add_u64 v[182:183], s[46:47], 0, v[0:1]
	s_mov_b32 m0, s39
	ds_read_b128 v[174:177], v187 offset:16384
	ds_read_b128 v[178:181], v187 offset:17408
	ds_read_b128 v[188:191], v187 offset:18432
	ds_read_b128 v[206:209], v187 offset:19456
	ds_read_b128 v[210:213], v187 offset:20480
	ds_read_b128 v[214:217], v187 offset:21504
	ds_read_b128 v[218:221], v187 offset:22528
	ds_read_b128 v[222:225], v187 offset:23552
	global_load_lds_dwordx4 v[182:183], off
	s_add_i32 m0, s39, 0x2000
	v_lshl_add_u64 v[192:193], s[46:47], 0, v[154:155]
	s_add_u32 s46, s46, s58
	s_addc_u32 s47, s47, s59
	s_add_i32 s26, s26, s12
	global_load_lds_dwordx4 v[192:193], off
	v_lshl_add_u64 v[226:227], s[46:47], 0, v[0:1]
	s_mov_b32 m0, s26
	v_lshl_add_u64 v[228:229], s[46:47], 0, v[154:155]
	global_load_lds_dwordx4 v[226:227], off
	s_add_i32 m0, s26, 0x2000
	v_lshl_add_u64 v[230:231], s[28:29], 0, v[158:159]
	global_load_lds_dwordx4 v[228:229], off
	s_mov_b32 m0, s13
	v_lshl_add_u64 v[232:233], s[28:29], 0, v[156:157]
	global_load_lds_dwordx4 v[230:231], off
	s_mov_b32 m0, s27
	s_nop 0
	global_load_lds_dwordx4 v[232:233], off
	s_waitcnt vmcnt(8)
	s_waitcnt lgkmcnt(0)
	s_barrier
; #define PG8_STAGE(bufoff, gbase, voff) do { _Pragma("unroll") for (int _i = 0; _i < 2; ++_i) \
;         __builtin_amdgcn_global_load_lds((const unsigned*)((const char*)(gbase) + (voff)[_i]), (LAS unsigned*)(lds + (bufoff) + ldsw + _i * 8192), 16, 0, 0); } while (0)
; #define PG8_LDA(dst, b, h) do { _Pragma("unroll") for (int m = 0; m < 4; ++m) _Pragma("unroll") for (int k = 0; k < 2; ++k) dst[m][k] = *(const LAS bf16x8*)(lds + PG8_SA(b, h) + aoff + m * 2048 + k * 1024); } while (0)
; #define PG8_LDB(dst, b, h) do { _Pragma("unroll") for (int n = 0; n < 2; ++n) _Pragma("unroll") for (int k = 0; k < 2; ++k) dst[n][k] = *(const LAS bf16x8*)(lds + PG8_SB(b, h) + boff + n * 2048 + k * 1024); } while (0)
; #define PG8_MMA(ai, bj, At, Bt) do { __builtin_amdgcn_s_setprio(1); _Pragma("unroll") for (int m = 0; m < 4; ++m) _Pragma("unroll") for (int n = 0; n < 2; ++n) _Pragma("unroll") for (int k = 0; k < 2; ++k) \
;         acc[ai][bj][m][n] = __builtin_amdgcn_mfma_f32_16x16x32_bf16(Bt[n][k], At[m][k], acc[ai][bj][m][n], 0, 0, 0); __builtin_amdgcn_s_setprio(0); } while (0)
; #define PG8_WAIT_V(n) asm volatile("s_waitcnt vmcnt(" #n ")" ::: "memory")
; #define PG8_WAIT_L(n) asm volatile("s_waitcnt lgkmcnt(" #n ")" ::: "memory")
; #define PG8_BAR __builtin_amdgcn_s_barrier()
; #define PG8_SCHED __builtin_amdgcn_sched_barrier(0)
; template <class Epi, class Sched>
; __device__ __forceinline__ void gemm_phase(LAS unsigned char* lds, const Gemm g, const Sched& S, const Epi& E) {
;     ...
;             PG8_WAIT_V(8); PG8_WAIT_L(0); PG8_BAR; PG8_MMA(1, 0, At, B0); PG8_MMA(1, 1, At, B1); PG8_BAR; PG8_SCHED;
;             PG8_LDB(B0, 1, 0); PG8_LDB(B1, 1, 1); PG8_SCHED; PG8_LDA(At, 1, 0); PG8_STAGE(PG8_SA(0, 1), a2 + hstep, voffA);
;             PG8_WAIT_V(8); PG8_WAIT_L(0); PG8_BAR; PG8_MMA(0, 0, At, B0); PG8_MMA(0, 1, At, B1); PG8_BAR; PG8_SCHED;
	s_waitcnt lgkmcnt(0)
	v_mfma_f32_16x16x32_bf16 v[62:65], v[130:133], v[174:177], v[62:65]
	v_mfma_f32_16x16x32_bf16 v[58:61], v[138:141], v[174:177], v[58:61]
	v_mfma_f32_16x16x32_bf16 v[46:49], v[130:133], v[188:191], v[46:49]
	v_mfma_f32_16x16x32_bf16 v[42:45], v[138:141], v[188:191], v[42:45]
	v_mfma_f32_16x16x32_bf16 v[30:33], v[130:133], v[210:213], v[30:33]
	v_mfma_f32_16x16x32_bf16 v[26:29], v[138:141], v[210:213], v[26:29]
	v_mfma_f32_16x16x32_bf16 v[14:17], v[130:133], v[218:221], v[14:17]
	v_mfma_f32_16x16x32_bf16 v[10:13], v[138:141], v[218:221], v[10:13]
	v_mfma_f32_16x16x32_bf16 v[62:65], v[134:137], v[178:181], v[62:65]
	v_mfma_f32_16x16x32_bf16 v[58:61], v[142:145], v[178:181], v[58:61]
	v_mfma_f32_16x16x32_bf16 v[46:49], v[134:137], v[206:209], v[46:49]
	v_mfma_f32_16x16x32_bf16 v[42:45], v[142:145], v[206:209], v[42:45]
	v_mfma_f32_16x16x32_bf16 v[30:33], v[134:137], v[214:217], v[30:33]
	v_mfma_f32_16x16x32_bf16 v[26:29], v[142:145], v[214:217], v[26:29]
	v_mfma_f32_16x16x32_bf16 v[14:17], v[134:137], v[222:225], v[14:17]
	v_mfma_f32_16x16x32_bf16 v[10:13], v[142:145], v[222:225], v[10:13]
	v_mfma_f32_16x16x32_bf16 v[54:57], v[146:149], v[174:177], v[54:57]
	v_mfma_f32_16x16x32_bf16 v[50:53], v[166:169], v[174:177], v[50:53]
	v_mfma_f32_16x16x32_bf16 v[38:41], v[146:149], v[188:191], v[38:41]
	v_mfma_f32_16x16x32_bf16 v[34:37], v[166:169], v[188:191], v[34:37]
	v_mfma_f32_16x16x32_bf16 v[22:25], v[146:149], v[210:213], v[22:25]
	v_mfma_f32_16x16x32_bf16 v[18:21], v[166:169], v[210:213], v[18:21]
	v_mfma_f32_16x16x32_bf16 v[6:9], v[146:149], v[218:221], v[6:9]
	v_mfma_f32_16x16x32_bf16 v[2:5], v[166:169], v[218:221], v[2:5]
	v_mfma_f32_16x16x32_bf16 v[54:57], v[150:153], v[178:181], v[54:57]
	v_mfma_f32_16x16x32_bf16 v[50:53], v[170:173], v[178:181], v[50:53]
	v_mfma_f32_16x16x32_bf16 v[38:41], v[150:153], v[206:209], v[38:41]
	v_mfma_f32_16x16x32_bf16 v[34:37], v[170:173], v[206:209], v[34:37]
	v_mfma_f32_16x16x32_bf16 v[22:25], v[150:153], v[214:217], v[22:25]
	v_mfma_f32_16x16x32_bf16 v[18:21], v[170:173], v[214:217], v[18:21]
	v_mfma_f32_16x16x32_bf16 v[6:9], v[150:153], v[222:225], v[6:9]
	v_mfma_f32_16x16x32_bf16 v[2:5], v[170:173], v[222:225], v[2:5]
	s_barrier
	ds_read_b128 v[130:133], v239
	ds_read_b128 v[134:137], v239 offset:1024
	ds_read_b128 v[138:141], v239 offset:2048
	ds_read_b128 v[142:145], v239 offset:3072
	ds_read_b128 v[146:149], v250
	ds_read_b128 v[150:153], v250 offset:1024
	ds_read_b128 v[166:169], v250 offset:2048
	ds_read_b128 v[170:173], v250 offset:3072
	s_add_i32 s26, 0, 0x18000
	s_add_i32 s39, 0, 0x1c000
	s_add_u32 s28, s28, s58
	s_addc_u32 s29, s29, s59
	s_mov_b32 m0, s30
	v_lshl_add_u64 v[244:245], s[28:29], 0, v[158:159]
	ds_read_b128 v[174:177], v187 offset:32768
	ds_read_b128 v[178:181], v187 offset:33792
	ds_read_b128 v[188:191], v187 offset:34816
	ds_read_b128 v[206:209], v187 offset:35840
	ds_read_b128 v[210:213], v187 offset:36864
	ds_read_b128 v[214:217], v187 offset:37888
	ds_read_b128 v[218:221], v187 offset:38912
	ds_read_b128 v[222:225], v187 offset:39936
	global_load_lds_dwordx4 v[244:245], off
	s_mov_b32 m0, s31
	v_lshl_add_u64 v[244:245], s[28:29], 0, v[156:157]
	global_load_lds_dwordx4 v[244:245], off
	s_waitcnt vmcnt(8)
	s_waitcnt lgkmcnt(0)
	s_barrier
	s_waitcnt lgkmcnt(0)
	v_mfma_f32_16x16x32_bf16 v[126:129], v[130:133], v[174:177], v[126:129]
	v_mfma_f32_16x16x32_bf16 v[122:125], v[138:141], v[174:177], v[122:125]
	v_mfma_f32_16x16x32_bf16 v[110:113], v[130:133], v[188:191], v[110:113]
	v_mfma_f32_16x16x32_bf16 v[106:109], v[138:141], v[188:191], v[106:109]
	v_mfma_f32_16x16x32_bf16 v[94:97], v[130:133], v[210:213], v[94:97]
	v_mfma_f32_16x16x32_bf16 v[90:93], v[138:141], v[210:213], v[90:93]
	v_mfma_f32_16x16x32_bf16 v[78:81], v[130:133], v[218:221], v[78:81]
	v_mfma_f32_16x16x32_bf16 v[74:77], v[138:141], v[218:221], v[74:77]
	v_mfma_f32_16x16x32_bf16 v[126:129], v[134:137], v[178:181], v[126:129]
	v_mfma_f32_16x16x32_bf16 v[122:125], v[142:145], v[178:181], v[122:125]
	v_mfma_f32_16x16x32_bf16 v[110:113], v[134:137], v[206:209], v[110:113]
	v_mfma_f32_16x16x32_bf16 v[106:109], v[142:145], v[206:209], v[106:109]
	v_mfma_f32_16x16x32_bf16 v[94:97], v[134:137], v[214:217], v[94:97]
	v_mfma_f32_16x16x32_bf16 v[90:93], v[142:145], v[214:217], v[90:93]
	v_mfma_f32_16x16x32_bf16 v[78:81], v[134:137], v[222:225], v[78:81]
	v_mfma_f32_16x16x32_bf16 v[74:77], v[142:145], v[222:225], v[74:77]
	v_mfma_f32_16x16x32_bf16 v[118:121], v[146:149], v[174:177], v[118:121]
	v_mfma_f32_16x16x32_bf16 v[114:117], v[166:169], v[174:177], v[114:117]
	v_mfma_f32_16x16x32_bf16 v[102:105], v[146:149], v[188:191], v[102:105]
	v_mfma_f32_16x16x32_bf16 v[98:101], v[166:169], v[188:191], v[98:101]
	v_mfma_f32_16x16x32_bf16 v[86:89], v[146:149], v[210:213], v[86:89]
	v_mfma_f32_16x16x32_bf16 v[82:85], v[166:169], v[210:213], v[82:85]
	v_mfma_f32_16x16x32_bf16 v[70:73], v[146:149], v[218:221], v[70:73]
	v_mfma_f32_16x16x32_bf16 v[66:69], v[166:169], v[218:221], v[66:69]
	v_mfma_f32_16x16x32_bf16 v[118:121], v[150:153], v[178:181], v[118:121]
	v_mfma_f32_16x16x32_bf16 v[114:117], v[170:173], v[178:181], v[114:117]
	v_mfma_f32_16x16x32_bf16 v[102:105], v[150:153], v[206:209], v[102:105]
	v_mfma_f32_16x16x32_bf16 v[98:101], v[170:173], v[206:209], v[98:101]
	v_mfma_f32_16x16x32_bf16 v[86:89], v[150:153], v[214:217], v[86:89]
	v_mfma_f32_16x16x32_bf16 v[82:85], v[170:173], v[214:217], v[82:85]
	v_mfma_f32_16x16x32_bf16 v[70:73], v[150:153], v[222:225], v[70:73]
	v_mfma_f32_16x16x32_bf16 v[66:69], v[170:173], v[222:225], v[66:69]
	s_barrier
; #define PG8_STAGE(bufoff, gbase, voff) do { _Pragma("unroll") for (int _i = 0; _i < 2; ++_i) \
;         __builtin_amdgcn_global_load_lds((const unsigned*)((const char*)(gbase) + (voff)[_i]), (LAS unsigned*)(lds + (bufoff) + ldsw + _i * 8192), 16, 0, 0); } while (0)
; #define PG8_LDA(dst, b, h) do { _Pragma("unroll") for (int m = 0; m < 4; ++m) _Pragma("unroll") for (int k = 0; k < 2; ++k) dst[m][k] = *(const LAS bf16x8*)(lds + PG8_SA(b, h) + aoff + m * 2048 + k * 1024); } while (0)
; #define PG8_MMA(ai, bj, At, Bt) do { __builtin_amdgcn_s_setprio(1); _Pragma("unroll") for (int m = 0; m < 4; ++m) _Pragma("unroll") for (int n = 0; n < 2; ++n) _Pragma("unroll") for (int k = 0; k < 2; ++k) \
;         acc[ai][bj][m][n] = __builtin_amdgcn_mfma_f32_16x16x32_bf16(Bt[n][k], At[m][k], acc[ai][bj][m][n], 0, 0, 0); __builtin_amdgcn_s_setprio(0); } while (0)
; #define PG8_WAIT_V(n) asm volatile("s_waitcnt vmcnt(" #n ")" ::: "memory")
; #define PG8_WAIT_L(n) asm volatile("s_waitcnt lgkmcnt(" #n ")" ::: "memory")
; #define PG8_BAR __builtin_amdgcn_s_barrier()
; #define PG8_SCHED __builtin_amdgcn_sched_barrier(0)
; template <class Epi, class Sched>
; __device__ __forceinline__ void gemm_phase(LAS unsigned char* lds, const Gemm g, const Sched& S, const Epi& E) {
;     ...
;             PG8_LDA(At, 1, 1); PG8_STAGE(PG8_SB(1, 0), b3, voffB); PG8_STAGE(PG8_SB(1, 1), b3 + hstep, voffB); PG8_STAGE(PG8_SA(1, 0), a3, voffA);
;             PG8_WAIT_V(8); PG8_WAIT_L(0); PG8_BAR; PG8_MMA(1, 0, At, B0); PG8_MMA(1, 1, At, B1); PG8_BAR; PG8_SCHED;
;         }
	s_add_i32 s26, s26, s12
	v_lshl_add_u64 v[182:183], v[182:183], 0, s[18:19]
	s_mov_b32 m0, s26
	ds_read_b128 v[174:177], v187 offset:49152
	ds_read_b128 v[178:181], v187 offset:50176
	ds_read_b128 v[188:191], v187 offset:51200
	ds_read_b128 v[206:209], v187 offset:52224
	ds_read_b128 v[210:213], v187 offset:53248
	ds_read_b128 v[214:217], v187 offset:54272
	ds_read_b128 v[218:221], v187 offset:55296
	ds_read_b128 v[222:225], v187 offset:56320
	global_load_lds_dwordx4 v[182:183], off
	v_lshl_add_u64 v[182:183], v[192:193], 0, s[18:19]
	s_add_i32 m0, s26, 0x2000
	s_add_i32 s26, s39, s12
	global_load_lds_dwordx4 v[182:183], off
	s_mov_b32 m0, s26
	v_lshl_add_u64 v[182:183], v[226:227], 0, s[18:19]
	global_load_lds_dwordx4 v[182:183], off
	s_add_i32 m0, s26, 0x2000
	v_lshl_add_u64 v[182:183], v[228:229], 0, s[18:19]
	global_load_lds_dwordx4 v[182:183], off
	s_mov_b32 m0, s34
	v_lshl_add_u64 v[182:183], v[230:231], 0, s[18:19]
	global_load_lds_dwordx4 v[182:183], off
	s_mov_b32 m0, s35
	v_lshl_add_u64 v[182:183], v[232:233], 0, s[18:19]
	global_load_lds_dwordx4 v[182:183], off
	s_waitcnt vmcnt(8)
	s_waitcnt lgkmcnt(0)
	s_barrier
	s_waitcnt lgkmcnt(0)
	v_mfma_f32_16x16x32_bf16 v[62:65], v[130:133], v[174:177], v[62:65]
	v_mfma_f32_16x16x32_bf16 v[58:61], v[138:141], v[174:177], v[58:61]
	v_mfma_f32_16x16x32_bf16 v[46:49], v[130:133], v[188:191], v[46:49]
	v_mfma_f32_16x16x32_bf16 v[42:45], v[138:141], v[188:191], v[42:45]
	v_mfma_f32_16x16x32_bf16 v[30:33], v[130:133], v[210:213], v[30:33]
	v_mfma_f32_16x16x32_bf16 v[26:29], v[138:141], v[210:213], v[26:29]
	v_mfma_f32_16x16x32_bf16 v[14:17], v[130:133], v[218:221], v[14:17]
	v_mfma_f32_16x16x32_bf16 v[10:13], v[138:141], v[218:221], v[10:13]
	v_mfma_f32_16x16x32_bf16 v[62:65], v[134:137], v[178:181], v[62:65]
	v_mfma_f32_16x16x32_bf16 v[58:61], v[142:145], v[178:181], v[58:61]
	v_mfma_f32_16x16x32_bf16 v[46:49], v[134:137], v[206:209], v[46:49]
	v_mfma_f32_16x16x32_bf16 v[42:45], v[142:145], v[206:209], v[42:45]
	v_mfma_f32_16x16x32_bf16 v[30:33], v[134:137], v[214:217], v[30:33]
	v_mfma_f32_16x16x32_bf16 v[26:29], v[142:145], v[214:217], v[26:29]
	v_mfma_f32_16x16x32_bf16 v[14:17], v[134:137], v[222:225], v[14:17]
	v_mfma_f32_16x16x32_bf16 v[10:13], v[142:145], v[222:225], v[10:13]
	v_mfma_f32_16x16x32_bf16 v[54:57], v[146:149], v[174:177], v[54:57]
	v_mfma_f32_16x16x32_bf16 v[50:53], v[166:169], v[174:177], v[50:53]
	v_mfma_f32_16x16x32_bf16 v[38:41], v[146:149], v[188:191], v[38:41]
	v_mfma_f32_16x16x32_bf16 v[34:37], v[166:169], v[188:191], v[34:37]
	v_mfma_f32_16x16x32_bf16 v[22:25], v[146:149], v[210:213], v[22:25]
	v_mfma_f32_16x16x32_bf16 v[18:21], v[166:169], v[210:213], v[18:21]
	v_mfma_f32_16x16x32_bf16 v[6:9], v[146:149], v[218:221], v[6:9]
	v_mfma_f32_16x16x32_bf16 v[2:5], v[166:169], v[218:221], v[2:5]
	v_mfma_f32_16x16x32_bf16 v[54:57], v[150:153], v[178:181], v[54:57]
	v_mfma_f32_16x16x32_bf16 v[50:53], v[170:173], v[178:181], v[50:53]
	v_mfma_f32_16x16x32_bf16 v[38:41], v[150:153], v[206:209], v[38:41]
	v_mfma_f32_16x16x32_bf16 v[34:37], v[170:173], v[206:209], v[34:37]
	v_mfma_f32_16x16x32_bf16 v[22:25], v[150:153], v[214:217], v[22:25]
	v_mfma_f32_16x16x32_bf16 v[18:21], v[170:173], v[214:217], v[18:21]
	v_mfma_f32_16x16x32_bf16 v[6:9], v[150:153], v[222:225], v[6:9]
	v_mfma_f32_16x16x32_bf16 v[2:5], v[170:173], v[222:225], v[2:5]
	s_barrier
	s_add_u32 s15, s15, 0x100
	s_addc_u32 s16, s16, 0
	s_add_u32 s0, s0, 0x100
	s_addc_u32 s1, s1, 0
	s_cmp_ge_i32 s38, s80
	s_mov_b32 s28, s38
	s_cbranch_scc0 .LBB0_1440

; #define PG8_STAGE(bufoff, gbase, voff) do { _Pragma("unroll") for (int _i = 0; _i < 2; ++_i) \
;         __builtin_amdgcn_global_load_lds((const unsigned*)((const char*)(gbase) + (voff)[_i]), (LAS unsigned*)(lds + (bufoff) + ldsw + _i * 8192), 16, 0, 0); } while (0)
; #define PG8_LDA(dst, b, h) do { _Pragma("unroll") for (int m = 0; m < 4; ++m) _Pragma("unroll") for (int k = 0; k < 2; ++k) dst[m][k] = *(const LAS bf16x8*)(lds + PG8_SA(b, h) + aoff + m * 2048 + k * 1024); } while (0)
; #define PG8_LDB(dst, b, h) do { _Pragma("unroll") for (int n = 0; n < 2; ++n) _Pragma("unroll") for (int k = 0; k < 2; ++k) dst[n][k] = *(const LAS bf16x8*)(lds + PG8_SB(b, h) + boff + n * 2048 + k * 1024); } while (0)
; #define PG8_MMA(ai, bj, At, Bt) do { __builtin_amdgcn_s_setprio(1); _Pragma("unroll") for (int m = 0; m < 4; ++m) _Pragma("unroll") for (int n = 0; n < 2; ++n) _Pragma("unroll") for (int k = 0; k < 2; ++k) \
;         acc[ai][bj][m][n] = __builtin_amdgcn_mfma_f32_16x16x32_bf16(Bt[n][k], At[m][k], acc[ai][bj][m][n], 0, 0, 0); __builtin_amdgcn_s_setprio(0); } while (0)
; #define PG8_WAIT_V(n) asm volatile("s_waitcnt vmcnt(" #n ")" ::: "memory")
; #define PG8_WAIT_L(n) asm volatile("s_waitcnt lgkmcnt(" #n ")" ::: "memory")
; #define PG8_BAR __builtin_amdgcn_s_barrier()
; #define PG8_SCHED __builtin_amdgcn_sched_barrier(0)
; template <class Epi, class Sched>
; __device__ __forceinline__ void gemm_phase(LAS unsigned char* lds, const Gemm g, const Sched& S, const Epi& E) {
;     ...
;         for (int t = 0; t < nt; t += 2) {
;             const bool last = (t == nt - 2);
;             const char* a1 = cA + (size_t)(t + 1) * kstep;
;             const char* a2 = last ? nA : cA + (size_t)(t + 2) * kstep; const char* b2 = last ? nB : cB + (size_t)(t + 2) * kstep;
;             const char* a3 = a2 + kstep; const char* b3 = b2 + kstep;
;             PG8_LDB(B0, 0, 0); PG8_LDB(B1, 0, 1); PG8_SCHED; PG8_LDA(At, 0, 0); PG8_STAGE(PG8_SA(1, 1), a1 + hstep, voffA);
;             PG8_WAIT_V(8); PG8_WAIT_L(0); PG8_BAR; PG8_MMA(0, 0, At, B0); PG8_MMA(0, 1, At, B1); PG8_BAR; PG8_SCHED;
;             PG8_LDA(At, 0, 1); PG8_STAGE(PG8_SB(0, 0), b2, voffB); PG8_STAGE(PG8_SB(0, 1), b2 + hstep, voffB); PG8_STAGE(PG8_SA(0, 0), a2, voffA);
.LBB0_1556:
	s_add_i32 s38, s28, 2
	s_add_u32 s26, s0, 0x80
	s_addc_u32 s29, s1, 0
	s_add_i32 s39, 0, 0x10000
	s_cmp_eq_u32 s84, s28
	s_cselect_b32 s29, s65, s29
	s_cselect_b32 s28, s64, s26
	v_add_u32_e32 v0, s39, v244
	s_cselect_b32 s47, s67, s16
	s_cselect_b32 s46, s66, s15
	s_add_i32 s26, 0, 0x14000
	ds_read_b128 v[130:133], v0
	ds_read_b128 v[134:137], v0 offset:1024
	ds_read_b128 v[138:141], v0 offset:2048
	ds_read_b128 v[142:145], v0 offset:3072
	v_add_u32_e32 v0, s26, v244
	ds_read_b128 v[146:149], v0
	ds_read_b128 v[150:153], v0 offset:1024
	ds_read_b128 v[154:157], v0 offset:2048
	ds_read_b128 v[158:161], v0 offset:3072
	v_lshl_add_u64 v[218:219], s[0:1], 0, v[216:217]
	s_add_i32 m0, s13, 0xc000
	ds_read_b128 v[162:165], v246
	ds_read_b128 v[166:169], v246 offset:1024
	ds_read_b128 v[170:173], v246 offset:2048
	ds_read_b128 v[174:177], v246 offset:3072
	ds_read_b128 v[178:181], v246 offset:4096
	ds_read_b128 v[182:185], v246 offset:5120
	ds_read_b128 v[186:189], v246 offset:6144
	ds_read_b128 v[190:193], v246 offset:7168
	global_load_lds_dwordx4 v[218:219], off
	s_add_i32 m0, s13, 0xe000
	v_lshl_add_u64 v[218:219], s[0:1], 0, v[214:215]
	global_load_lds_dwordx4 v[218:219], off
	s_waitcnt vmcnt(8)
	s_waitcnt lgkmcnt(0)
	s_barrier
	s_waitcnt lgkmcnt(0)
	v_mfma_f32_16x16x32_bf16 v[126:129], v[130:133], v[162:165], v[126:129]
	v_mfma_f32_16x16x32_bf16 v[122:125], v[138:141], v[162:165], v[122:125]
	v_mfma_f32_16x16x32_bf16 v[110:113], v[130:133], v[170:173], v[110:113]
	v_mfma_f32_16x16x32_bf16 v[106:109], v[138:141], v[170:173], v[106:109]
	v_mfma_f32_16x16x32_bf16 v[102:105], v[130:133], v[178:181], v[102:105]
	v_mfma_f32_16x16x32_bf16 v[98:101], v[138:141], v[178:181], v[98:101]
	v_mfma_f32_16x16x32_bf16 v[94:97], v[130:133], v[186:189], v[94:97]
	v_mfma_f32_16x16x32_bf16 v[90:93], v[138:141], v[186:189], v[90:93]
	v_mfma_f32_16x16x32_bf16 v[126:129], v[134:137], v[166:169], v[126:129]
	v_mfma_f32_16x16x32_bf16 v[122:125], v[142:145], v[166:169], v[122:125]
	v_mfma_f32_16x16x32_bf16 v[110:113], v[134:137], v[174:177], v[110:113]
	v_mfma_f32_16x16x32_bf16 v[106:109], v[142:145], v[174:177], v[106:109]
	v_mfma_f32_16x16x32_bf16 v[102:105], v[134:137], v[182:185], v[102:105]
	v_mfma_f32_16x16x32_bf16 v[98:101], v[142:145], v[182:185], v[98:101]
	v_mfma_f32_16x16x32_bf16 v[94:97], v[134:137], v[190:193], v[94:97]
	v_mfma_f32_16x16x32_bf16 v[90:93], v[142:145], v[190:193], v[90:93]
	v_mfma_f32_16x16x32_bf16 v[118:121], v[146:149], v[162:165], v[118:121]
	v_mfma_f32_16x16x32_bf16 v[114:117], v[154:157], v[162:165], v[114:117]
	v_mfma_f32_16x16x32_bf16 v[86:89], v[146:149], v[170:173], v[86:89]
	v_mfma_f32_16x16x32_bf16 v[82:85], v[154:157], v[170:173], v[82:85]
	v_mfma_f32_16x16x32_bf16 v[78:81], v[146:149], v[178:181], v[78:81]
	v_mfma_f32_16x16x32_bf16 v[74:77], v[154:157], v[178:181], v[74:77]
	v_mfma_f32_16x16x32_bf16 v[70:73], v[146:149], v[186:189], v[70:73]
	v_mfma_f32_16x16x32_bf16 v[66:69], v[154:157], v[186:189], v[66:69]
	v_mfma_f32_16x16x32_bf16 v[118:121], v[150:153], v[166:169], v[118:121]
	v_mfma_f32_16x16x32_bf16 v[114:117], v[158:161], v[166:169], v[114:117]
	v_mfma_f32_16x16x32_bf16 v[86:89], v[150:153], v[174:177], v[86:89]
	v_mfma_f32_16x16x32_bf16 v[82:85], v[158:161], v[174:177], v[82:85]
	v_mfma_f32_16x16x32_bf16 v[78:81], v[150:153], v[182:185], v[78:81]
	v_mfma_f32_16x16x32_bf16 v[74:77], v[158:161], v[182:185], v[74:77]
	v_mfma_f32_16x16x32_bf16 v[70:73], v[150:153], v[190:193], v[70:73]
	v_mfma_f32_16x16x32_bf16 v[66:69], v[158:161], v[190:193], v[66:69]
	s_barrier
	s_add_i32 s39, s39, s12
	v_lshl_add_u64 v[218:219], s[46:47], 0, v[210:211]
	s_mov_b32 m0, s39
	ds_read_b128 v[162:165], v246 offset:16384
	ds_read_b128 v[166:169], v246 offset:17408
	ds_read_b128 v[170:173], v246 offset:18432
	ds_read_b128 v[174:177], v246 offset:19456
	ds_read_b128 v[178:181], v246 offset:20480
	ds_read_b128 v[182:185], v246 offset:21504
	ds_read_b128 v[186:189], v246 offset:22528
	ds_read_b128 v[190:193], v246 offset:23552
	global_load_lds_dwordx4 v[218:219], off
	s_add_i32 m0, s39, 0x2000
	v_lshl_add_u64 v[220:221], s[46:47], 0, v[206:207]
	s_add_u32 s46, s46, s48
	s_addc_u32 s47, s47, s49
	s_add_i32 s26, s26, s12
	global_load_lds_dwordx4 v[220:221], off
	v_lshl_add_u64 v[222:223], s[46:47], 0, v[210:211]
	s_mov_b32 m0, s26
	v_lshl_add_u64 v[224:225], s[46:47], 0, v[206:207]
	global_load_lds_dwordx4 v[222:223], off
	s_add_i32 m0, s26, 0x2000
	v_lshl_add_u64 v[226:227], s[28:29], 0, v[212:213]
	global_load_lds_dwordx4 v[224:225], off
	s_mov_b32 m0, s13
	v_lshl_add_u64 v[228:229], s[28:29], 0, v[208:209]
	global_load_lds_dwordx4 v[226:227], off
	s_mov_b32 m0, s27
	s_nop 0
	global_load_lds_dwordx4 v[228:229], off
	s_waitcnt vmcnt(8)
	s_waitcnt lgkmcnt(0)
	s_barrier
; #define PG8_STAGE(bufoff, gbase, voff) do { _Pragma("unroll") for (int _i = 0; _i < 2; ++_i) \
;         __builtin_amdgcn_global_load_lds((const unsigned*)((const char*)(gbase) + (voff)[_i]), (LAS unsigned*)(lds + (bufoff) + ldsw + _i * 8192), 16, 0, 0); } while (0)
; #define PG8_LDA(dst, b, h) do { _Pragma("unroll") for (int m = 0; m < 4; ++m) _Pragma("unroll") for (int k = 0; k < 2; ++k) dst[m][k] = *(const LAS bf16x8*)(lds + PG8_SA(b, h) + aoff + m * 2048 + k * 1024); } while (0)
; #define PG8_LDB(dst, b, h) do { _Pragma("unroll") for (int n = 0; n < 2; ++n) _Pragma("unroll") for (int k = 0; k < 2; ++k) dst[n][k] = *(const LAS bf16x8*)(lds + PG8_SB(b, h) + boff + n * 2048 + k * 1024); } while (0)
; #define PG8_MMA(ai, bj, At, Bt) do { __builtin_amdgcn_s_setprio(1); _Pragma("unroll") for (int m = 0; m < 4; ++m) _Pragma("unroll") for (int n = 0; n < 2; ++n) _Pragma("unroll") for (int k = 0; k < 2; ++k) \
;         acc[ai][bj][m][n] = __builtin_amdgcn_mfma_f32_16x16x32_bf16(Bt[n][k], At[m][k], acc[ai][bj][m][n], 0, 0, 0); __builtin_amdgcn_s_setprio(0); } while (0)
; #define PG8_WAIT_V(n) asm volatile("s_waitcnt vmcnt(" #n ")" ::: "memory")
; #define PG8_WAIT_L(n) asm volatile("s_waitcnt lgkmcnt(" #n ")" ::: "memory")
; #define PG8_BAR __builtin_amdgcn_s_barrier()
; #define PG8_SCHED __builtin_amdgcn_sched_barrier(0)
; template <class Epi, class Sched>
; __device__ __forceinline__ void gemm_phase(LAS unsigned char* lds, const Gemm g, const Sched& S, const Epi& E) {
;     ...
;             PG8_WAIT_V(8); PG8_WAIT_L(0); PG8_BAR; PG8_MMA(1, 0, At, B0); PG8_MMA(1, 1, At, B1); PG8_BAR; PG8_SCHED;
;             PG8_LDB(B0, 1, 0); PG8_LDB(B1, 1, 1); PG8_SCHED; PG8_LDA(At, 1, 0); PG8_STAGE(PG8_SA(0, 1), a2 + hstep, voffA);
;             PG8_WAIT_V(8); PG8_WAIT_L(0); PG8_BAR; PG8_MMA(0, 0, At, B0); PG8_MMA(0, 1, At, B1); PG8_BAR; PG8_SCHED;
	s_waitcnt lgkmcnt(0)
	v_mfma_f32_16x16x32_bf16 v[62:65], v[130:133], v[162:165], v[62:65]
	v_mfma_f32_16x16x32_bf16 v[58:61], v[138:141], v[162:165], v[58:61]
	v_mfma_f32_16x16x32_bf16 v[46:49], v[130:133], v[170:173], v[46:49]
	v_mfma_f32_16x16x32_bf16 v[42:45], v[138:141], v[170:173], v[42:45]
	v_mfma_f32_16x16x32_bf16 v[30:33], v[130:133], v[178:181], v[30:33]
	v_mfma_f32_16x16x32_bf16 v[26:29], v[138:141], v[178:181], v[26:29]
	v_mfma_f32_16x16x32_bf16 v[14:17], v[130:133], v[186:189], v[14:17]
	v_mfma_f32_16x16x32_bf16 v[10:13], v[138:141], v[186:189], v[10:13]
	v_mfma_f32_16x16x32_bf16 v[62:65], v[134:137], v[166:169], v[62:65]
	v_mfma_f32_16x16x32_bf16 v[58:61], v[142:145], v[166:169], v[58:61]
	v_mfma_f32_16x16x32_bf16 v[46:49], v[134:137], v[174:177], v[46:49]
	v_mfma_f32_16x16x32_bf16 v[42:45], v[142:145], v[174:177], v[42:45]
	v_mfma_f32_16x16x32_bf16 v[30:33], v[134:137], v[182:185], v[30:33]
	v_mfma_f32_16x16x32_bf16 v[26:29], v[142:145], v[182:185], v[26:29]
	v_mfma_f32_16x16x32_bf16 v[14:17], v[134:137], v[190:193], v[14:17]
	v_mfma_f32_16x16x32_bf16 v[10:13], v[142:145], v[190:193], v[10:13]
	v_mfma_f32_16x16x32_bf16 v[54:57], v[146:149], v[162:165], v[54:57]
	v_mfma_f32_16x16x32_bf16 v[50:53], v[154:157], v[162:165], v[50:53]
	v_mfma_f32_16x16x32_bf16 v[38:41], v[146:149], v[170:173], v[38:41]
	v_mfma_f32_16x16x32_bf16 v[34:37], v[154:157], v[170:173], v[34:37]
	v_mfma_f32_16x16x32_bf16 v[22:25], v[146:149], v[178:181], v[22:25]
	v_mfma_f32_16x16x32_bf16 v[18:21], v[154:157], v[178:181], v[18:21]
	v_mfma_f32_16x16x32_bf16 v[6:9], v[146:149], v[186:189], v[6:9]
	v_mfma_f32_16x16x32_bf16 v[2:5], v[154:157], v[186:189], v[2:5]
	v_mfma_f32_16x16x32_bf16 v[54:57], v[150:153], v[166:169], v[54:57]
	v_mfma_f32_16x16x32_bf16 v[50:53], v[158:161], v[166:169], v[50:53]
	v_mfma_f32_16x16x32_bf16 v[38:41], v[150:153], v[174:177], v[38:41]
	v_mfma_f32_16x16x32_bf16 v[34:37], v[158:161], v[174:177], v[34:37]
	v_mfma_f32_16x16x32_bf16 v[22:25], v[150:153], v[182:185], v[22:25]
	v_mfma_f32_16x16x32_bf16 v[18:21], v[158:161], v[182:185], v[18:21]
	v_mfma_f32_16x16x32_bf16 v[6:9], v[150:153], v[190:193], v[6:9]
	v_mfma_f32_16x16x32_bf16 v[2:5], v[158:161], v[190:193], v[2:5]
	s_barrier
	s_add_i32 s26, 0, 0x18000
	v_add_u32_e32 v0, s26, v244
	s_add_i32 s39, 0, 0x1c000
	ds_read_b128 v[130:133], v0
	ds_read_b128 v[134:137], v0 offset:1024
	ds_read_b128 v[138:141], v0 offset:2048
	ds_read_b128 v[142:145], v0 offset:3072
	v_add_u32_e32 v0, s39, v244
	ds_read_b128 v[146:149], v0
	ds_read_b128 v[150:153], v0 offset:1024
	ds_read_b128 v[154:157], v0 offset:2048
	ds_read_b128 v[158:161], v0 offset:3072
	s_add_u32 s28, s28, s48
	s_addc_u32 s29, s29, s49
	s_mov_b32 m0, s34
	v_lshl_add_u64 v[230:231], s[28:29], 0, v[212:213]
	ds_read_b128 v[162:165], v246 offset:32768
	ds_read_b128 v[166:169], v246 offset:33792
	ds_read_b128 v[170:173], v246 offset:34816
	ds_read_b128 v[174:177], v246 offset:35840
	ds_read_b128 v[178:181], v246 offset:36864
	ds_read_b128 v[182:185], v246 offset:37888
	ds_read_b128 v[186:189], v246 offset:38912
	ds_read_b128 v[190:193], v246 offset:39936
	global_load_lds_dwordx4 v[230:231], off
	s_mov_b32 m0, s35
	v_lshl_add_u64 v[230:231], s[28:29], 0, v[208:209]
	global_load_lds_dwordx4 v[230:231], off
	s_waitcnt vmcnt(8)
	s_waitcnt lgkmcnt(0)
	s_barrier
	s_waitcnt lgkmcnt(0)
	v_mfma_f32_16x16x32_bf16 v[126:129], v[130:133], v[162:165], v[126:129]
	v_mfma_f32_16x16x32_bf16 v[122:125], v[138:141], v[162:165], v[122:125]
	v_mfma_f32_16x16x32_bf16 v[110:113], v[130:133], v[170:173], v[110:113]
	v_mfma_f32_16x16x32_bf16 v[106:109], v[138:141], v[170:173], v[106:109]
	v_mfma_f32_16x16x32_bf16 v[102:105], v[130:133], v[178:181], v[102:105]
	v_mfma_f32_16x16x32_bf16 v[98:101], v[138:141], v[178:181], v[98:101]
	v_mfma_f32_16x16x32_bf16 v[94:97], v[130:133], v[186:189], v[94:97]
	v_mfma_f32_16x16x32_bf16 v[90:93], v[138:141], v[186:189], v[90:93]
	v_mfma_f32_16x16x32_bf16 v[126:129], v[134:137], v[166:169], v[126:129]
	v_mfma_f32_16x16x32_bf16 v[122:125], v[142:145], v[166:169], v[122:125]
	v_mfma_f32_16x16x32_bf16 v[110:113], v[134:137], v[174:177], v[110:113]
	v_mfma_f32_16x16x32_bf16 v[106:109], v[142:145], v[174:177], v[106:109]
	v_mfma_f32_16x16x32_bf16 v[102:105], v[134:137], v[182:185], v[102:105]
	v_mfma_f32_16x16x32_bf16 v[98:101], v[142:145], v[182:185], v[98:101]
	v_mfma_f32_16x16x32_bf16 v[94:97], v[134:137], v[190:193], v[94:97]
	v_mfma_f32_16x16x32_bf16 v[90:93], v[142:145], v[190:193], v[90:93]
	v_mfma_f32_16x16x32_bf16 v[118:121], v[146:149], v[162:165], v[118:121]
	v_mfma_f32_16x16x32_bf16 v[114:117], v[154:157], v[162:165], v[114:117]
	v_mfma_f32_16x16x32_bf16 v[86:89], v[146:149], v[170:173], v[86:89]
	v_mfma_f32_16x16x32_bf16 v[82:85], v[154:157], v[170:173], v[82:85]
	v_mfma_f32_16x16x32_bf16 v[78:81], v[146:149], v[178:181], v[78:81]
	v_mfma_f32_16x16x32_bf16 v[74:77], v[154:157], v[178:181], v[74:77]
	v_mfma_f32_16x16x32_bf16 v[70:73], v[146:149], v[186:189], v[70:73]
	v_mfma_f32_16x16x32_bf16 v[66:69], v[154:157], v[186:189], v[66:69]
	v_mfma_f32_16x16x32_bf16 v[118:121], v[150:153], v[166:169], v[118:121]
	v_mfma_f32_16x16x32_bf16 v[114:117], v[158:161], v[166:169], v[114:117]
	v_mfma_f32_16x16x32_bf16 v[86:89], v[150:153], v[174:177], v[86:89]
	v_mfma_f32_16x16x32_bf16 v[82:85], v[158:161], v[174:177], v[82:85]
	v_mfma_f32_16x16x32_bf16 v[78:81], v[150:153], v[182:185], v[78:81]
	v_mfma_f32_16x16x32_bf16 v[74:77], v[158:161], v[182:185], v[74:77]
	v_mfma_f32_16x16x32_bf16 v[70:73], v[150:153], v[190:193], v[70:73]
	v_mfma_f32_16x16x32_bf16 v[66:69], v[158:161], v[190:193], v[66:69]
	s_barrier
; #define PG8_STAGE(bufoff, gbase, voff) do { _Pragma("unroll") for (int _i = 0; _i < 2; ++_i) \
;         __builtin_amdgcn_global_load_lds((const unsigned*)((const char*)(gbase) + (voff)[_i]), (LAS unsigned*)(lds + (bufoff) + ldsw + _i * 8192), 16, 0, 0); } while (0)
; #define PG8_LDA(dst, b, h) do { _Pragma("unroll") for (int m = 0; m < 4; ++m) _Pragma("unroll") for (int k = 0; k < 2; ++k) dst[m][k] = *(const LAS bf16x8*)(lds + PG8_SA(b, h) + aoff + m * 2048 + k * 1024); } while (0)
; #define PG8_MMA(ai, bj, At, Bt) do { __builtin_amdgcn_s_setprio(1); _Pragma("unroll") for (int m = 0; m < 4; ++m) _Pragma("unroll") for (int n = 0; n < 2; ++n) _Pragma("unroll") for (int k = 0; k < 2; ++k) \
;         acc[ai][bj][m][n] = __builtin_amdgcn_mfma_f32_16x16x32_bf16(Bt[n][k], At[m][k], acc[ai][bj][m][n], 0, 0, 0); __builtin_amdgcn_s_setprio(0); } while (0)
; #define PG8_WAIT_V(n) asm volatile("s_waitcnt vmcnt(" #n ")" ::: "memory")
; #define PG8_WAIT_L(n) asm volatile("s_waitcnt lgkmcnt(" #n ")" ::: "memory")
; #define PG8_BAR __builtin_amdgcn_s_barrier()
; #define PG8_SCHED __builtin_amdgcn_sched_barrier(0)
; template <class Epi, class Sched>
; __device__ __forceinline__ void gemm_phase(LAS unsigned char* lds, const Gemm g, const Sched& S, const Epi& E) {
;     ...
;             PG8_LDA(At, 1, 1); PG8_STAGE(PG8_SB(1, 0), b3, voffB); PG8_STAGE(PG8_SB(1, 1), b3 + hstep, voffB); PG8_STAGE(PG8_SA(1, 0), a3, voffA);
;             PG8_WAIT_V(8); PG8_WAIT_L(0); PG8_BAR; PG8_MMA(1, 0, At, B0); PG8_MMA(1, 1, At, B1); PG8_BAR; PG8_SCHED;
;         }
	s_add_i32 s26, s26, s12
	v_lshl_add_u64 v[218:219], v[218:219], 0, s[18:19]
	s_mov_b32 m0, s26
	ds_read_b128 v[162:165], v246 offset:49152
	ds_read_b128 v[166:169], v246 offset:50176
	ds_read_b128 v[170:173], v246 offset:51200
	ds_read_b128 v[174:177], v246 offset:52224
	ds_read_b128 v[178:181], v246 offset:53248
	ds_read_b128 v[182:185], v246 offset:54272
	ds_read_b128 v[186:189], v246 offset:55296
	ds_read_b128 v[190:193], v246 offset:56320
	global_load_lds_dwordx4 v[218:219], off
	v_lshl_add_u64 v[218:219], v[220:221], 0, s[18:19]
	s_add_i32 m0, s26, 0x2000
	s_add_i32 s26, s39, s12
	global_load_lds_dwordx4 v[218:219], off
	s_mov_b32 m0, s26
	v_lshl_add_u64 v[218:219], v[222:223], 0, s[18:19]
	global_load_lds_dwordx4 v[218:219], off
	s_add_i32 m0, s26, 0x2000
	v_lshl_add_u64 v[218:219], v[224:225], 0, s[18:19]
	global_load_lds_dwordx4 v[218:219], off
	s_mov_b32 m0, s31
	v_lshl_add_u64 v[218:219], v[226:227], 0, s[18:19]
	global_load_lds_dwordx4 v[218:219], off
	s_mov_b32 m0, s80
	v_lshl_add_u64 v[218:219], v[228:229], 0, s[18:19]
	global_load_lds_dwordx4 v[218:219], off
	s_waitcnt vmcnt(8)
	s_waitcnt lgkmcnt(0)
	s_barrier
	s_waitcnt lgkmcnt(0)
	v_mfma_f32_16x16x32_bf16 v[62:65], v[130:133], v[162:165], v[62:65]
	v_mfma_f32_16x16x32_bf16 v[58:61], v[138:141], v[162:165], v[58:61]
	v_mfma_f32_16x16x32_bf16 v[46:49], v[130:133], v[170:173], v[46:49]
	v_mfma_f32_16x16x32_bf16 v[42:45], v[138:141], v[170:173], v[42:45]
	v_mfma_f32_16x16x32_bf16 v[30:33], v[130:133], v[178:181], v[30:33]
	v_mfma_f32_16x16x32_bf16 v[26:29], v[138:141], v[178:181], v[26:29]
	v_mfma_f32_16x16x32_bf16 v[14:17], v[130:133], v[186:189], v[14:17]
	v_mfma_f32_16x16x32_bf16 v[10:13], v[138:141], v[186:189], v[10:13]
	v_mfma_f32_16x16x32_bf16 v[62:65], v[134:137], v[166:169], v[62:65]
	v_mfma_f32_16x16x32_bf16 v[58:61], v[142:145], v[166:169], v[58:61]
	v_mfma_f32_16x16x32_bf16 v[46:49], v[134:137], v[174:177], v[46:49]
	v_mfma_f32_16x16x32_bf16 v[42:45], v[142:145], v[174:177], v[42:45]
	v_mfma_f32_16x16x32_bf16 v[30:33], v[134:137], v[182:185], v[30:33]
	v_mfma_f32_16x16x32_bf16 v[26:29], v[142:145], v[182:185], v[26:29]
	v_mfma_f32_16x16x32_bf16 v[14:17], v[134:137], v[190:193], v[14:17]
	v_mfma_f32_16x16x32_bf16 v[10:13], v[142:145], v[190:193], v[10:13]
	v_mfma_f32_16x16x32_bf16 v[54:57], v[146:149], v[162:165], v[54:57]
	v_mfma_f32_16x16x32_bf16 v[50:53], v[154:157], v[162:165], v[50:53]
	v_mfma_f32_16x16x32_bf16 v[38:41], v[146:149], v[170:173], v[38:41]
	v_mfma_f32_16x16x32_bf16 v[34:37], v[154:157], v[170:173], v[34:37]
	v_mfma_f32_16x16x32_bf16 v[22:25], v[146:149], v[178:181], v[22:25]
	v_mfma_f32_16x16x32_bf16 v[18:21], v[154:157], v[178:181], v[18:21]
	v_mfma_f32_16x16x32_bf16 v[6:9], v[146:149], v[186:189], v[6:9]
	v_mfma_f32_16x16x32_bf16 v[2:5], v[154:157], v[186:189], v[2:5]
	v_mfma_f32_16x16x32_bf16 v[54:57], v[150:153], v[166:169], v[54:57]
	v_mfma_f32_16x16x32_bf16 v[50:53], v[158:161], v[166:169], v[50:53]
	v_mfma_f32_16x16x32_bf16 v[38:41], v[150:153], v[174:177], v[38:41]
	v_mfma_f32_16x16x32_bf16 v[34:37], v[158:161], v[174:177], v[34:37]
	v_mfma_f32_16x16x32_bf16 v[22:25], v[150:153], v[182:185], v[22:25]
	v_mfma_f32_16x16x32_bf16 v[18:21], v[158:161], v[182:185], v[18:21]
	v_mfma_f32_16x16x32_bf16 v[6:9], v[150:153], v[190:193], v[6:9]
	v_mfma_f32_16x16x32_bf16 v[2:5], v[158:161], v[190:193], v[2:5]
	s_barrier
	s_add_u32 s15, s15, 0x100
	s_addc_u32 s16, s16, 0
	s_add_u32 s0, s0, 0x100
	s_addc_u32 s1, s1, 0
	s_cmp_ge_i32 s38, s30
	s_mov_b32 s28, s38
	s_cbranch_scc0 .LBB0_1556

; #define PG8_STAGE(bufoff, gbase, voff) do { _Pragma("unroll") for (int _i = 0; _i < 2; ++_i) \
;         __builtin_amdgcn_global_load_lds((const unsigned*)((const char*)(gbase) + (voff)[_i]), (LAS unsigned*)(lds + (bufoff) + ldsw + _i * 8192), 16, 0, 0); } while (0)
; #define PG8_LDA(dst, b, h) do { _Pragma("unroll") for (int m = 0; m < 4; ++m) _Pragma("unroll") for (int k = 0; k < 2; ++k) dst[m][k] = *(const LAS bf16x8*)(lds + PG8_SA(b, h) + aoff + m * 2048 + k * 1024); } while (0)
; #define PG8_LDB(dst, b, h) do { _Pragma("unroll") for (int n = 0; n < 2; ++n) _Pragma("unroll") for (int k = 0; k < 2; ++k) dst[n][k] = *(const LAS bf16x8*)(lds + PG8_SB(b, h) + boff + n * 2048 + k * 1024); } while (0)
; #define PG8_MMA(ai, bj, At, Bt) do { __builtin_amdgcn_s_setprio(1); _Pragma("unroll") for (int m = 0; m < 4; ++m) _Pragma("unroll") for (int n = 0; n < 2; ++n) _Pragma("unroll") for (int k = 0; k < 2; ++k) \
;         acc[ai][bj][m][n] = __builtin_amdgcn_mfma_f32_16x16x32_bf16(Bt[n][k], At[m][k], acc[ai][bj][m][n], 0, 0, 0); __builtin_amdgcn_s_setprio(0); } while (0)
; #define PG8_WAIT_V(n) asm volatile("s_waitcnt vmcnt(" #n ")" ::: "memory")
; #define PG8_WAIT_L(n) asm volatile("s_waitcnt lgkmcnt(" #n ")" ::: "memory")
; #define PG8_BAR __builtin_amdgcn_s_barrier()
; #define PG8_SCHED __builtin_amdgcn_sched_barrier(0)
; template <class Epi, class Sched>
; __device__ __forceinline__ void gemm_phase(LAS unsigned char* lds, const Gemm g, const Sched& S, const Epi& E) {
;     ...
;         for (int t = 0; t < nt; t += 2) {
;             const bool last = (t == nt - 2);
;             const char* a1 = cA + (size_t)(t + 1) * kstep;
;             const char* a2 = last ? nA : cA + (size_t)(t + 2) * kstep; const char* b2 = last ? nB : cB + (size_t)(t + 2) * kstep;
;             const char* a3 = a2 + kstep; const char* b3 = b2 + kstep;
;             PG8_LDB(B0, 0, 0); PG8_LDB(B1, 0, 1); PG8_SCHED; PG8_LDA(At, 0, 0); PG8_STAGE(PG8_SA(1, 1), a1 + hstep, voffA);
;             PG8_WAIT_V(8); PG8_WAIT_L(0); PG8_BAR; PG8_MMA(0, 0, At, B0); PG8_MMA(0, 1, At, B1); PG8_BAR; PG8_SCHED;
;             PG8_LDA(At, 0, 1); PG8_STAGE(PG8_SB(0, 0), b2, voffB); PG8_STAGE(PG8_SB(0, 1), b2 + hstep, voffB); PG8_STAGE(PG8_SA(0, 0), a2, voffA);
.LBB0_1776:
	ds_read_b128 v[130:133], v235
	ds_read_b128 v[134:137], v235 offset:1024
	ds_read_b128 v[138:141], v235 offset:2048
	ds_read_b128 v[142:145], v235 offset:3072
	ds_read_b128 v[146:149], v238
	ds_read_b128 v[150:153], v238 offset:1024
	ds_read_b128 v[154:157], v238 offset:2048
	ds_read_b128 v[158:161], v238 offset:3072
	ds_read_b128 v[162:165], v219
	ds_read_b128 v[166:169], v219 offset:1024
	ds_read_b128 v[170:173], v219 offset:2048
	ds_read_b128 v[174:177], v219 offset:3072
	ds_read_b128 v[178:181], v219 offset:4096
	ds_read_b128 v[182:185], v219 offset:5120
	ds_read_b128 v[186:189], v219 offset:6144
	ds_read_b128 v[212:215], v219 offset:7168
	s_add_i32 s38, s28, 2
	s_add_u32 s26, s0, 0x80
	s_addc_u32 s29, s1, 0
	s_add_i32 s39, 0, 0x10000
	s_cmp_eq_u32 s88, s28
	s_cselect_b32 s29, s49, s29
	s_cselect_b32 s28, s48, s26
	s_cselect_b32 s93, s67, s16
	s_cselect_b32 s92, s66, s15
	s_add_i32 s26, 0, 0x14000
	s_add_i32 m0, s13, 0xc000
	v_lshl_add_u64 v[202:203], s[0:1], 0, v[210:211]
	global_load_lds_dwordx4 v[202:203], off
	s_add_i32 m0, s13, 0xe000
	v_lshl_add_u64 v[202:203], s[0:1], 0, v[208:209]
	global_load_lds_dwordx4 v[202:203], off
	s_waitcnt vmcnt(8)
	s_waitcnt lgkmcnt(0)
	s_barrier
	s_waitcnt lgkmcnt(0)
	v_mfma_f32_16x16x32_bf16 v[122:125], v[130:133], v[162:165], v[122:125]
	v_mfma_f32_16x16x32_bf16 v[126:129], v[138:141], v[162:165], v[126:129]
	v_mfma_f32_16x16x32_bf16 v[110:113], v[130:133], v[170:173], v[110:113]
	v_mfma_f32_16x16x32_bf16 v[106:109], v[138:141], v[170:173], v[106:109]
	v_mfma_f32_16x16x32_bf16 v[94:97], v[130:133], v[178:181], v[94:97]
	v_mfma_f32_16x16x32_bf16 v[90:93], v[138:141], v[178:181], v[90:93]
	v_mfma_f32_16x16x32_bf16 v[78:81], v[130:133], v[186:189], v[78:81]
	v_mfma_f32_16x16x32_bf16 v[74:77], v[138:141], v[186:189], v[74:77]
	v_mfma_f32_16x16x32_bf16 v[122:125], v[134:137], v[166:169], v[122:125]
	v_mfma_f32_16x16x32_bf16 v[126:129], v[142:145], v[166:169], v[126:129]
	v_mfma_f32_16x16x32_bf16 v[110:113], v[134:137], v[174:177], v[110:113]
	v_mfma_f32_16x16x32_bf16 v[106:109], v[142:145], v[174:177], v[106:109]
	v_mfma_f32_16x16x32_bf16 v[94:97], v[134:137], v[182:185], v[94:97]
	v_mfma_f32_16x16x32_bf16 v[90:93], v[142:145], v[182:185], v[90:93]
	v_mfma_f32_16x16x32_bf16 v[78:81], v[134:137], v[212:215], v[78:81]
	v_mfma_f32_16x16x32_bf16 v[74:77], v[142:145], v[212:215], v[74:77]
	v_mfma_f32_16x16x32_bf16 v[118:121], v[146:149], v[162:165], v[118:121]
	v_mfma_f32_16x16x32_bf16 v[114:117], v[154:157], v[162:165], v[114:117]
	v_mfma_f32_16x16x32_bf16 v[102:105], v[146:149], v[170:173], v[102:105]
	v_mfma_f32_16x16x32_bf16 v[98:101], v[154:157], v[170:173], v[98:101]
	v_mfma_f32_16x16x32_bf16 v[86:89], v[146:149], v[178:181], v[86:89]
	v_mfma_f32_16x16x32_bf16 v[82:85], v[154:157], v[178:181], v[82:85]
	v_mfma_f32_16x16x32_bf16 v[70:73], v[146:149], v[186:189], v[70:73]
	v_mfma_f32_16x16x32_bf16 v[66:69], v[154:157], v[186:189], v[66:69]
	v_mfma_f32_16x16x32_bf16 v[118:121], v[150:153], v[166:169], v[118:121]
	v_mfma_f32_16x16x32_bf16 v[114:117], v[158:161], v[166:169], v[114:117]
	v_mfma_f32_16x16x32_bf16 v[102:105], v[150:153], v[174:177], v[102:105]
	v_mfma_f32_16x16x32_bf16 v[98:101], v[158:161], v[174:177], v[98:101]
	v_mfma_f32_16x16x32_bf16 v[86:89], v[150:153], v[182:185], v[86:89]
	v_mfma_f32_16x16x32_bf16 v[82:85], v[158:161], v[182:185], v[82:85]
	v_mfma_f32_16x16x32_bf16 v[70:73], v[150:153], v[212:215], v[70:73]
	v_mfma_f32_16x16x32_bf16 v[66:69], v[158:161], v[212:215], v[66:69]
	s_barrier
	s_add_i32 s39, s39, s12
	v_lshl_add_u64 v[202:203], s[92:93], 0, v[0:1]
	s_mov_b32 m0, s39
	ds_read_b128 v[162:165], v219 offset:16384
	ds_read_b128 v[166:169], v219 offset:17408
	ds_read_b128 v[170:173], v219 offset:18432
	ds_read_b128 v[174:177], v219 offset:19456
	ds_read_b128 v[178:181], v219 offset:20480
	ds_read_b128 v[182:185], v219 offset:21504
	ds_read_b128 v[186:189], v219 offset:22528
	ds_read_b128 v[212:215], v219 offset:23552
	global_load_lds_dwordx4 v[202:203], off
	s_add_i32 m0, s39, 0x2000
	v_lshl_add_u64 v[220:221], s[92:93], 0, v[190:191]
	s_add_u32 s92, s92, s56
	s_addc_u32 s93, s93, s57
	s_add_i32 s26, s26, s12
	global_load_lds_dwordx4 v[220:221], off
	v_lshl_add_u64 v[222:223], s[92:93], 0, v[0:1]
	s_mov_b32 m0, s26
	v_lshl_add_u64 v[224:225], s[92:93], 0, v[190:191]
	global_load_lds_dwordx4 v[222:223], off
	s_add_i32 m0, s26, 0x2000
	v_lshl_add_u64 v[226:227], s[28:29], 0, v[206:207]
	global_load_lds_dwordx4 v[224:225], off
	s_mov_b32 m0, s13
	v_lshl_add_u64 v[228:229], s[28:29], 0, v[192:193]
	global_load_lds_dwordx4 v[226:227], off
	s_mov_b32 m0, s27
	s_nop 0
	global_load_lds_dwordx4 v[228:229], off
	s_waitcnt vmcnt(8)
	s_waitcnt lgkmcnt(0)
	s_barrier
; #define PG8_STAGE(bufoff, gbase, voff) do { _Pragma("unroll") for (int _i = 0; _i < 2; ++_i) \
;         __builtin_amdgcn_global_load_lds((const unsigned*)((const char*)(gbase) + (voff)[_i]), (LAS unsigned*)(lds + (bufoff) + ldsw + _i * 8192), 16, 0, 0); } while (0)
; #define PG8_LDA(dst, b, h) do { _Pragma("unroll") for (int m = 0; m < 4; ++m) _Pragma("unroll") for (int k = 0; k < 2; ++k) dst[m][k] = *(const LAS bf16x8*)(lds + PG8_SA(b, h) + aoff + m * 2048 + k * 1024); } while (0)
; #define PG8_LDB(dst, b, h) do { _Pragma("unroll") for (int n = 0; n < 2; ++n) _Pragma("unroll") for (int k = 0; k < 2; ++k) dst[n][k] = *(const LAS bf16x8*)(lds + PG8_SB(b, h) + boff + n * 2048 + k * 1024); } while (0)
; #define PG8_MMA(ai, bj, At, Bt) do { __builtin_amdgcn_s_setprio(1); _Pragma("unroll") for (int m = 0; m < 4; ++m) _Pragma("unroll") for (int n = 0; n < 2; ++n) _Pragma("unroll") for (int k = 0; k < 2; ++k) \
;         acc[ai][bj][m][n] = __builtin_amdgcn_mfma_f32_16x16x32_bf16(Bt[n][k], At[m][k], acc[ai][bj][m][n], 0, 0, 0); __builtin_amdgcn_s_setprio(0); } while (0)
; #define PG8_WAIT_V(n) asm volatile("s_waitcnt vmcnt(" #n ")" ::: "memory")
; #define PG8_WAIT_L(n) asm volatile("s_waitcnt lgkmcnt(" #n ")" ::: "memory")
; #define PG8_BAR __builtin_amdgcn_s_barrier()
; #define PG8_SCHED __builtin_amdgcn_sched_barrier(0)
; template <class Epi, class Sched>
; __device__ __forceinline__ void gemm_phase(LAS unsigned char* lds, const Gemm g, const Sched& S, const Epi& E) {
;     ...
;             PG8_WAIT_V(8); PG8_WAIT_L(0); PG8_BAR; PG8_MMA(1, 0, At, B0); PG8_MMA(1, 1, At, B1); PG8_BAR; PG8_SCHED;
;             PG8_LDB(B0, 1, 0); PG8_LDB(B1, 1, 1); PG8_SCHED; PG8_LDA(At, 1, 0); PG8_STAGE(PG8_SA(0, 1), a2 + hstep, voffA);
;             PG8_WAIT_V(8); PG8_WAIT_L(0); PG8_BAR; PG8_MMA(0, 0, At, B0); PG8_MMA(0, 1, At, B1); PG8_BAR; PG8_SCHED;
	s_waitcnt lgkmcnt(0)
	v_mfma_f32_16x16x32_bf16 v[62:65], v[130:133], v[162:165], v[62:65]
	v_mfma_f32_16x16x32_bf16 v[58:61], v[138:141], v[162:165], v[58:61]
	v_mfma_f32_16x16x32_bf16 v[46:49], v[130:133], v[170:173], v[46:49]
	v_mfma_f32_16x16x32_bf16 v[42:45], v[138:141], v[170:173], v[42:45]
	v_mfma_f32_16x16x32_bf16 v[30:33], v[130:133], v[178:181], v[30:33]
	v_mfma_f32_16x16x32_bf16 v[26:29], v[138:141], v[178:181], v[26:29]
	v_mfma_f32_16x16x32_bf16 v[14:17], v[130:133], v[186:189], v[14:17]
	v_mfma_f32_16x16x32_bf16 v[10:13], v[138:141], v[186:189], v[10:13]
	v_mfma_f32_16x16x32_bf16 v[62:65], v[134:137], v[166:169], v[62:65]
	v_mfma_f32_16x16x32_bf16 v[58:61], v[142:145], v[166:169], v[58:61]
	v_mfma_f32_16x16x32_bf16 v[46:49], v[134:137], v[174:177], v[46:49]
	v_mfma_f32_16x16x32_bf16 v[42:45], v[142:145], v[174:177], v[42:45]
	v_mfma_f32_16x16x32_bf16 v[30:33], v[134:137], v[182:185], v[30:33]
	v_mfma_f32_16x16x32_bf16 v[26:29], v[142:145], v[182:185], v[26:29]
	v_mfma_f32_16x16x32_bf16 v[14:17], v[134:137], v[212:215], v[14:17]
	v_mfma_f32_16x16x32_bf16 v[10:13], v[142:145], v[212:215], v[10:13]
	v_mfma_f32_16x16x32_bf16 v[54:57], v[146:149], v[162:165], v[54:57]
	v_mfma_f32_16x16x32_bf16 v[50:53], v[154:157], v[162:165], v[50:53]
	v_mfma_f32_16x16x32_bf16 v[38:41], v[146:149], v[170:173], v[38:41]
	v_mfma_f32_16x16x32_bf16 v[34:37], v[154:157], v[170:173], v[34:37]
	v_mfma_f32_16x16x32_bf16 v[22:25], v[146:149], v[178:181], v[22:25]
	v_mfma_f32_16x16x32_bf16 v[18:21], v[154:157], v[178:181], v[18:21]
	v_mfma_f32_16x16x32_bf16 v[6:9], v[146:149], v[186:189], v[6:9]
	v_mfma_f32_16x16x32_bf16 v[2:5], v[154:157], v[186:189], v[2:5]
	v_mfma_f32_16x16x32_bf16 v[54:57], v[150:153], v[166:169], v[54:57]
	v_mfma_f32_16x16x32_bf16 v[50:53], v[158:161], v[166:169], v[50:53]
	v_mfma_f32_16x16x32_bf16 v[38:41], v[150:153], v[174:177], v[38:41]
	v_mfma_f32_16x16x32_bf16 v[34:37], v[158:161], v[174:177], v[34:37]
	v_mfma_f32_16x16x32_bf16 v[22:25], v[150:153], v[182:185], v[22:25]
	v_mfma_f32_16x16x32_bf16 v[18:21], v[158:161], v[182:185], v[18:21]
	v_mfma_f32_16x16x32_bf16 v[6:9], v[150:153], v[212:215], v[6:9]
	v_mfma_f32_16x16x32_bf16 v[2:5], v[158:161], v[212:215], v[2:5]
	s_barrier
	ds_read_b128 v[130:133], v239
	ds_read_b128 v[134:137], v239 offset:1024
	ds_read_b128 v[138:141], v239 offset:2048
	ds_read_b128 v[142:145], v239 offset:3072
	ds_read_b128 v[146:149], v250
	ds_read_b128 v[150:153], v250 offset:1024
	ds_read_b128 v[154:157], v250 offset:2048
	ds_read_b128 v[158:161], v250 offset:3072
	s_add_i32 s26, 0, 0x18000
	s_add_i32 s39, 0, 0x1c000
	s_add_u32 s28, s28, s56
	s_addc_u32 s29, s29, s57
	s_mov_b32 m0, s34
	v_lshl_add_u64 v[230:231], s[28:29], 0, v[206:207]
	ds_read_b128 v[162:165], v219 offset:32768
	ds_read_b128 v[166:169], v219 offset:33792
	ds_read_b128 v[170:173], v219 offset:34816
	ds_read_b128 v[174:177], v219 offset:35840
	ds_read_b128 v[178:181], v219 offset:36864
	ds_read_b128 v[182:185], v219 offset:37888
	ds_read_b128 v[186:189], v219 offset:38912
	ds_read_b128 v[212:215], v219 offset:39936
	global_load_lds_dwordx4 v[230:231], off
	s_mov_b32 m0, s35
	v_lshl_add_u64 v[230:231], s[28:29], 0, v[192:193]
	global_load_lds_dwordx4 v[230:231], off
	s_waitcnt vmcnt(8)
	s_waitcnt lgkmcnt(0)
	s_barrier
	s_waitcnt lgkmcnt(0)
	v_mfma_f32_16x16x32_bf16 v[122:125], v[130:133], v[162:165], v[122:125]
	v_mfma_f32_16x16x32_bf16 v[126:129], v[138:141], v[162:165], v[126:129]
	v_mfma_f32_16x16x32_bf16 v[110:113], v[130:133], v[170:173], v[110:113]
	v_mfma_f32_16x16x32_bf16 v[106:109], v[138:141], v[170:173], v[106:109]
	v_mfma_f32_16x16x32_bf16 v[94:97], v[130:133], v[178:181], v[94:97]
	v_mfma_f32_16x16x32_bf16 v[90:93], v[138:141], v[178:181], v[90:93]
	v_mfma_f32_16x16x32_bf16 v[78:81], v[130:133], v[186:189], v[78:81]
	v_mfma_f32_16x16x32_bf16 v[74:77], v[138:141], v[186:189], v[74:77]
	v_mfma_f32_16x16x32_bf16 v[122:125], v[134:137], v[166:169], v[122:125]
	v_mfma_f32_16x16x32_bf16 v[126:129], v[142:145], v[166:169], v[126:129]
	v_mfma_f32_16x16x32_bf16 v[110:113], v[134:137], v[174:177], v[110:113]
	v_mfma_f32_16x16x32_bf16 v[106:109], v[142:145], v[174:177], v[106:109]
	v_mfma_f32_16x16x32_bf16 v[94:97], v[134:137], v[182:185], v[94:97]
	v_mfma_f32_16x16x32_bf16 v[90:93], v[142:145], v[182:185], v[90:93]
	v_mfma_f32_16x16x32_bf16 v[78:81], v[134:137], v[212:215], v[78:81]
	v_mfma_f32_16x16x32_bf16 v[74:77], v[142:145], v[212:215], v[74:77]
	v_mfma_f32_16x16x32_bf16 v[118:121], v[146:149], v[162:165], v[118:121]
	v_mfma_f32_16x16x32_bf16 v[114:117], v[154:157], v[162:165], v[114:117]
	v_mfma_f32_16x16x32_bf16 v[102:105], v[146:149], v[170:173], v[102:105]
	v_mfma_f32_16x16x32_bf16 v[98:101], v[154:157], v[170:173], v[98:101]
	v_mfma_f32_16x16x32_bf16 v[86:89], v[146:149], v[178:181], v[86:89]
	v_mfma_f32_16x16x32_bf16 v[82:85], v[154:157], v[178:181], v[82:85]
	v_mfma_f32_16x16x32_bf16 v[70:73], v[146:149], v[186:189], v[70:73]
	v_mfma_f32_16x16x32_bf16 v[66:69], v[154:157], v[186:189], v[66:69]
	v_mfma_f32_16x16x32_bf16 v[118:121], v[150:153], v[166:169], v[118:121]
	v_mfma_f32_16x16x32_bf16 v[114:117], v[158:161], v[166:169], v[114:117]
	v_mfma_f32_16x16x32_bf16 v[102:105], v[150:153], v[174:177], v[102:105]
	v_mfma_f32_16x16x32_bf16 v[98:101], v[158:161], v[174:177], v[98:101]
	v_mfma_f32_16x16x32_bf16 v[86:89], v[150:153], v[182:185], v[86:89]
	v_mfma_f32_16x16x32_bf16 v[82:85], v[158:161], v[182:185], v[82:85]
	v_mfma_f32_16x16x32_bf16 v[70:73], v[150:153], v[212:215], v[70:73]
	v_mfma_f32_16x16x32_bf16 v[66:69], v[158:161], v[212:215], v[66:69]
	s_barrier
; #define PG8_STAGE(bufoff, gbase, voff) do { _Pragma("unroll") for (int _i = 0; _i < 2; ++_i) \
;         __builtin_amdgcn_global_load_lds((const unsigned*)((const char*)(gbase) + (voff)[_i]), (LAS unsigned*)(lds + (bufoff) + ldsw + _i * 8192), 16, 0, 0); } while (0)
; #define PG8_LDA(dst, b, h) do { _Pragma("unroll") for (int m = 0; m < 4; ++m) _Pragma("unroll") for (int k = 0; k < 2; ++k) dst[m][k] = *(const LAS bf16x8*)(lds + PG8_SA(b, h) + aoff + m * 2048 + k * 1024); } while (0)
; #define PG8_MMA(ai, bj, At, Bt) do { __builtin_amdgcn_s_setprio(1); _Pragma("unroll") for (int m = 0; m < 4; ++m) _Pragma("unroll") for (int n = 0; n < 2; ++n) _Pragma("unroll") for (int k = 0; k < 2; ++k) \
;         acc[ai][bj][m][n] = __builtin_amdgcn_mfma_f32_16x16x32_bf16(Bt[n][k], At[m][k], acc[ai][bj][m][n], 0, 0, 0); __builtin_amdgcn_s_setprio(0); } while (0)
; #define PG8_WAIT_V(n) asm volatile("s_waitcnt vmcnt(" #n ")" ::: "memory")
; #define PG8_WAIT_L(n) asm volatile("s_waitcnt lgkmcnt(" #n ")" ::: "memory")
; #define PG8_BAR __builtin_amdgcn_s_barrier()
; #define PG8_SCHED __builtin_amdgcn_sched_barrier(0)
; template <class Epi, class Sched>
; __device__ __forceinline__ void gemm_phase(LAS unsigned char* lds, const Gemm g, const Sched& S, const Epi& E) {
;     ...
;             PG8_LDA(At, 1, 1); PG8_STAGE(PG8_SB(1, 0), b3, voffB); PG8_STAGE(PG8_SB(1, 1), b3 + hstep, voffB); PG8_STAGE(PG8_SA(1, 0), a3, voffA);
;             PG8_WAIT_V(8); PG8_WAIT_L(0); PG8_BAR; PG8_MMA(1, 0, At, B0); PG8_MMA(1, 1, At, B1); PG8_BAR; PG8_SCHED;
;         }
	s_add_i32 s26, s26, s12
	v_lshl_add_u64 v[202:203], v[202:203], 0, s[18:19]
	s_mov_b32 m0, s26
	ds_read_b128 v[162:165], v219 offset:49152
	ds_read_b128 v[166:169], v219 offset:50176
	ds_read_b128 v[170:173], v219 offset:51200
	ds_read_b128 v[174:177], v219 offset:52224
	ds_read_b128 v[178:181], v219 offset:53248
	ds_read_b128 v[182:185], v219 offset:54272
	ds_read_b128 v[186:189], v219 offset:55296
	ds_read_b128 v[212:215], v219 offset:56320
	global_load_lds_dwordx4 v[202:203], off
	v_lshl_add_u64 v[202:203], v[220:221], 0, s[18:19]
	s_add_i32 m0, s26, 0x2000
	s_add_i32 s26, s39, s12
	global_load_lds_dwordx4 v[202:203], off
	s_mov_b32 m0, s26
	v_lshl_add_u64 v[202:203], v[222:223], 0, s[18:19]
	global_load_lds_dwordx4 v[202:203], off
	s_add_i32 m0, s26, 0x2000
	v_lshl_add_u64 v[202:203], v[224:225], 0, s[18:19]
	global_load_lds_dwordx4 v[202:203], off
	s_mov_b32 m0, s84
	v_lshl_add_u64 v[202:203], v[226:227], 0, s[18:19]
	global_load_lds_dwordx4 v[202:203], off
	s_mov_b32 m0, s85
	v_lshl_add_u64 v[202:203], v[228:229], 0, s[18:19]
	global_load_lds_dwordx4 v[202:203], off
	s_waitcnt vmcnt(8)
	s_waitcnt lgkmcnt(0)
	s_barrier
	s_waitcnt lgkmcnt(0)
	v_mfma_f32_16x16x32_bf16 v[62:65], v[130:133], v[162:165], v[62:65]
	v_mfma_f32_16x16x32_bf16 v[58:61], v[138:141], v[162:165], v[58:61]
	v_mfma_f32_16x16x32_bf16 v[46:49], v[130:133], v[170:173], v[46:49]
	v_mfma_f32_16x16x32_bf16 v[42:45], v[138:141], v[170:173], v[42:45]
	v_mfma_f32_16x16x32_bf16 v[30:33], v[130:133], v[178:181], v[30:33]
	v_mfma_f32_16x16x32_bf16 v[26:29], v[138:141], v[178:181], v[26:29]
	v_mfma_f32_16x16x32_bf16 v[14:17], v[130:133], v[186:189], v[14:17]
	v_mfma_f32_16x16x32_bf16 v[10:13], v[138:141], v[186:189], v[10:13]
	v_mfma_f32_16x16x32_bf16 v[62:65], v[134:137], v[166:169], v[62:65]
	v_mfma_f32_16x16x32_bf16 v[58:61], v[142:145], v[166:169], v[58:61]
	v_mfma_f32_16x16x32_bf16 v[46:49], v[134:137], v[174:177], v[46:49]
	v_mfma_f32_16x16x32_bf16 v[42:45], v[142:145], v[174:177], v[42:45]
	v_mfma_f32_16x16x32_bf16 v[30:33], v[134:137], v[182:185], v[30:33]
	v_mfma_f32_16x16x32_bf16 v[26:29], v[142:145], v[182:185], v[26:29]
	v_mfma_f32_16x16x32_bf16 v[14:17], v[134:137], v[212:215], v[14:17]
	v_mfma_f32_16x16x32_bf16 v[10:13], v[142:145], v[212:215], v[10:13]
	v_mfma_f32_16x16x32_bf16 v[54:57], v[146:149], v[162:165], v[54:57]
	v_mfma_f32_16x16x32_bf16 v[50:53], v[154:157], v[162:165], v[50:53]
	v_mfma_f32_16x16x32_bf16 v[38:41], v[146:149], v[170:173], v[38:41]
	v_mfma_f32_16x16x32_bf16 v[34:37], v[154:157], v[170:173], v[34:37]
	v_mfma_f32_16x16x32_bf16 v[22:25], v[146:149], v[178:181], v[22:25]
	v_mfma_f32_16x16x32_bf16 v[18:21], v[154:157], v[178:181], v[18:21]
	v_mfma_f32_16x16x32_bf16 v[6:9], v[146:149], v[186:189], v[6:9]
	v_mfma_f32_16x16x32_bf16 v[2:5], v[154:157], v[186:189], v[2:5]
	v_mfma_f32_16x16x32_bf16 v[54:57], v[150:153], v[166:169], v[54:57]
	v_mfma_f32_16x16x32_bf16 v[50:53], v[158:161], v[166:169], v[50:53]
	v_mfma_f32_16x16x32_bf16 v[38:41], v[150:153], v[174:177], v[38:41]
	v_mfma_f32_16x16x32_bf16 v[34:37], v[158:161], v[174:177], v[34:37]
	v_mfma_f32_16x16x32_bf16 v[22:25], v[150:153], v[182:185], v[22:25]
	v_mfma_f32_16x16x32_bf16 v[18:21], v[158:161], v[182:185], v[18:21]
	v_mfma_f32_16x16x32_bf16 v[6:9], v[150:153], v[212:215], v[6:9]
	v_mfma_f32_16x16x32_bf16 v[2:5], v[158:161], v[212:215], v[2:5]
	s_barrier
	s_add_u32 s15, s15, 0x100
	s_addc_u32 s16, s16, 0
	s_add_u32 s0, s0, 0x100
	s_addc_u32 s1, s1, 0
	s_cmp_ge_i32 s38, s31
	s_mov_b32 s28, s38
	s_cbranch_scc0 .LBB0_1776
	v_readlane_b32 s92, v255, 40
	v_readlane_b32 s93, v255, 41

; #define PG8_STAGE(bufoff, gbase, voff) do { _Pragma("unroll") for (int _i = 0; _i < 2; ++_i) \
;         __builtin_amdgcn_global_load_lds((const unsigned*)((const char*)(gbase) + (voff)[_i]), (LAS unsigned*)(lds + (bufoff) + ldsw + _i * 8192), 16, 0, 0); } while (0)
; #define PG8_LDA(dst, b, h) do { _Pragma("unroll") for (int m = 0; m < 4; ++m) _Pragma("unroll") for (int k = 0; k < 2; ++k) dst[m][k] = *(const LAS bf16x8*)(lds + PG8_SA(b, h) + aoff + m * 2048 + k * 1024); } while (0)
; #define PG8_LDB(dst, b, h) do { _Pragma("unroll") for (int n = 0; n < 2; ++n) _Pragma("unroll") for (int k = 0; k < 2; ++k) dst[n][k] = *(const LAS bf16x8*)(lds + PG8_SB(b, h) + boff + n * 2048 + k * 1024); } while (0)
; #define PG8_MMA(ai, bj, At, Bt) do { __builtin_amdgcn_s_setprio(1); _Pragma("unroll") for (int m = 0; m < 4; ++m) _Pragma("unroll") for (int n = 0; n < 2; ++n) _Pragma("unroll") for (int k = 0; k < 2; ++k) \
;         acc[ai][bj][m][n] = __builtin_amdgcn_mfma_f32_16x16x32_bf16(Bt[n][k], At[m][k], acc[ai][bj][m][n], 0, 0, 0); __builtin_amdgcn_s_setprio(0); } while (0)
; #define PG8_WAIT_V(n) asm volatile("s_waitcnt vmcnt(" #n ")" ::: "memory")
; #define PG8_WAIT_L(n) asm volatile("s_waitcnt lgkmcnt(" #n ")" ::: "memory")
; #define PG8_BAR __builtin_amdgcn_s_barrier()
; #define PG8_SCHED __builtin_amdgcn_sched_barrier(0)
; template <class Epi, class Sched>
; __device__ __forceinline__ void gemm_phase(LAS unsigned char* lds, const Gemm g, const Sched& S, const Epi& E) {
;     ...
;         for (int t = 0; t < nt; t += 2) {
;             const bool last = (t == nt - 2);
;             const char* a1 = cA + (size_t)(t + 1) * kstep;
;             const char* a2 = last ? nA : cA + (size_t)(t + 2) * kstep; const char* b2 = last ? nB : cB + (size_t)(t + 2) * kstep;
;             const char* a3 = a2 + kstep; const char* b3 = b2 + kstep;
;             PG8_LDB(B0, 0, 0); PG8_LDB(B1, 0, 1); PG8_SCHED; PG8_LDA(At, 0, 0); PG8_STAGE(PG8_SA(1, 1), a1 + hstep, voffA);
;             PG8_WAIT_V(8); PG8_WAIT_L(0); PG8_BAR; PG8_MMA(0, 0, At, B0); PG8_MMA(0, 1, At, B1); PG8_BAR; PG8_SCHED;
;             PG8_LDA(At, 0, 1); PG8_STAGE(PG8_SB(0, 0), b2, voffB); PG8_STAGE(PG8_SB(0, 1), b2 + hstep, voffB); PG8_STAGE(PG8_SA(0, 0), a2, voffA);
.LBB0_1908:
	ds_read_b128 v[130:133], v235
	ds_read_b128 v[134:137], v235 offset:1024
	ds_read_b128 v[138:141], v235 offset:2048
	ds_read_b128 v[142:145], v235 offset:3072
	ds_read_b128 v[146:149], v238
	ds_read_b128 v[150:153], v238 offset:1024
	ds_read_b128 v[166:169], v238 offset:2048
	ds_read_b128 v[170:173], v238 offset:3072
	ds_read_b128 v[174:177], v187
	ds_read_b128 v[178:181], v187 offset:1024
	ds_read_b128 v[188:191], v187 offset:2048
	ds_read_b128 v[206:209], v187 offset:3072
	ds_read_b128 v[210:213], v187 offset:4096
	ds_read_b128 v[214:217], v187 offset:5120
	ds_read_b128 v[218:221], v187 offset:6144
	ds_read_b128 v[222:225], v187 offset:7168
	s_add_i32 s38, s28, 2
	s_add_u32 s26, s0, 0x80
	s_addc_u32 s29, s1, 0
	s_add_i32 s39, 0, 0x10000
	s_cmp_eq_u32 s84, s28
	s_cselect_b32 s29, s65, s29
	s_cselect_b32 s28, s64, s26
	s_cselect_b32 s45, s67, s16
	s_cselect_b32 s44, s66, s15
	s_add_i32 s26, 0, 0x14000
	s_add_i32 m0, s13, 0xc000
	v_lshl_add_u64 v[182:183], s[0:1], 0, v[164:165]
	global_load_lds_dwordx4 v[182:183], off
	s_add_i32 m0, s13, 0xe000
	v_lshl_add_u64 v[182:183], s[0:1], 0, v[162:163]
	global_load_lds_dwordx4 v[182:183], off
	s_waitcnt vmcnt(8)
	s_waitcnt lgkmcnt(0)
	s_barrier
	s_waitcnt lgkmcnt(0)
	v_mfma_f32_16x16x32_bf16 v[122:125], v[130:133], v[174:177], v[122:125]
	v_mfma_f32_16x16x32_bf16 v[114:117], v[138:141], v[174:177], v[114:117]
	v_mfma_f32_16x16x32_bf16 v[106:109], v[130:133], v[188:191], v[106:109]
	v_mfma_f32_16x16x32_bf16 v[98:101], v[138:141], v[188:191], v[98:101]
	v_mfma_f32_16x16x32_bf16 v[90:93], v[130:133], v[210:213], v[90:93]
	v_mfma_f32_16x16x32_bf16 v[82:85], v[138:141], v[210:213], v[82:85]
	v_mfma_f32_16x16x32_bf16 v[74:77], v[130:133], v[218:221], v[74:77]
	v_mfma_f32_16x16x32_bf16 v[66:69], v[138:141], v[218:221], v[66:69]
	v_mfma_f32_16x16x32_bf16 v[122:125], v[134:137], v[178:181], v[122:125]
	v_mfma_f32_16x16x32_bf16 v[114:117], v[142:145], v[178:181], v[114:117]
	v_mfma_f32_16x16x32_bf16 v[106:109], v[134:137], v[206:209], v[106:109]
	v_mfma_f32_16x16x32_bf16 v[98:101], v[142:145], v[206:209], v[98:101]
	v_mfma_f32_16x16x32_bf16 v[90:93], v[134:137], v[214:217], v[90:93]
	v_mfma_f32_16x16x32_bf16 v[82:85], v[142:145], v[214:217], v[82:85]
	v_mfma_f32_16x16x32_bf16 v[74:77], v[134:137], v[222:225], v[74:77]
	v_mfma_f32_16x16x32_bf16 v[66:69], v[142:145], v[222:225], v[66:69]
	v_mfma_f32_16x16x32_bf16 v[126:129], v[146:149], v[174:177], v[126:129]
	v_mfma_f32_16x16x32_bf16 v[118:121], v[166:169], v[174:177], v[118:121]
	v_mfma_f32_16x16x32_bf16 v[110:113], v[146:149], v[188:191], v[110:113]
	v_mfma_f32_16x16x32_bf16 v[102:105], v[166:169], v[188:191], v[102:105]
	v_mfma_f32_16x16x32_bf16 v[94:97], v[146:149], v[210:213], v[94:97]
	v_mfma_f32_16x16x32_bf16 v[86:89], v[166:169], v[210:213], v[86:89]
	v_mfma_f32_16x16x32_bf16 v[78:81], v[146:149], v[218:221], v[78:81]
	v_mfma_f32_16x16x32_bf16 v[70:73], v[166:169], v[218:221], v[70:73]
	v_mfma_f32_16x16x32_bf16 v[126:129], v[150:153], v[178:181], v[126:129]
	v_mfma_f32_16x16x32_bf16 v[118:121], v[170:173], v[178:181], v[118:121]
	v_mfma_f32_16x16x32_bf16 v[110:113], v[150:153], v[206:209], v[110:113]
	v_mfma_f32_16x16x32_bf16 v[102:105], v[170:173], v[206:209], v[102:105]
	v_mfma_f32_16x16x32_bf16 v[94:97], v[150:153], v[214:217], v[94:97]
	v_mfma_f32_16x16x32_bf16 v[86:89], v[170:173], v[214:217], v[86:89]
	v_mfma_f32_16x16x32_bf16 v[78:81], v[150:153], v[222:225], v[78:81]
	v_mfma_f32_16x16x32_bf16 v[70:73], v[170:173], v[222:225], v[70:73]
	s_barrier
	s_add_i32 s39, s39, s12
	v_lshl_add_u64 v[182:183], s[44:45], 0, v[0:1]
	s_mov_b32 m0, s39
	ds_read_b128 v[174:177], v187 offset:16384
	ds_read_b128 v[178:181], v187 offset:17408
	ds_read_b128 v[188:191], v187 offset:18432
	ds_read_b128 v[206:209], v187 offset:19456
	ds_read_b128 v[210:213], v187 offset:20480
	ds_read_b128 v[214:217], v187 offset:21504
	ds_read_b128 v[218:221], v187 offset:22528
	ds_read_b128 v[222:225], v187 offset:23552
	global_load_lds_dwordx4 v[182:183], off
	s_add_i32 m0, s39, 0x2000
	v_lshl_add_u64 v[192:193], s[44:45], 0, v[154:155]
	s_add_u32 s44, s44, s56
	s_addc_u32 s45, s45, s57
	s_add_i32 s26, s26, s12
	global_load_lds_dwordx4 v[192:193], off
	v_lshl_add_u64 v[202:203], s[44:45], 0, v[0:1]
	s_mov_b32 m0, s26
	v_lshl_add_u64 v[226:227], s[44:45], 0, v[154:155]
	global_load_lds_dwordx4 v[202:203], off
	s_add_i32 m0, s26, 0x2000
	v_lshl_add_u64 v[228:229], s[28:29], 0, v[158:159]
	global_load_lds_dwordx4 v[226:227], off
	s_mov_b32 m0, s13
	v_lshl_add_u64 v[230:231], s[28:29], 0, v[156:157]
	global_load_lds_dwordx4 v[228:229], off
	s_mov_b32 m0, s27
	s_nop 0
	global_load_lds_dwordx4 v[230:231], off
	s_waitcnt vmcnt(8)
	s_waitcnt lgkmcnt(0)
	s_barrier
; #define PG8_STAGE(bufoff, gbase, voff) do { _Pragma("unroll") for (int _i = 0; _i < 2; ++_i) \
;         __builtin_amdgcn_global_load_lds((const unsigned*)((const char*)(gbase) + (voff)[_i]), (LAS unsigned*)(lds + (bufoff) + ldsw + _i * 8192), 16, 0, 0); } while (0)
; #define PG8_LDA(dst, b, h) do { _Pragma("unroll") for (int m = 0; m < 4; ++m) _Pragma("unroll") for (int k = 0; k < 2; ++k) dst[m][k] = *(const LAS bf16x8*)(lds + PG8_SA(b, h) + aoff + m * 2048 + k * 1024); } while (0)
; #define PG8_LDB(dst, b, h) do { _Pragma("unroll") for (int n = 0; n < 2; ++n) _Pragma("unroll") for (int k = 0; k < 2; ++k) dst[n][k] = *(const LAS bf16x8*)(lds + PG8_SB(b, h) + boff + n * 2048 + k * 1024); } while (0)
; #define PG8_MMA(ai, bj, At, Bt) do { __builtin_amdgcn_s_setprio(1); _Pragma("unroll") for (int m = 0; m < 4; ++m) _Pragma("unroll") for (int n = 0; n < 2; ++n) _Pragma("unroll") for (int k = 0; k < 2; ++k) \
;         acc[ai][bj][m][n] = __builtin_amdgcn_mfma_f32_16x16x32_bf16(Bt[n][k], At[m][k], acc[ai][bj][m][n], 0, 0, 0); __builtin_amdgcn_s_setprio(0); } while (0)
; #define PG8_WAIT_V(n) asm volatile("s_waitcnt vmcnt(" #n ")" ::: "memory")
; #define PG8_WAIT_L(n) asm volatile("s_waitcnt lgkmcnt(" #n ")" ::: "memory")
; #define PG8_BAR __builtin_amdgcn_s_barrier()
; #define PG8_SCHED __builtin_amdgcn_sched_barrier(0)
; template <class Epi, class Sched>
; __device__ __forceinline__ void gemm_phase(LAS unsigned char* lds, const Gemm g, const Sched& S, const Epi& E) {
;     ...
;             PG8_WAIT_V(8); PG8_WAIT_L(0); PG8_BAR; PG8_MMA(1, 0, At, B0); PG8_MMA(1, 1, At, B1); PG8_BAR; PG8_SCHED;
;             PG8_LDB(B0, 1, 0); PG8_LDB(B1, 1, 1); PG8_SCHED; PG8_LDA(At, 1, 0); PG8_STAGE(PG8_SA(0, 1), a2 + hstep, voffA);
;             PG8_WAIT_V(8); PG8_WAIT_L(0); PG8_BAR; PG8_MMA(0, 0, At, B0); PG8_MMA(0, 1, At, B1); PG8_BAR; PG8_SCHED;
	s_waitcnt lgkmcnt(0)
	v_mfma_f32_16x16x32_bf16 v[58:61], v[130:133], v[174:177], v[58:61]
	v_mfma_f32_16x16x32_bf16 v[50:53], v[138:141], v[174:177], v[50:53]
	v_mfma_f32_16x16x32_bf16 v[42:45], v[130:133], v[188:191], v[42:45]
	v_mfma_f32_16x16x32_bf16 v[34:37], v[138:141], v[188:191], v[34:37]
	v_mfma_f32_16x16x32_bf16 v[26:29], v[130:133], v[210:213], v[26:29]
	v_mfma_f32_16x16x32_bf16 v[18:21], v[138:141], v[210:213], v[18:21]
	v_mfma_f32_16x16x32_bf16 v[10:13], v[130:133], v[218:221], v[10:13]
	v_mfma_f32_16x16x32_bf16 v[2:5], v[138:141], v[218:221], v[2:5]
	v_mfma_f32_16x16x32_bf16 v[58:61], v[134:137], v[178:181], v[58:61]
	v_mfma_f32_16x16x32_bf16 v[50:53], v[142:145], v[178:181], v[50:53]
	v_mfma_f32_16x16x32_bf16 v[42:45], v[134:137], v[206:209], v[42:45]
	v_mfma_f32_16x16x32_bf16 v[34:37], v[142:145], v[206:209], v[34:37]
	v_mfma_f32_16x16x32_bf16 v[26:29], v[134:137], v[214:217], v[26:29]
	v_mfma_f32_16x16x32_bf16 v[18:21], v[142:145], v[214:217], v[18:21]
	v_mfma_f32_16x16x32_bf16 v[10:13], v[134:137], v[222:225], v[10:13]
	v_mfma_f32_16x16x32_bf16 v[2:5], v[142:145], v[222:225], v[2:5]
	v_mfma_f32_16x16x32_bf16 v[62:65], v[146:149], v[174:177], v[62:65]
	v_mfma_f32_16x16x32_bf16 v[54:57], v[166:169], v[174:177], v[54:57]
	v_mfma_f32_16x16x32_bf16 v[46:49], v[146:149], v[188:191], v[46:49]
	v_mfma_f32_16x16x32_bf16 v[38:41], v[166:169], v[188:191], v[38:41]
	v_mfma_f32_16x16x32_bf16 v[30:33], v[146:149], v[210:213], v[30:33]
	v_mfma_f32_16x16x32_bf16 v[22:25], v[166:169], v[210:213], v[22:25]
	v_mfma_f32_16x16x32_bf16 v[14:17], v[146:149], v[218:221], v[14:17]
	v_mfma_f32_16x16x32_bf16 v[6:9], v[166:169], v[218:221], v[6:9]
	v_mfma_f32_16x16x32_bf16 v[62:65], v[150:153], v[178:181], v[62:65]
	v_mfma_f32_16x16x32_bf16 v[54:57], v[170:173], v[178:181], v[54:57]
	v_mfma_f32_16x16x32_bf16 v[46:49], v[150:153], v[206:209], v[46:49]
	v_mfma_f32_16x16x32_bf16 v[38:41], v[170:173], v[206:209], v[38:41]
	v_mfma_f32_16x16x32_bf16 v[30:33], v[150:153], v[214:217], v[30:33]
	v_mfma_f32_16x16x32_bf16 v[22:25], v[170:173], v[214:217], v[22:25]
	v_mfma_f32_16x16x32_bf16 v[14:17], v[150:153], v[222:225], v[14:17]
	v_mfma_f32_16x16x32_bf16 v[6:9], v[170:173], v[222:225], v[6:9]
	s_barrier
	ds_read_b128 v[130:133], v239
	ds_read_b128 v[134:137], v239 offset:1024
	ds_read_b128 v[138:141], v239 offset:2048
	ds_read_b128 v[142:145], v239 offset:3072
	ds_read_b128 v[146:149], v250
	ds_read_b128 v[150:153], v250 offset:1024
	ds_read_b128 v[166:169], v250 offset:2048
	ds_read_b128 v[170:173], v250 offset:3072
	s_add_i32 s26, 0, 0x18000
	s_add_i32 s39, 0, 0x1c000
	s_add_u32 s28, s28, s56
	s_addc_u32 s29, s29, s57
	s_mov_b32 m0, s30
	v_lshl_add_u64 v[232:233], s[28:29], 0, v[158:159]
	ds_read_b128 v[174:177], v187 offset:32768
	ds_read_b128 v[178:181], v187 offset:33792
	ds_read_b128 v[188:191], v187 offset:34816
	ds_read_b128 v[206:209], v187 offset:35840
	ds_read_b128 v[210:213], v187 offset:36864
	ds_read_b128 v[214:217], v187 offset:37888
	ds_read_b128 v[218:221], v187 offset:38912
	ds_read_b128 v[222:225], v187 offset:39936
	global_load_lds_dwordx4 v[232:233], off
	s_mov_b32 m0, s31
	v_lshl_add_u64 v[232:233], s[28:29], 0, v[156:157]
	global_load_lds_dwordx4 v[232:233], off
	s_waitcnt vmcnt(8)
	s_waitcnt lgkmcnt(0)
	s_barrier
	s_waitcnt lgkmcnt(0)
	v_mfma_f32_16x16x32_bf16 v[122:125], v[130:133], v[174:177], v[122:125]
	v_mfma_f32_16x16x32_bf16 v[114:117], v[138:141], v[174:177], v[114:117]
	v_mfma_f32_16x16x32_bf16 v[106:109], v[130:133], v[188:191], v[106:109]
	v_mfma_f32_16x16x32_bf16 v[98:101], v[138:141], v[188:191], v[98:101]
	v_mfma_f32_16x16x32_bf16 v[90:93], v[130:133], v[210:213], v[90:93]
	v_mfma_f32_16x16x32_bf16 v[82:85], v[138:141], v[210:213], v[82:85]
	v_mfma_f32_16x16x32_bf16 v[74:77], v[130:133], v[218:221], v[74:77]
	v_mfma_f32_16x16x32_bf16 v[66:69], v[138:141], v[218:221], v[66:69]
	v_mfma_f32_16x16x32_bf16 v[122:125], v[134:137], v[178:181], v[122:125]
	v_mfma_f32_16x16x32_bf16 v[114:117], v[142:145], v[178:181], v[114:117]
	v_mfma_f32_16x16x32_bf16 v[106:109], v[134:137], v[206:209], v[106:109]
	v_mfma_f32_16x16x32_bf16 v[98:101], v[142:145], v[206:209], v[98:101]
	v_mfma_f32_16x16x32_bf16 v[90:93], v[134:137], v[214:217], v[90:93]
	v_mfma_f32_16x16x32_bf16 v[82:85], v[142:145], v[214:217], v[82:85]
	v_mfma_f32_16x16x32_bf16 v[74:77], v[134:137], v[222:225], v[74:77]
	v_mfma_f32_16x16x32_bf16 v[66:69], v[142:145], v[222:225], v[66:69]
	v_mfma_f32_16x16x32_bf16 v[126:129], v[146:149], v[174:177], v[126:129]
	v_mfma_f32_16x16x32_bf16 v[118:121], v[166:169], v[174:177], v[118:121]
	v_mfma_f32_16x16x32_bf16 v[110:113], v[146:149], v[188:191], v[110:113]
	v_mfma_f32_16x16x32_bf16 v[102:105], v[166:169], v[188:191], v[102:105]
	v_mfma_f32_16x16x32_bf16 v[94:97], v[146:149], v[210:213], v[94:97]
	v_mfma_f32_16x16x32_bf16 v[86:89], v[166:169], v[210:213], v[86:89]
	v_mfma_f32_16x16x32_bf16 v[78:81], v[146:149], v[218:221], v[78:81]
	v_mfma_f32_16x16x32_bf16 v[70:73], v[166:169], v[218:221], v[70:73]
	v_mfma_f32_16x16x32_bf16 v[126:129], v[150:153], v[178:181], v[126:129]
	v_mfma_f32_16x16x32_bf16 v[118:121], v[170:173], v[178:181], v[118:121]
	v_mfma_f32_16x16x32_bf16 v[110:113], v[150:153], v[206:209], v[110:113]
	v_mfma_f32_16x16x32_bf16 v[102:105], v[170:173], v[206:209], v[102:105]
	v_mfma_f32_16x16x32_bf16 v[94:97], v[150:153], v[214:217], v[94:97]
	v_mfma_f32_16x16x32_bf16 v[86:89], v[170:173], v[214:217], v[86:89]
	v_mfma_f32_16x16x32_bf16 v[78:81], v[150:153], v[222:225], v[78:81]
	v_mfma_f32_16x16x32_bf16 v[70:73], v[170:173], v[222:225], v[70:73]
	s_barrier
; #define PG8_STAGE(bufoff, gbase, voff) do { _Pragma("unroll") for (int _i = 0; _i < 2; ++_i) \
;         __builtin_amdgcn_global_load_lds((const unsigned*)((const char*)(gbase) + (voff)[_i]), (LAS unsigned*)(lds + (bufoff) + ldsw + _i * 8192), 16, 0, 0); } while (0)
; #define PG8_LDA(dst, b, h) do { _Pragma("unroll") for (int m = 0; m < 4; ++m) _Pragma("unroll") for (int k = 0; k < 2; ++k) dst[m][k] = *(const LAS bf16x8*)(lds + PG8_SA(b, h) + aoff + m * 2048 + k * 1024); } while (0)
; #define PG8_MMA(ai, bj, At, Bt) do { __builtin_amdgcn_s_setprio(1); _Pragma("unroll") for (int m = 0; m < 4; ++m) _Pragma("unroll") for (int n = 0; n < 2; ++n) _Pragma("unroll") for (int k = 0; k < 2; ++k) \
;         acc[ai][bj][m][n] = __builtin_amdgcn_mfma_f32_16x16x32_bf16(Bt[n][k], At[m][k], acc[ai][bj][m][n], 0, 0, 0); __builtin_amdgcn_s_setprio(0); } while (0)
; #define PG8_WAIT_V(n) asm volatile("s_waitcnt vmcnt(" #n ")" ::: "memory")
; #define PG8_WAIT_L(n) asm volatile("s_waitcnt lgkmcnt(" #n ")" ::: "memory")
; #define PG8_BAR __builtin_amdgcn_s_barrier()
; #define PG8_SCHED __builtin_amdgcn_sched_barrier(0)
; template <class Epi, class Sched>
; __device__ __forceinline__ void gemm_phase(LAS unsigned char* lds, const Gemm g, const Sched& S, const Epi& E) {
;     ...
;             PG8_LDA(At, 1, 1); PG8_STAGE(PG8_SB(1, 0), b3, voffB); PG8_STAGE(PG8_SB(1, 1), b3 + hstep, voffB); PG8_STAGE(PG8_SA(1, 0), a3, voffA);
;             PG8_WAIT_V(8); PG8_WAIT_L(0); PG8_BAR; PG8_MMA(1, 0, At, B0); PG8_MMA(1, 1, At, B1); PG8_BAR; PG8_SCHED;
;         }
	s_add_i32 s26, s26, s12
	v_lshl_add_u64 v[182:183], v[182:183], 0, s[18:19]
	s_mov_b32 m0, s26
	ds_read_b128 v[174:177], v187 offset:49152
	ds_read_b128 v[178:181], v187 offset:50176
	ds_read_b128 v[188:191], v187 offset:51200
	ds_read_b128 v[206:209], v187 offset:52224
	ds_read_b128 v[210:213], v187 offset:53248
	ds_read_b128 v[214:217], v187 offset:54272
	ds_read_b128 v[218:221], v187 offset:55296
	ds_read_b128 v[222:225], v187 offset:56320
	global_load_lds_dwordx4 v[182:183], off
	v_lshl_add_u64 v[182:183], v[192:193], 0, s[18:19]
	s_add_i32 m0, s26, 0x2000
	s_add_i32 s26, s39, s12
	global_load_lds_dwordx4 v[182:183], off
	s_mov_b32 m0, s26
	v_lshl_add_u64 v[182:183], v[202:203], 0, s[18:19]
	global_load_lds_dwordx4 v[182:183], off
	s_add_i32 m0, s26, 0x2000
	v_lshl_add_u64 v[182:183], v[226:227], 0, s[18:19]
	global_load_lds_dwordx4 v[182:183], off
	s_mov_b32 m0, s34
	v_lshl_add_u64 v[182:183], v[228:229], 0, s[18:19]
	global_load_lds_dwordx4 v[182:183], off
	s_mov_b32 m0, s35
	v_lshl_add_u64 v[182:183], v[230:231], 0, s[18:19]
	global_load_lds_dwordx4 v[182:183], off
	s_waitcnt vmcnt(8)
	s_waitcnt lgkmcnt(0)
	s_barrier
	s_waitcnt lgkmcnt(0)
	v_mfma_f32_16x16x32_bf16 v[58:61], v[130:133], v[174:177], v[58:61]
	v_mfma_f32_16x16x32_bf16 v[50:53], v[138:141], v[174:177], v[50:53]
	v_mfma_f32_16x16x32_bf16 v[42:45], v[130:133], v[188:191], v[42:45]
	v_mfma_f32_16x16x32_bf16 v[34:37], v[138:141], v[188:191], v[34:37]
	v_mfma_f32_16x16x32_bf16 v[26:29], v[130:133], v[210:213], v[26:29]
	v_mfma_f32_16x16x32_bf16 v[18:21], v[138:141], v[210:213], v[18:21]
	v_mfma_f32_16x16x32_bf16 v[10:13], v[130:133], v[218:221], v[10:13]
	v_mfma_f32_16x16x32_bf16 v[2:5], v[138:141], v[218:221], v[2:5]
	v_mfma_f32_16x16x32_bf16 v[58:61], v[134:137], v[178:181], v[58:61]
	v_mfma_f32_16x16x32_bf16 v[50:53], v[142:145], v[178:181], v[50:53]
	v_mfma_f32_16x16x32_bf16 v[42:45], v[134:137], v[206:209], v[42:45]
	v_mfma_f32_16x16x32_bf16 v[34:37], v[142:145], v[206:209], v[34:37]
	v_mfma_f32_16x16x32_bf16 v[26:29], v[134:137], v[214:217], v[26:29]
	v_mfma_f32_16x16x32_bf16 v[18:21], v[142:145], v[214:217], v[18:21]
	v_mfma_f32_16x16x32_bf16 v[10:13], v[134:137], v[222:225], v[10:13]
	v_mfma_f32_16x16x32_bf16 v[2:5], v[142:145], v[222:225], v[2:5]
	v_mfma_f32_16x16x32_bf16 v[62:65], v[146:149], v[174:177], v[62:65]
	v_mfma_f32_16x16x32_bf16 v[54:57], v[166:169], v[174:177], v[54:57]
	v_mfma_f32_16x16x32_bf16 v[46:49], v[146:149], v[188:191], v[46:49]
	v_mfma_f32_16x16x32_bf16 v[38:41], v[166:169], v[188:191], v[38:41]
	v_mfma_f32_16x16x32_bf16 v[30:33], v[146:149], v[210:213], v[30:33]
	v_mfma_f32_16x16x32_bf16 v[22:25], v[166:169], v[210:213], v[22:25]
	v_mfma_f32_16x16x32_bf16 v[14:17], v[146:149], v[218:221], v[14:17]
	v_mfma_f32_16x16x32_bf16 v[6:9], v[166:169], v[218:221], v[6:9]
	v_mfma_f32_16x16x32_bf16 v[62:65], v[150:153], v[178:181], v[62:65]
	v_mfma_f32_16x16x32_bf16 v[54:57], v[170:173], v[178:181], v[54:57]
	v_mfma_f32_16x16x32_bf16 v[46:49], v[150:153], v[206:209], v[46:49]
	v_mfma_f32_16x16x32_bf16 v[38:41], v[170:173], v[206:209], v[38:41]
	v_mfma_f32_16x16x32_bf16 v[30:33], v[150:153], v[214:217], v[30:33]
	v_mfma_f32_16x16x32_bf16 v[22:25], v[170:173], v[214:217], v[22:25]
	v_mfma_f32_16x16x32_bf16 v[14:17], v[150:153], v[222:225], v[14:17]
	v_mfma_f32_16x16x32_bf16 v[6:9], v[170:173], v[222:225], v[6:9]
	s_barrier
	s_add_u32 s15, s15, 0x100
	s_addc_u32 s16, s16, 0
	s_add_u32 s0, s0, 0x100
	s_addc_u32 s1, s1, 0
	s_cmp_ge_i32 s38, s80
	s_mov_b32 s28, s38
	s_cbranch_scc0 .LBB0_1908

; #define PG8_STAGE(bufoff, gbase, voff) do { _Pragma("unroll") for (int _i = 0; _i < 2; ++_i) \
;         __builtin_amdgcn_global_load_lds((const unsigned*)((const char*)(gbase) + (voff)[_i]), (LAS unsigned*)(lds + (bufoff) + ldsw + _i * 8192), 16, 0, 0); } while (0)
; #define PG8_LDA(dst, b, h) do { _Pragma("unroll") for (int m = 0; m < 4; ++m) _Pragma("unroll") for (int k = 0; k < 2; ++k) dst[m][k] = *(const LAS bf16x8*)(lds + PG8_SA(b, h) + aoff + m * 2048 + k * 1024); } while (0)
; #define PG8_LDB(dst, b, h) do { _Pragma("unroll") for (int n = 0; n < 2; ++n) _Pragma("unroll") for (int k = 0; k < 2; ++k) dst[n][k] = *(const LAS bf16x8*)(lds + PG8_SB(b, h) + boff + n * 2048 + k * 1024); } while (0)
; #define PG8_MMA(ai, bj, At, Bt) do { __builtin_amdgcn_s_setprio(1); _Pragma("unroll") for (int m = 0; m < 4; ++m) _Pragma("unroll") for (int n = 0; n < 2; ++n) _Pragma("unroll") for (int k = 0; k < 2; ++k) \
;         acc[ai][bj][m][n] = __builtin_amdgcn_mfma_f32_16x16x32_bf16(Bt[n][k], At[m][k], acc[ai][bj][m][n], 0, 0, 0); __builtin_amdgcn_s_setprio(0); } while (0)
; #define PG8_WAIT_V(n) asm volatile("s_waitcnt vmcnt(" #n ")" ::: "memory")
; #define PG8_WAIT_L(n) asm volatile("s_waitcnt lgkmcnt(" #n ")" ::: "memory")
; #define PG8_BAR __builtin_amdgcn_s_barrier()
; #define PG8_SCHED __builtin_amdgcn_sched_barrier(0)
; template <class Epi, class Sched>
; __device__ __forceinline__ void gemm_phase(LAS unsigned char* lds, const Gemm g, const Sched& S, const Epi& E) {
;     ...
;         for (int t = 0; t < nt; t += 2) {
;             const bool last = (t == nt - 2);
;             const char* a1 = cA + (size_t)(t + 1) * kstep;
;             const char* a2 = last ? nA : cA + (size_t)(t + 2) * kstep; const char* b2 = last ? nB : cB + (size_t)(t + 2) * kstep;
;             const char* a3 = a2 + kstep; const char* b3 = b2 + kstep;
;             PG8_LDB(B0, 0, 0); PG8_LDB(B1, 0, 1); PG8_SCHED; PG8_LDA(At, 0, 0); PG8_STAGE(PG8_SA(1, 1), a1 + hstep, voffA);
;             PG8_WAIT_V(8); PG8_WAIT_L(0); PG8_BAR; PG8_MMA(0, 0, At, B0); PG8_MMA(0, 1, At, B1); PG8_BAR; PG8_SCHED;
;             PG8_LDA(At, 0, 1); PG8_STAGE(PG8_SB(0, 0), b2, voffB); PG8_STAGE(PG8_SB(0, 1), b2 + hstep, voffB); PG8_STAGE(PG8_SA(0, 0), a2, voffA);
.LBB0_2026:
	ds_read_b128 v[140:143], v235
	ds_read_b128 v[144:147], v235 offset:1024
	ds_read_b128 v[148:151], v235 offset:2048
	ds_read_b128 v[152:155], v235 offset:3072
	ds_read_b128 v[156:159], v238
	ds_read_b128 v[160:163], v238 offset:1024
	ds_read_b128 v[164:167], v238 offset:2048
	ds_read_b128 v[168:171], v238 offset:3072
	ds_read_b128 v[172:175], v219
	ds_read_b128 v[176:179], v219 offset:1024
	ds_read_b128 v[180:183], v219 offset:2048
	ds_read_b128 v[184:187], v219 offset:3072
	ds_read_b128 v[188:191], v219 offset:4096
	ds_read_b128 v[206:209], v219 offset:5120
	ds_read_b128 v[210:213], v219 offset:6144
	ds_read_b128 v[220:223], v219 offset:7168
	s_add_i32 s64, s28, 2
	s_add_u32 s26, s0, 0x80
	s_addc_u32 s29, s1, 0
	s_add_i32 s65, 0, 0x10000
	s_cmp_eq_u32 s84, s28
	s_cselect_b32 s29, s45, s29
	s_cselect_b32 s28, s44, s26
	s_cselect_b32 s91, s63, s16
	s_cselect_b32 s90, s62, s15
	s_add_i32 s26, 0, 0x14000
	s_add_i32 m0, s13, 0xc000
	v_lshl_add_u64 v[192:193], s[0:1], 0, v[138:139]
	global_load_lds_dwordx4 v[192:193], off
	s_add_i32 m0, s13, 0xe000
	v_lshl_add_u64 v[192:193], s[0:1], 0, v[136:137]
	global_load_lds_dwordx4 v[192:193], off
	s_waitcnt vmcnt(8)
	s_waitcnt lgkmcnt(0)
	s_barrier
	s_waitcnt lgkmcnt(0)
	v_mfma_f32_16x16x32_bf16 v[126:129], v[140:143], v[172:175], v[126:129]
	v_mfma_f32_16x16x32_bf16 v[122:125], v[148:151], v[172:175], v[122:125]
	v_mfma_f32_16x16x32_bf16 v[118:121], v[140:143], v[180:183], v[118:121]
	v_mfma_f32_16x16x32_bf16 v[114:117], v[148:151], v[180:183], v[114:117]
	v_mfma_f32_16x16x32_bf16 v[106:109], v[140:143], v[188:191], v[106:109]
	v_mfma_f32_16x16x32_bf16 v[98:101], v[148:151], v[188:191], v[98:101]
	v_mfma_f32_16x16x32_bf16 v[90:93], v[140:143], v[210:213], v[90:93]
	v_mfma_f32_16x16x32_bf16 v[82:85], v[148:151], v[210:213], v[82:85]
	v_mfma_f32_16x16x32_bf16 v[126:129], v[144:147], v[176:179], v[126:129]
	v_mfma_f32_16x16x32_bf16 v[122:125], v[152:155], v[176:179], v[122:125]
	v_mfma_f32_16x16x32_bf16 v[118:121], v[144:147], v[184:187], v[118:121]
	v_mfma_f32_16x16x32_bf16 v[114:117], v[152:155], v[184:187], v[114:117]
	v_mfma_f32_16x16x32_bf16 v[106:109], v[144:147], v[206:209], v[106:109]
	v_mfma_f32_16x16x32_bf16 v[98:101], v[152:155], v[206:209], v[98:101]
	v_mfma_f32_16x16x32_bf16 v[90:93], v[144:147], v[220:223], v[90:93]
	v_mfma_f32_16x16x32_bf16 v[82:85], v[152:155], v[220:223], v[82:85]
	v_mfma_f32_16x16x32_bf16 v[110:113], v[156:159], v[172:175], v[110:113]
	v_mfma_f32_16x16x32_bf16 v[102:105], v[164:167], v[172:175], v[102:105]
	v_mfma_f32_16x16x32_bf16 v[94:97], v[156:159], v[180:183], v[94:97]
	v_mfma_f32_16x16x32_bf16 v[86:89], v[164:167], v[180:183], v[86:89]
	v_mfma_f32_16x16x32_bf16 v[78:81], v[156:159], v[188:191], v[78:81]
	v_mfma_f32_16x16x32_bf16 v[74:77], v[164:167], v[188:191], v[74:77]
	v_mfma_f32_16x16x32_bf16 v[70:73], v[156:159], v[210:213], v[70:73]
	v_mfma_f32_16x16x32_bf16 v[66:69], v[164:167], v[210:213], v[66:69]
	v_mfma_f32_16x16x32_bf16 v[110:113], v[160:163], v[176:179], v[110:113]
	v_mfma_f32_16x16x32_bf16 v[102:105], v[168:171], v[176:179], v[102:105]
	v_mfma_f32_16x16x32_bf16 v[94:97], v[160:163], v[184:187], v[94:97]
	v_mfma_f32_16x16x32_bf16 v[86:89], v[168:171], v[184:187], v[86:89]
	v_mfma_f32_16x16x32_bf16 v[78:81], v[160:163], v[206:209], v[78:81]
	v_mfma_f32_16x16x32_bf16 v[74:77], v[168:171], v[206:209], v[74:77]
	v_mfma_f32_16x16x32_bf16 v[70:73], v[160:163], v[220:223], v[70:73]
	v_mfma_f32_16x16x32_bf16 v[66:69], v[168:171], v[220:223], v[66:69]
	s_barrier
	s_add_i32 s65, s65, s12
	v_lshl_add_u64 v[192:193], s[90:91], 0, v[0:1]
	s_mov_b32 m0, s65
	ds_read_b128 v[172:175], v219 offset:16384
	ds_read_b128 v[176:179], v219 offset:17408
	ds_read_b128 v[180:183], v219 offset:18432
	ds_read_b128 v[184:187], v219 offset:19456
	ds_read_b128 v[188:191], v219 offset:20480
	ds_read_b128 v[206:209], v219 offset:21504
	ds_read_b128 v[210:213], v219 offset:22528
	ds_read_b128 v[220:223], v219 offset:23552
	global_load_lds_dwordx4 v[192:193], off
	s_add_i32 m0, s65, 0x2000
	v_lshl_add_u64 v[202:203], s[90:91], 0, v[130:131]
	s_add_u32 s90, s90, s48
	s_addc_u32 s91, s91, s49
	s_add_i32 s26, s26, s12
	global_load_lds_dwordx4 v[202:203], off
	v_lshl_add_u64 v[214:215], s[90:91], 0, v[0:1]
	s_mov_b32 m0, s26
	v_lshl_add_u64 v[224:225], s[90:91], 0, v[130:131]
	global_load_lds_dwordx4 v[214:215], off
	s_add_i32 m0, s26, 0x2000
	v_lshl_add_u64 v[226:227], s[28:29], 0, v[134:135]
	global_load_lds_dwordx4 v[224:225], off
	s_mov_b32 m0, s13
	v_lshl_add_u64 v[228:229], s[28:29], 0, v[132:133]
	global_load_lds_dwordx4 v[226:227], off
	s_mov_b32 m0, s27
	s_nop 0
	global_load_lds_dwordx4 v[228:229], off
	s_waitcnt vmcnt(8)
	s_waitcnt lgkmcnt(0)
	s_barrier
; #define PG8_STAGE(bufoff, gbase, voff) do { _Pragma("unroll") for (int _i = 0; _i < 2; ++_i) \
;         __builtin_amdgcn_global_load_lds((const unsigned*)((const char*)(gbase) + (voff)[_i]), (LAS unsigned*)(lds + (bufoff) + ldsw + _i * 8192), 16, 0, 0); } while (0)
; #define PG8_LDA(dst, b, h) do { _Pragma("unroll") for (int m = 0; m < 4; ++m) _Pragma("unroll") for (int k = 0; k < 2; ++k) dst[m][k] = *(const LAS bf16x8*)(lds + PG8_SA(b, h) + aoff + m * 2048 + k * 1024); } while (0)
; #define PG8_LDB(dst, b, h) do { _Pragma("unroll") for (int n = 0; n < 2; ++n) _Pragma("unroll") for (int k = 0; k < 2; ++k) dst[n][k] = *(const LAS bf16x8*)(lds + PG8_SB(b, h) + boff + n * 2048 + k * 1024); } while (0)
; #define PG8_MMA(ai, bj, At, Bt) do { __builtin_amdgcn_s_setprio(1); _Pragma("unroll") for (int m = 0; m < 4; ++m) _Pragma("unroll") for (int n = 0; n < 2; ++n) _Pragma("unroll") for (int k = 0; k < 2; ++k) \
;         acc[ai][bj][m][n] = __builtin_amdgcn_mfma_f32_16x16x32_bf16(Bt[n][k], At[m][k], acc[ai][bj][m][n], 0, 0, 0); __builtin_amdgcn_s_setprio(0); } while (0)
; #define PG8_WAIT_V(n) asm volatile("s_waitcnt vmcnt(" #n ")" ::: "memory")
; #define PG8_WAIT_L(n) asm volatile("s_waitcnt lgkmcnt(" #n ")" ::: "memory")
; #define PG8_BAR __builtin_amdgcn_s_barrier()
; #define PG8_SCHED __builtin_amdgcn_sched_barrier(0)
; template <class Epi, class Sched>
; __device__ __forceinline__ void gemm_phase(LAS unsigned char* lds, const Gemm g, const Sched& S, const Epi& E) {
;     ...
;             PG8_WAIT_V(8); PG8_WAIT_L(0); PG8_BAR; PG8_MMA(1, 0, At, B0); PG8_MMA(1, 1, At, B1); PG8_BAR; PG8_SCHED;
;             PG8_LDB(B0, 1, 0); PG8_LDB(B1, 1, 1); PG8_SCHED; PG8_LDA(At, 1, 0); PG8_STAGE(PG8_SA(0, 1), a2 + hstep, voffA);
;             PG8_WAIT_V(8); PG8_WAIT_L(0); PG8_BAR; PG8_MMA(0, 0, At, B0); PG8_MMA(0, 1, At, B1); PG8_BAR; PG8_SCHED;
	s_waitcnt lgkmcnt(0)
	v_mfma_f32_16x16x32_bf16 v[62:65], v[140:143], v[172:175], v[62:65]
	v_mfma_f32_16x16x32_bf16 v[58:61], v[148:151], v[172:175], v[58:61]
	v_mfma_f32_16x16x32_bf16 v[54:57], v[140:143], v[180:183], v[54:57]
	v_mfma_f32_16x16x32_bf16 v[50:53], v[148:151], v[180:183], v[50:53]
	v_mfma_f32_16x16x32_bf16 v[42:45], v[140:143], v[188:191], v[42:45]
	v_mfma_f32_16x16x32_bf16 v[34:37], v[148:151], v[188:191], v[34:37]
	v_mfma_f32_16x16x32_bf16 v[26:29], v[140:143], v[210:213], v[26:29]
	v_mfma_f32_16x16x32_bf16 v[18:21], v[148:151], v[210:213], v[18:21]
	v_mfma_f32_16x16x32_bf16 v[62:65], v[144:147], v[176:179], v[62:65]
	v_mfma_f32_16x16x32_bf16 v[58:61], v[152:155], v[176:179], v[58:61]
	v_mfma_f32_16x16x32_bf16 v[54:57], v[144:147], v[184:187], v[54:57]
	v_mfma_f32_16x16x32_bf16 v[50:53], v[152:155], v[184:187], v[50:53]
	v_mfma_f32_16x16x32_bf16 v[42:45], v[144:147], v[206:209], v[42:45]
	v_mfma_f32_16x16x32_bf16 v[34:37], v[152:155], v[206:209], v[34:37]
	v_mfma_f32_16x16x32_bf16 v[26:29], v[144:147], v[220:223], v[26:29]
	v_mfma_f32_16x16x32_bf16 v[18:21], v[152:155], v[220:223], v[18:21]
	v_mfma_f32_16x16x32_bf16 v[46:49], v[156:159], v[172:175], v[46:49]
	v_mfma_f32_16x16x32_bf16 v[38:41], v[164:167], v[172:175], v[38:41]
	v_mfma_f32_16x16x32_bf16 v[30:33], v[156:159], v[180:183], v[30:33]
	v_mfma_f32_16x16x32_bf16 v[22:25], v[164:167], v[180:183], v[22:25]
	v_mfma_f32_16x16x32_bf16 v[14:17], v[156:159], v[188:191], v[14:17]
	v_mfma_f32_16x16x32_bf16 v[10:13], v[164:167], v[188:191], v[10:13]
	v_mfma_f32_16x16x32_bf16 v[6:9], v[156:159], v[210:213], v[6:9]
	v_mfma_f32_16x16x32_bf16 v[2:5], v[164:167], v[210:213], v[2:5]
	v_mfma_f32_16x16x32_bf16 v[46:49], v[160:163], v[176:179], v[46:49]
	v_mfma_f32_16x16x32_bf16 v[38:41], v[168:171], v[176:179], v[38:41]
	v_mfma_f32_16x16x32_bf16 v[30:33], v[160:163], v[184:187], v[30:33]
	v_mfma_f32_16x16x32_bf16 v[22:25], v[168:171], v[184:187], v[22:25]
	v_mfma_f32_16x16x32_bf16 v[14:17], v[160:163], v[206:209], v[14:17]
	v_mfma_f32_16x16x32_bf16 v[10:13], v[168:171], v[206:209], v[10:13]
	v_mfma_f32_16x16x32_bf16 v[6:9], v[160:163], v[220:223], v[6:9]
	v_mfma_f32_16x16x32_bf16 v[2:5], v[168:171], v[220:223], v[2:5]
	s_barrier
	ds_read_b128 v[140:143], v239
	ds_read_b128 v[144:147], v239 offset:1024
	ds_read_b128 v[148:151], v239 offset:2048
	ds_read_b128 v[152:155], v239 offset:3072
	ds_read_b128 v[156:159], v250
	ds_read_b128 v[160:163], v250 offset:1024
	ds_read_b128 v[164:167], v250 offset:2048
	ds_read_b128 v[168:171], v250 offset:3072
	s_add_i32 s26, 0, 0x18000
	s_add_i32 s65, 0, 0x1c000
	s_add_u32 s28, s28, s48
	s_addc_u32 s29, s29, s49
	s_mov_b32 m0, s34
	v_lshl_add_u64 v[230:231], s[28:29], 0, v[134:135]
	ds_read_b128 v[172:175], v219 offset:32768
	ds_read_b128 v[176:179], v219 offset:33792
	ds_read_b128 v[180:183], v219 offset:34816
	ds_read_b128 v[184:187], v219 offset:35840
	ds_read_b128 v[188:191], v219 offset:36864
	ds_read_b128 v[206:209], v219 offset:37888
	ds_read_b128 v[210:213], v219 offset:38912
	ds_read_b128 v[220:223], v219 offset:39936
	global_load_lds_dwordx4 v[230:231], off
	s_mov_b32 m0, s35
	v_lshl_add_u64 v[230:231], s[28:29], 0, v[132:133]
	global_load_lds_dwordx4 v[230:231], off
	s_waitcnt vmcnt(8)
	s_waitcnt lgkmcnt(0)
	s_barrier
	s_waitcnt lgkmcnt(0)
	v_mfma_f32_16x16x32_bf16 v[126:129], v[140:143], v[172:175], v[126:129]
	v_mfma_f32_16x16x32_bf16 v[122:125], v[148:151], v[172:175], v[122:125]
	v_mfma_f32_16x16x32_bf16 v[118:121], v[140:143], v[180:183], v[118:121]
	v_mfma_f32_16x16x32_bf16 v[114:117], v[148:151], v[180:183], v[114:117]
	v_mfma_f32_16x16x32_bf16 v[106:109], v[140:143], v[188:191], v[106:109]
	v_mfma_f32_16x16x32_bf16 v[98:101], v[148:151], v[188:191], v[98:101]
	v_mfma_f32_16x16x32_bf16 v[90:93], v[140:143], v[210:213], v[90:93]
	v_mfma_f32_16x16x32_bf16 v[82:85], v[148:151], v[210:213], v[82:85]
	v_mfma_f32_16x16x32_bf16 v[126:129], v[144:147], v[176:179], v[126:129]
	v_mfma_f32_16x16x32_bf16 v[122:125], v[152:155], v[176:179], v[122:125]
	v_mfma_f32_16x16x32_bf16 v[118:121], v[144:147], v[184:187], v[118:121]
	v_mfma_f32_16x16x32_bf16 v[114:117], v[152:155], v[184:187], v[114:117]
	v_mfma_f32_16x16x32_bf16 v[106:109], v[144:147], v[206:209], v[106:109]
	v_mfma_f32_16x16x32_bf16 v[98:101], v[152:155], v[206:209], v[98:101]
	v_mfma_f32_16x16x32_bf16 v[90:93], v[144:147], v[220:223], v[90:93]
	v_mfma_f32_16x16x32_bf16 v[82:85], v[152:155], v[220:223], v[82:85]
	v_mfma_f32_16x16x32_bf16 v[110:113], v[156:159], v[172:175], v[110:113]
	v_mfma_f32_16x16x32_bf16 v[102:105], v[164:167], v[172:175], v[102:105]
	v_mfma_f32_16x16x32_bf16 v[94:97], v[156:159], v[180:183], v[94:97]
	v_mfma_f32_16x16x32_bf16 v[86:89], v[164:167], v[180:183], v[86:89]
	v_mfma_f32_16x16x32_bf16 v[78:81], v[156:159], v[188:191], v[78:81]
	v_mfma_f32_16x16x32_bf16 v[74:77], v[164:167], v[188:191], v[74:77]
	v_mfma_f32_16x16x32_bf16 v[70:73], v[156:159], v[210:213], v[70:73]
	v_mfma_f32_16x16x32_bf16 v[66:69], v[164:167], v[210:213], v[66:69]
	v_mfma_f32_16x16x32_bf16 v[110:113], v[160:163], v[176:179], v[110:113]
	v_mfma_f32_16x16x32_bf16 v[102:105], v[168:171], v[176:179], v[102:105]
	v_mfma_f32_16x16x32_bf16 v[94:97], v[160:163], v[184:187], v[94:97]
	v_mfma_f32_16x16x32_bf16 v[86:89], v[168:171], v[184:187], v[86:89]
	v_mfma_f32_16x16x32_bf16 v[78:81], v[160:163], v[206:209], v[78:81]
	v_mfma_f32_16x16x32_bf16 v[74:77], v[168:171], v[206:209], v[74:77]
	v_mfma_f32_16x16x32_bf16 v[70:73], v[160:163], v[220:223], v[70:73]
	v_mfma_f32_16x16x32_bf16 v[66:69], v[168:171], v[220:223], v[66:69]
	s_barrier
; #define PG8_STAGE(bufoff, gbase, voff) do { _Pragma("unroll") for (int _i = 0; _i < 2; ++_i) \
;         __builtin_amdgcn_global_load_lds((const unsigned*)((const char*)(gbase) + (voff)[_i]), (LAS unsigned*)(lds + (bufoff) + ldsw + _i * 8192), 16, 0, 0); } while (0)
; #define PG8_LDA(dst, b, h) do { _Pragma("unroll") for (int m = 0; m < 4; ++m) _Pragma("unroll") for (int k = 0; k < 2; ++k) dst[m][k] = *(const LAS bf16x8*)(lds + PG8_SA(b, h) + aoff + m * 2048 + k * 1024); } while (0)
; #define PG8_MMA(ai, bj, At, Bt) do { __builtin_amdgcn_s_setprio(1); _Pragma("unroll") for (int m = 0; m < 4; ++m) _Pragma("unroll") for (int n = 0; n < 2; ++n) _Pragma("unroll") for (int k = 0; k < 2; ++k) \
;         acc[ai][bj][m][n] = __builtin_amdgcn_mfma_f32_16x16x32_bf16(Bt[n][k], At[m][k], acc[ai][bj][m][n], 0, 0, 0); __builtin_amdgcn_s_setprio(0); } while (0)
; #define PG8_WAIT_V(n) asm volatile("s_waitcnt vmcnt(" #n ")" ::: "memory")
; #define PG8_WAIT_L(n) asm volatile("s_waitcnt lgkmcnt(" #n ")" ::: "memory")
; #define PG8_BAR __builtin_amdgcn_s_barrier()
; #define PG8_SCHED __builtin_amdgcn_sched_barrier(0)
; template <class Epi, class Sched>
; __device__ __forceinline__ void gemm_phase(LAS unsigned char* lds, const Gemm g, const Sched& S, const Epi& E) {
;     ...
;             PG8_LDA(At, 1, 1); PG8_STAGE(PG8_SB(1, 0), b3, voffB); PG8_STAGE(PG8_SB(1, 1), b3 + hstep, voffB); PG8_STAGE(PG8_SA(1, 0), a3, voffA);
;             PG8_WAIT_V(8); PG8_WAIT_L(0); PG8_BAR; PG8_MMA(1, 0, At, B0); PG8_MMA(1, 1, At, B1); PG8_BAR; PG8_SCHED;
;         }
	s_add_i32 s26, s26, s12
	v_lshl_add_u64 v[192:193], v[192:193], 0, s[18:19]
	s_mov_b32 m0, s26
	ds_read_b128 v[172:175], v219 offset:49152
	ds_read_b128 v[176:179], v219 offset:50176
	ds_read_b128 v[180:183], v219 offset:51200
	ds_read_b128 v[184:187], v219 offset:52224
	ds_read_b128 v[188:191], v219 offset:53248
	ds_read_b128 v[206:209], v219 offset:54272
	ds_read_b128 v[210:213], v219 offset:55296
	ds_read_b128 v[220:223], v219 offset:56320
	global_load_lds_dwordx4 v[192:193], off
	v_lshl_add_u64 v[192:193], v[202:203], 0, s[18:19]
	s_add_i32 m0, s26, 0x2000
	s_add_i32 s26, s65, s12
	global_load_lds_dwordx4 v[192:193], off
	s_mov_b32 m0, s26
	v_lshl_add_u64 v[192:193], v[214:215], 0, s[18:19]
	global_load_lds_dwordx4 v[192:193], off
	s_add_i32 m0, s26, 0x2000
	v_lshl_add_u64 v[192:193], v[224:225], 0, s[18:19]
	global_load_lds_dwordx4 v[192:193], off
	s_mov_b32 m0, s66
	v_lshl_add_u64 v[192:193], v[226:227], 0, s[18:19]
	global_load_lds_dwordx4 v[192:193], off
	s_mov_b32 m0, s67
	v_lshl_add_u64 v[192:193], v[228:229], 0, s[18:19]
	global_load_lds_dwordx4 v[192:193], off
	s_waitcnt vmcnt(8)
	s_waitcnt lgkmcnt(0)
	s_barrier
	s_waitcnt lgkmcnt(0)
	v_mfma_f32_16x16x32_bf16 v[62:65], v[140:143], v[172:175], v[62:65]
	v_mfma_f32_16x16x32_bf16 v[58:61], v[148:151], v[172:175], v[58:61]
	v_mfma_f32_16x16x32_bf16 v[54:57], v[140:143], v[180:183], v[54:57]
	v_mfma_f32_16x16x32_bf16 v[50:53], v[148:151], v[180:183], v[50:53]
	v_mfma_f32_16x16x32_bf16 v[42:45], v[140:143], v[188:191], v[42:45]
	v_mfma_f32_16x16x32_bf16 v[34:37], v[148:151], v[188:191], v[34:37]
	v_mfma_f32_16x16x32_bf16 v[26:29], v[140:143], v[210:213], v[26:29]
	v_mfma_f32_16x16x32_bf16 v[18:21], v[148:151], v[210:213], v[18:21]
	v_mfma_f32_16x16x32_bf16 v[62:65], v[144:147], v[176:179], v[62:65]
	v_mfma_f32_16x16x32_bf16 v[58:61], v[152:155], v[176:179], v[58:61]
	v_mfma_f32_16x16x32_bf16 v[54:57], v[144:147], v[184:187], v[54:57]
	v_mfma_f32_16x16x32_bf16 v[50:53], v[152:155], v[184:187], v[50:53]
	v_mfma_f32_16x16x32_bf16 v[42:45], v[144:147], v[206:209], v[42:45]
	v_mfma_f32_16x16x32_bf16 v[34:37], v[152:155], v[206:209], v[34:37]
	v_mfma_f32_16x16x32_bf16 v[26:29], v[144:147], v[220:223], v[26:29]
	v_mfma_f32_16x16x32_bf16 v[18:21], v[152:155], v[220:223], v[18:21]
	v_mfma_f32_16x16x32_bf16 v[46:49], v[156:159], v[172:175], v[46:49]
	v_mfma_f32_16x16x32_bf16 v[38:41], v[164:167], v[172:175], v[38:41]
	v_mfma_f32_16x16x32_bf16 v[30:33], v[156:159], v[180:183], v[30:33]
	v_mfma_f32_16x16x32_bf16 v[22:25], v[164:167], v[180:183], v[22:25]
	v_mfma_f32_16x16x32_bf16 v[14:17], v[156:159], v[188:191], v[14:17]
	v_mfma_f32_16x16x32_bf16 v[10:13], v[164:167], v[188:191], v[10:13]
	v_mfma_f32_16x16x32_bf16 v[6:9], v[156:159], v[210:213], v[6:9]
	v_mfma_f32_16x16x32_bf16 v[2:5], v[164:167], v[210:213], v[2:5]
	v_mfma_f32_16x16x32_bf16 v[46:49], v[160:163], v[176:179], v[46:49]
	v_mfma_f32_16x16x32_bf16 v[38:41], v[168:171], v[176:179], v[38:41]
	v_mfma_f32_16x16x32_bf16 v[30:33], v[160:163], v[184:187], v[30:33]
	v_mfma_f32_16x16x32_bf16 v[22:25], v[168:171], v[184:187], v[22:25]
	v_mfma_f32_16x16x32_bf16 v[14:17], v[160:163], v[206:209], v[14:17]
	v_mfma_f32_16x16x32_bf16 v[10:13], v[168:171], v[206:209], v[10:13]
	v_mfma_f32_16x16x32_bf16 v[6:9], v[160:163], v[220:223], v[6:9]
	v_mfma_f32_16x16x32_bf16 v[2:5], v[168:171], v[220:223], v[2:5]
	s_barrier
	s_add_u32 s15, s15, 0x100
	s_addc_u32 s16, s16, 0
	s_add_u32 s0, s0, 0x100
	s_addc_u32 s1, s1, 0
	s_cmp_ge_i32 s64, s31
	s_mov_b32 s28, s64
	s_cbranch_scc0 .LBB0_2026
; #define PG8_BAR __builtin_amdgcn_s_barrier()
; template <class Epi, class Sched>
; __device__ __forceinline__ void gemm_phase(LAS unsigned char* lds, const Gemm g, const Sched& S, const Epi& E) {
;     ...
;         if (wr == 0) PG8_BAR;
;         E(acc, cur, wr, wc, fr, fq);
;     __device__ __forceinline__ void operator()(const AccT& acc, const Unit& u, int wr, int wc, int fr, int fq) const {
;     ...
;                     v0 = v0 + acc[ai][bj][m][0] * c; v1 = v1 + acc[ai][bj][m][1] * c;
	v_readlane_b32 s90, v255, 43
	v_pk_mul_f32 v[208:209], v[128:129], 0.5 op_sel_hi:[1,0]
	v_pk_mul_f32 v[210:211], v[126:127], 0.5 op_sel_hi:[1,0]
	v_pk_mul_f32 v[212:213], v[124:125], 0.5 op_sel_hi:[1,0]
	v_pk_mul_f32 v[214:215], v[122:123], 0.5 op_sel_hi:[1,0]
	v_pk_mul_f32 v[192:193], v[112:113], 0.5 op_sel_hi:[1,0]
	v_pk_mul_f32 v[190:191], v[110:111], 0.5 op_sel_hi:[1,0]
	v_pk_mul_f32 v[188:189], v[104:105], 0.5 op_sel_hi:[1,0]
	v_pk_mul_f32 v[186:187], v[102:103], 0.5 op_sel_hi:[1,0]
	v_pk_mul_f32 v[184:185], v[120:121], 0.5 op_sel_hi:[1,0]
	v_pk_mul_f32 v[182:183], v[118:119], 0.5 op_sel_hi:[1,0]
	v_pk_mul_f32 v[180:181], v[116:117], 0.5 op_sel_hi:[1,0]
	v_pk_mul_f32 v[178:179], v[114:115], 0.5 op_sel_hi:[1,0]
	v_pk_mul_f32 v[176:177], v[96:97], 0.5 op_sel_hi:[1,0]
	v_pk_mul_f32 v[174:175], v[94:95], 0.5 op_sel_hi:[1,0]
	v_pk_mul_f32 v[172:173], v[88:89], 0.5 op_sel_hi:[1,0]
	v_pk_mul_f32 v[170:171], v[86:87], 0.5 op_sel_hi:[1,0]
	v_pk_mul_f32 v[168:169], v[108:109], 0.5 op_sel_hi:[1,0]
	v_pk_mul_f32 v[166:167], v[106:107], 0.5 op_sel_hi:[1,0]
	v_pk_mul_f32 v[164:165], v[100:101], 0.5 op_sel_hi:[1,0]
	v_pk_mul_f32 v[162:163], v[98:99], 0.5 op_sel_hi:[1,0]
	v_pk_mul_f32 v[160:161], v[80:81], 0.5 op_sel_hi:[1,0]
	v_pk_mul_f32 v[158:159], v[78:79], 0.5 op_sel_hi:[1,0]
	v_pk_mul_f32 v[156:157], v[76:77], 0.5 op_sel_hi:[1,0]
	v_pk_mul_f32 v[154:155], v[74:75], 0.5 op_sel_hi:[1,0]
	v_pk_mul_f32 v[150:151], v[92:93], 0.5 op_sel_hi:[1,0]
	v_pk_mul_f32 v[148:149], v[90:91], 0.5 op_sel_hi:[1,0]
	v_pk_mul_f32 v[146:147], v[84:85], 0.5 op_sel_hi:[1,0]
	v_pk_mul_f32 v[144:145], v[82:83], 0.5 op_sel_hi:[1,0]
	v_pk_mul_f32 v[142:143], v[72:73], 0.5 op_sel_hi:[1,0]
	v_pk_mul_f32 v[140:141], v[70:71], 0.5 op_sel_hi:[1,0]
	v_pk_mul_f32 v[128:129], v[68:69], 0.5 op_sel_hi:[1,0]
	v_pk_mul_f32 v[126:127], v[66:67], 0.5 op_sel_hi:[1,0]
	v_pk_mul_f32 v[124:125], v[64:65], 0.5 op_sel_hi:[1,0]
	v_pk_mul_f32 v[122:123], v[62:63], 0.5 op_sel_hi:[1,0]
	v_pk_mul_f32 v[120:121], v[60:61], 0.5 op_sel_hi:[1,0]
	v_pk_mul_f32 v[118:119], v[58:59], 0.5 op_sel_hi:[1,0]
	v_pk_mul_f32 v[116:117], v[48:49], 0.5 op_sel_hi:[1,0]
	v_pk_mul_f32 v[114:115], v[46:47], 0.5 op_sel_hi:[1,0]
	v_pk_mul_f32 v[112:113], v[40:41], 0.5 op_sel_hi:[1,0]
	v_pk_mul_f32 v[110:111], v[38:39], 0.5 op_sel_hi:[1,0]
	v_pk_mul_f32 v[108:109], v[56:57], 0.5 op_sel_hi:[1,0]
	v_pk_mul_f32 v[106:107], v[54:55], 0.5 op_sel_hi:[1,0]
	v_pk_mul_f32 v[104:105], v[52:53], 0.5 op_sel_hi:[1,0]
	v_pk_mul_f32 v[102:103], v[50:51], 0.5 op_sel_hi:[1,0]
	v_pk_mul_f32 v[100:101], v[32:33], 0.5 op_sel_hi:[1,0]
	v_pk_mul_f32 v[98:99], v[30:31], 0.5 op_sel_hi:[1,0]
	v_pk_mul_f32 v[96:97], v[24:25], 0.5 op_sel_hi:[1,0]
	v_pk_mul_f32 v[94:95], v[22:23], 0.5 op_sel_hi:[1,0]
	v_pk_mul_f32 v[92:93], v[44:45], 0.5 op_sel_hi:[1,0]
	v_pk_mul_f32 v[90:91], v[42:43], 0.5 op_sel_hi:[1,0]
	v_pk_mul_f32 v[88:89], v[36:37], 0.5 op_sel_hi:[1,0]
	v_pk_mul_f32 v[86:87], v[34:35], 0.5 op_sel_hi:[1,0]
	v_pk_mul_f32 v[84:85], v[16:17], 0.5 op_sel_hi:[1,0]
	v_pk_mul_f32 v[82:83], v[14:15], 0.5 op_sel_hi:[1,0]
	v_pk_mul_f32 v[80:81], v[12:13], 0.5 op_sel_hi:[1,0]
	v_pk_mul_f32 v[78:79], v[10:11], 0.5 op_sel_hi:[1,0]
	v_pk_mul_f32 v[76:77], v[28:29], 0.5 op_sel_hi:[1,0]
	v_pk_mul_f32 v[74:75], v[26:27], 0.5 op_sel_hi:[1,0]
	v_pk_mul_f32 v[72:73], v[20:21], 0.5 op_sel_hi:[1,0]
	v_pk_mul_f32 v[70:71], v[18:19], 0.5 op_sel_hi:[1,0]
	v_pk_mul_f32 v[68:69], v[8:9], 0.5 op_sel_hi:[1,0]
	v_pk_mul_f32 v[66:67], v[6:7], 0.5 op_sel_hi:[1,0]
	v_pk_mul_f32 v[64:65], v[4:5], 0.5 op_sel_hi:[1,0]
	v_pk_mul_f32 v[62:63], v[2:3], 0.5 op_sel_hi:[1,0]
	v_readlane_b32 s91, v255, 44
